# GEMM epilogue stores made write-through (sc0 sc1) so the grid barrier's L2 write-back has less to flush
# baseline (speedup 1.0000x reference)
; #define LAS __attribute__((address_space(3)))
; __device__ __forceinline__ float bflo(unsigned w) { return __uint_as_float(w << 16); }
; __device__ __forceinline__ float bfhi(unsigned w) { return __uint_as_float(w & 0xffff0000u); }
;     __device__ __forceinline__ void operator()(const f32x4 (&acc)[2][2][4][2], const Unit& u, int wr, int wc, int fr, int fq, const LAS float* rsl) const {
;         const int row0 = u.pm * 256 + wr * 64 + fr;
; #pragma unroll
;         for (int ai = 0; ai < 2; ++ai)
; #pragma unroll
;             for (int m = 0; m < 4; ++m) {
;                 const int row = row0 + ai * 128 + m * 16; float s = 0.f;
; #pragma unroll
;                 for (int bj = 0; bj < 2; ++bj) {
;                     bf16_t* ptr = xb + (size_t)row * 1024 + u.pn * 256 + bj * 128 + wc * 32 + 8 * fq;
;                     const u32x4 g = *(const u32x4*)ptr;
;                     f32x4 v0 = acc[ai][bj][m][0], v1 = acc[ai][bj][m][1];
;                     v0[0] += bflo(g.x); v0[1] += bfhi(g.x); v0[2] += bflo(g.y); v0[3] += bfhi(g.y);
;                     v1[0] += bflo(g.z); v1[1] += bfhi(g.z); v1[2] += bflo(g.w); v1[3] += bfhi(g.w);
;                     *(u32x4*)ptr = pack8(v0, v1);
;                     s += (v0[0] * v0[0] + v0[1] * v0[1]) + (v0[2] * v0[2] + v0[3] * v0[3]) + (v1[0] * v1[0] + v1[1] * v1[1]) + (v1[2] * v1[2] + v1[3] * v1[3]);
;                 }
;                 s += __shfl_xor(s, 16); s += __shfl_xor(s, 32);
;                 if (fq == 0) ssq[(size_t)row * 16 + u.pn * 4 + wc] = s;
.LBB0_87:
	v_and_b32_e32 v146, 64, v223
	v_xor_b32_e32 v143, 16, v223
	v_add_u32_e32 v146, 64, v146
	v_cmp_lt_i32_e32 vcc, v143, v146
	v_lshl_add_u32 v142, s51, 8, v137
	v_readlane_b32 s8, v254, 28
	v_cndmask_b32_e32 v143, v223, v143, vcc
	v_lshlrev_b32_e32 v161, 2, v143
	v_xor_b32_e32 v143, 32, v223
	v_cmp_lt_i32_e32 vcc, v143, v146
	s_lshl_b32 s4, s50, 8
	v_readlane_b32 s9, v254, 29
	v_cndmask_b32_e32 v143, v223, v143, vcc
	v_lshlrev_b32_e32 v160, 2, v143
	v_ashrrev_i32_e32 v143, 31, v142
	v_lshlrev_b64 v[152:153], 11, v[142:143]
	s_ashr_i32 s5, s4, 31
	v_lshl_add_u64 v[152:153], s[8:9], 0, v[152:153]
	v_lshl_add_u64 v[152:153], s[4:5], 1, v[152:153]
	s_lshl_b32 s68, s43, 1
	v_lshl_add_u64 v[152:153], v[152:153], 0, s[68:69]
	v_lshlrev_b32_e32 v146, 1, v136
	v_lshl_add_u64 v[156:157], v[152:153], 0, v[146:147]
	v_mbcnt_lo_u32_b32 v163, -1, 0
	v_mbcnt_hi_u32_b32 v163, -1, v163
	v_and_b32_e32 v162, 15, v163
	v_lshrrev_b32_e32 v163, 4, v163
	v_lshlrev_b32_e32 v162, 11, v162
	v_readfirstlane_b32 s8, v156
	v_readfirstlane_b32 s9, v157
	v_lshl_or_b32 v162, v163, 4, v162
	s_nop 4
	global_load_dwordx4 v[168:171], v162, s[8:9]
	global_load_dwordx4 v[172:175], v162, s[8:9] offset:256
	s_add_u32 s8, s8, 0x8000
	s_addc_u32 s9, s9, 0
	global_load_dwordx4 v[176:179], v162, s[8:9]
	global_load_dwordx4 v[180:183], v162, s[8:9] offset:256
	s_add_u32 s8, s8, 0x8000
	s_addc_u32 s9, s9, 0
	global_load_dwordx4 v[184:187], v162, s[8:9]
	global_load_dwordx4 v[188:191], v162, s[8:9] offset:256
	s_add_u32 s8, s8, 0x8000
	s_addc_u32 s9, s9, 0
	global_load_dwordx4 v[192:195], v162, s[8:9]
	global_load_dwordx4 v[196:199], v162, s[8:9] offset:256
	s_add_u32 s8, s8, 0x28000
	s_addc_u32 s9, s9, 0
	global_load_dwordx4 v[200:203], v162, s[8:9]
	global_load_dwordx4 v[204:207], v162, s[8:9] offset:256
	s_add_u32 s8, s8, 0x8000
	s_addc_u32 s9, s9, 0
	global_load_dwordx4 v[208:211], v162, s[8:9]
	global_load_dwordx4 v[212:215], v162, s[8:9] offset:256
	s_add_u32 s8, s8, 0x8000
	s_addc_u32 s9, s9, 0
	global_load_dwordx4 v[216:219], v162, s[8:9]
	global_load_dwordx4 v[228:231], v162, s[8:9] offset:256
	s_add_u32 s8, s8, 0x8000
	s_addc_u32 s9, s9, 0
	global_load_dwordx4 v[232:235], v162, s[8:9]
	global_load_dwordx4 v[236:239], v162, s[8:9] offset:256
	s_waitcnt vmcnt(15)
	v_mov_b32_e32 v162, v168
	v_mov_b32_e32 v163, v169
	v_mov_b32_e32 v164, v170
	v_mov_b32_e32 v165, v171
	s_lshl_b32 s0, s50, 2
	s_ashr_i32 s1, s0, 31
	v_lshlrev_b32_e32 v152, 16, v162
	v_and_b32_e32 v153, 0xffff0000, v162
	v_pk_add_f32 v[124:125], v[124:125], v[152:153]
	v_lshlrev_b32_e32 v152, 16, v163
	v_and_b32_e32 v153, 0xffff0000, v163
	v_pk_add_f32 v[126:127], v[126:127], v[152:153]
	v_lshlrev_b32_e32 v152, 16, v164
	v_and_b32_e32 v153, 0xffff0000, v164
	v_pk_add_f32 v[152:153], v[120:121], v[152:153]
	v_lshlrev_b32_e32 v120, 16, v165
	v_and_b32_e32 v121, 0xffff0000, v165
	v_pk_add_f32 v[162:163], v[122:123], v[120:121]
	v_cvt_pk_bf16_f32 v120, v124, v125
	v_cvt_pk_bf16_f32 v121, v126, v127
	v_cvt_pk_bf16_f32 v122, v152, v153
	v_cvt_pk_bf16_f32 v123, v162, v163
	global_store_dwordx4 v[156:157], v[120:123], off sc0 sc1
	s_nop 1
	v_pk_mul_f32 v[122:123], v[124:125], v[124:125]
	v_pk_mul_f32 v[124:125], v[126:127], v[126:127]
	v_pk_mul_f32 v[126:127], v[162:163], v[162:163]
	s_waitcnt vmcnt(15)
	v_mov_b32_e32 v162, v172
	v_mov_b32_e32 v163, v173
	v_mov_b32_e32 v164, v174
	v_mov_b32_e32 v165, v175
	v_pk_mul_f32 v[120:121], v[152:153], v[152:153]
	v_lshlrev_b32_e32 v152, 16, v162
	v_and_b32_e32 v153, 0xffff0000, v162
	v_pk_add_f32 v[116:117], v[116:117], v[152:153]
	v_lshlrev_b32_e32 v152, 16, v163
	v_and_b32_e32 v153, 0xffff0000, v163
	v_pk_add_f32 v[118:119], v[118:119], v[152:153]
	v_lshlrev_b32_e32 v152, 16, v164
	v_and_b32_e32 v153, 0xffff0000, v164
	v_pk_add_f32 v[152:153], v[112:113], v[152:153]
	v_lshlrev_b32_e32 v112, 16, v165
	v_and_b32_e32 v113, 0xffff0000, v165
	v_pk_add_f32 v[162:163], v[114:115], v[112:113]
	v_cvt_pk_bf16_f32 v112, v116, v117
	v_cvt_pk_bf16_f32 v113, v118, v119
	v_cvt_pk_bf16_f32 v114, v152, v153
	v_cvt_pk_bf16_f32 v115, v162, v163
	global_store_dwordx4 v[156:157], v[112:115], off offset:256 sc0 sc1
	s_nop 1
	v_pk_mul_f32 v[112:113], v[116:117], v[116:117]
	v_pk_mul_f32 v[114:115], v[118:119], v[118:119]
	v_add_f32_e32 v112, v112, v113
	v_add_f32_e32 v114, v114, v115
	v_pk_mul_f32 v[116:117], v[152:153], v[152:153]
	v_add_f32_e32 v112, v112, v114
	v_add_f32_e32 v114, v124, v125
	v_add_f32_e32 v115, v122, v123
	v_pk_mul_f32 v[118:119], v[162:163], v[162:163]
	v_add_f32_e32 v113, v116, v117
	v_add_f32_e32 v114, v115, v114
	v_add_f32_e32 v115, v120, v121
	v_add_f32_e32 v118, v118, v119
	v_add_f32_e32 v112, v113, v112
	v_add_f32_e32 v113, v126, v127
	v_add_f32_e32 v114, v115, v114
	v_add_f32_e32 v112, v118, v112
	v_add_f32_e32 v113, v113, v114
	v_add_f32_e32 v112, v113, v112
	ds_bpermute_b32 v113, v161, v112
	s_waitcnt lgkmcnt(0)
	v_add_f32_e32 v112, v112, v113
	ds_bpermute_b32 v113, v160, v112
	s_and_saveexec_b64 s[8:9], s[10:11]
	s_cbranch_execz .LBB0_89
	v_readlane_b32 s14, v254, 30
	s_waitcnt lgkmcnt(0)
	v_add_f32_e32 v114, v112, v113
	v_lshlrev_b64 v[112:113], 6, v[142:143]
	v_readlane_b32 s15, v254, 31
	s_nop 1
	v_lshl_add_u64 v[112:113], s[14:15], 0, v[112:113]
	v_lshl_add_u64 v[112:113], s[0:1], 2, v[112:113]
	s_lshl_b32 s14, s41, 2
	s_mov_b32 s15, s69
	v_lshl_add_u64 v[112:113], v[112:113], 0, s[14:15]
	global_store_dword v[112:113], v114, off
; __device__ __forceinline__ float bflo(unsigned w) { return __uint_as_float(w << 16); }
; __device__ __forceinline__ float bfhi(unsigned w) { return __uint_as_float(w & 0xffff0000u); }
;     __device__ __forceinline__ void operator()(const f32x4 (&acc)[2][2][4][2], const Unit& u, int wr, int wc, int fr, int fq, const LAS float* rsl) const {
;     ...
;             for (int m = 0; m < 4; ++m) {
;                 const int row = row0 + ai * 128 + m * 16; float s = 0.f;
; #pragma unroll
;                 for (int bj = 0; bj < 2; ++bj) {
;                     bf16_t* ptr = xb + (size_t)row * 1024 + u.pn * 256 + bj * 128 + wc * 32 + 8 * fq;
;                     const u32x4 g = *(const u32x4*)ptr;
;                     f32x4 v0 = acc[ai][bj][m][0], v1 = acc[ai][bj][m][1];
;                     v0[0] += bflo(g.x); v0[1] += bfhi(g.x); v0[2] += bflo(g.y); v0[3] += bfhi(g.y);
;                     v1[0] += bflo(g.z); v1[1] += bfhi(g.z); v1[2] += bflo(g.w); v1[3] += bfhi(g.w);
;                     *(u32x4*)ptr = pack8(v0, v1);
;                     s += (v0[0] * v0[0] + v0[1] * v0[1]) + (v0[2] * v0[2] + v0[3] * v0[3]) + (v1[0] * v1[0] + v1[1] * v1[1]) + (v1[2] * v1[2] + v1[3] * v1[3]);
;                 }
;                 s += __shfl_xor(s, 16); s += __shfl_xor(s, 32);
;                 if (fq == 0) ssq[(size_t)row * 16 + u.pn * 4 + wc] = s;
.LBB0_89:
	s_or_b64 exec, exec, s[8:9]
	v_or_b32_e32 v112, 16, v142
	s_waitcnt lgkmcnt(0)
	v_ashrrev_i32_e32 v113, 31, v112
	v_readlane_b32 s8, v254, 28
	v_lshlrev_b64 v[114:115], 11, v[112:113]
	v_readlane_b32 s9, v254, 29
	s_nop 1
	v_lshl_add_u64 v[114:115], s[8:9], 0, v[114:115]
	v_lshl_add_u64 v[114:115], s[4:5], 1, v[114:115]
	v_lshl_add_u64 v[114:115], v[114:115], 0, s[68:69]
	v_lshl_add_u64 v[118:119], v[114:115], 0, v[146:147]
	s_waitcnt vmcnt(15)
	v_mov_b32_e32 v114, v176
	v_mov_b32_e32 v115, v177
	v_mov_b32_e32 v116, v178
	v_mov_b32_e32 v117, v179
	v_lshlrev_b32_e32 v120, 16, v114
	v_and_b32_e32 v121, 0xffff0000, v114
	v_lshlrev_b32_e32 v114, 16, v115
	v_and_b32_e32 v115, 0xffff0000, v115
	v_pk_add_f32 v[110:111], v[110:111], v[114:115]
	v_lshlrev_b32_e32 v114, 16, v116
	v_and_b32_e32 v115, 0xffff0000, v116
	v_pk_add_f32 v[114:115], v[104:105], v[114:115]
	v_lshlrev_b32_e32 v104, 16, v117
	v_and_b32_e32 v105, 0xffff0000, v117
	v_pk_add_f32 v[108:109], v[108:109], v[120:121]
	v_pk_add_f32 v[116:117], v[106:107], v[104:105]
	v_cvt_pk_bf16_f32 v104, v108, v109
	v_cvt_pk_bf16_f32 v105, v110, v111
	v_cvt_pk_bf16_f32 v106, v114, v115
	v_cvt_pk_bf16_f32 v107, v116, v117
	global_store_dwordx4 v[118:119], v[104:107], off sc0 sc1
	s_nop 1
	v_pk_mul_f32 v[106:107], v[108:109], v[108:109]
	v_pk_mul_f32 v[108:109], v[110:111], v[110:111]
	v_pk_mul_f32 v[104:105], v[114:115], v[114:115]
	v_pk_mul_f32 v[110:111], v[116:117], v[116:117]
	s_waitcnt vmcnt(15)
	v_mov_b32_e32 v114, v180
	v_mov_b32_e32 v115, v181
	v_mov_b32_e32 v116, v182
	v_mov_b32_e32 v117, v183
	v_lshlrev_b32_e32 v120, 16, v114
	v_and_b32_e32 v121, 0xffff0000, v114
	v_lshlrev_b32_e32 v114, 16, v115
	v_and_b32_e32 v115, 0xffff0000, v115
	v_pk_add_f32 v[102:103], v[102:103], v[114:115]
	v_lshlrev_b32_e32 v114, 16, v116
	v_and_b32_e32 v115, 0xffff0000, v116
	v_pk_add_f32 v[114:115], v[96:97], v[114:115]
	v_lshlrev_b32_e32 v96, 16, v117
	v_and_b32_e32 v97, 0xffff0000, v117
	v_pk_add_f32 v[100:101], v[100:101], v[120:121]
	v_pk_add_f32 v[116:117], v[98:99], v[96:97]
	v_cvt_pk_bf16_f32 v96, v100, v101
	v_cvt_pk_bf16_f32 v97, v102, v103
	v_cvt_pk_bf16_f32 v98, v114, v115
	v_cvt_pk_bf16_f32 v99, v116, v117
	global_store_dwordx4 v[118:119], v[96:99], off offset:256 sc0 sc1
	s_nop 1
	v_pk_mul_f32 v[96:97], v[100:101], v[100:101]
	v_pk_mul_f32 v[98:99], v[102:103], v[102:103]
	v_add_f32_e32 v96, v96, v97
	v_add_f32_e32 v98, v98, v99
	v_pk_mul_f32 v[100:101], v[114:115], v[114:115]
	v_add_f32_e32 v96, v96, v98
	v_add_f32_e32 v98, v108, v109
	v_add_f32_e32 v99, v106, v107
	v_pk_mul_f32 v[102:103], v[116:117], v[116:117]
	v_add_f32_e32 v97, v100, v101
	v_add_f32_e32 v98, v99, v98
	v_add_f32_e32 v99, v104, v105
	v_add_f32_e32 v102, v102, v103
	v_add_f32_e32 v96, v97, v96
	v_add_f32_e32 v97, v110, v111
	v_add_f32_e32 v98, v99, v98
	v_add_f32_e32 v96, v102, v96
	v_add_f32_e32 v97, v97, v98
	v_add_f32_e32 v96, v97, v96
	ds_bpermute_b32 v97, v161, v96
	s_waitcnt lgkmcnt(0)
	v_add_f32_e32 v96, v96, v97
	ds_bpermute_b32 v97, v160, v96
	s_and_saveexec_b64 s[8:9], s[10:11]
	s_cbranch_execz .LBB0_91
	v_readlane_b32 s14, v254, 30
	s_waitcnt lgkmcnt(0)
	v_add_f32_e32 v98, v96, v97
	v_lshlrev_b64 v[96:97], 6, v[112:113]
	v_readlane_b32 s15, v254, 31
	s_nop 1
	v_lshl_add_u64 v[96:97], s[14:15], 0, v[96:97]
	v_lshl_add_u64 v[96:97], s[0:1], 2, v[96:97]
	s_lshl_b32 s14, s41, 2
	s_mov_b32 s15, s69
	v_lshl_add_u64 v[96:97], v[96:97], 0, s[14:15]
	global_store_dword v[96:97], v98, off
.LBB0_91:
	s_or_b64 exec, exec, s[8:9]
	v_or_b32_e32 v96, 32, v142
	s_waitcnt lgkmcnt(0)
	v_ashrrev_i32_e32 v97, 31, v96
	v_readlane_b32 s8, v254, 28
	v_lshlrev_b64 v[98:99], 11, v[96:97]
	v_readlane_b32 s9, v254, 29
	s_nop 1
	v_lshl_add_u64 v[98:99], s[8:9], 0, v[98:99]
	v_lshl_add_u64 v[98:99], s[4:5], 1, v[98:99]
	v_lshl_add_u64 v[98:99], v[98:99], 0, s[68:69]
	v_lshl_add_u64 v[102:103], v[98:99], 0, v[146:147]
	s_waitcnt vmcnt(15)
	v_mov_b32_e32 v98, v184
	v_mov_b32_e32 v99, v185
	v_mov_b32_e32 v100, v186
	v_mov_b32_e32 v101, v187
	v_lshlrev_b32_e32 v104, 16, v98
	v_and_b32_e32 v105, 0xffff0000, v98
	v_lshlrev_b32_e32 v98, 16, v99
	v_and_b32_e32 v99, 0xffff0000, v99
	v_pk_add_f32 v[94:95], v[94:95], v[98:99]
	v_lshlrev_b32_e32 v98, 16, v100
	v_and_b32_e32 v99, 0xffff0000, v100
	v_pk_add_f32 v[98:99], v[88:89], v[98:99]
	v_lshlrev_b32_e32 v88, 16, v101
	v_and_b32_e32 v89, 0xffff0000, v101
	v_pk_add_f32 v[92:93], v[92:93], v[104:105]
	v_pk_add_f32 v[100:101], v[90:91], v[88:89]
	v_cvt_pk_bf16_f32 v88, v92, v93
	v_cvt_pk_bf16_f32 v89, v94, v95
	v_cvt_pk_bf16_f32 v90, v98, v99
	v_cvt_pk_bf16_f32 v91, v100, v101
	global_store_dwordx4 v[102:103], v[88:91], off sc0 sc1
	s_nop 1
	v_pk_mul_f32 v[90:91], v[92:93], v[92:93]
	v_pk_mul_f32 v[92:93], v[94:95], v[94:95]
	v_pk_mul_f32 v[88:89], v[98:99], v[98:99]
	v_pk_mul_f32 v[94:95], v[100:101], v[100:101]
	s_waitcnt vmcnt(15)
	v_mov_b32_e32 v98, v188
	v_mov_b32_e32 v99, v189
	v_mov_b32_e32 v100, v190
	v_mov_b32_e32 v101, v191
	v_lshlrev_b32_e32 v104, 16, v98
	v_and_b32_e32 v105, 0xffff0000, v98
	v_lshlrev_b32_e32 v98, 16, v99
	v_and_b32_e32 v99, 0xffff0000, v99
	v_pk_add_f32 v[86:87], v[86:87], v[98:99]
	v_lshlrev_b32_e32 v98, 16, v100
	v_and_b32_e32 v99, 0xffff0000, v100
	v_pk_add_f32 v[98:99], v[80:81], v[98:99]
	v_lshlrev_b32_e32 v80, 16, v101
	v_and_b32_e32 v81, 0xffff0000, v101
	v_pk_add_f32 v[84:85], v[84:85], v[104:105]
	v_pk_add_f32 v[100:101], v[82:83], v[80:81]
	v_cvt_pk_bf16_f32 v80, v84, v85
	v_cvt_pk_bf16_f32 v81, v86, v87
	v_cvt_pk_bf16_f32 v82, v98, v99
	v_cvt_pk_bf16_f32 v83, v100, v101
	global_store_dwordx4 v[102:103], v[80:83], off offset:256 sc0 sc1
	s_nop 1
	v_pk_mul_f32 v[80:81], v[84:85], v[84:85]
	v_pk_mul_f32 v[82:83], v[86:87], v[86:87]
	v_add_f32_e32 v80, v80, v81
	v_add_f32_e32 v82, v82, v83
	v_pk_mul_f32 v[84:85], v[98:99], v[98:99]
	v_add_f32_e32 v80, v80, v82
	v_add_f32_e32 v82, v92, v93
	v_add_f32_e32 v83, v90, v91
	v_pk_mul_f32 v[86:87], v[100:101], v[100:101]
	v_add_f32_e32 v81, v84, v85
	v_add_f32_e32 v82, v83, v82
	v_add_f32_e32 v83, v88, v89
	v_add_f32_e32 v86, v86, v87
	v_add_f32_e32 v80, v81, v80
	v_add_f32_e32 v81, v94, v95
	v_add_f32_e32 v82, v83, v82
	v_add_f32_e32 v80, v86, v80
	v_add_f32_e32 v81, v81, v82
	v_add_f32_e32 v80, v81, v80
	ds_bpermute_b32 v81, v161, v80
	s_waitcnt lgkmcnt(0)
	v_add_f32_e32 v80, v80, v81
	ds_bpermute_b32 v81, v160, v80
	s_and_saveexec_b64 s[8:9], s[10:11]
	s_cbranch_execz .LBB0_93
	v_readlane_b32 s14, v254, 30
	s_waitcnt lgkmcnt(0)
	v_add_f32_e32 v82, v80, v81
	v_lshlrev_b64 v[80:81], 6, v[96:97]
	v_readlane_b32 s15, v254, 31
	s_nop 1
	v_lshl_add_u64 v[80:81], s[14:15], 0, v[80:81]
	v_lshl_add_u64 v[80:81], s[0:1], 2, v[80:81]
	s_lshl_b32 s14, s41, 2
	s_mov_b32 s15, s69
	v_lshl_add_u64 v[80:81], v[80:81], 0, s[14:15]
	global_store_dword v[80:81], v82, off
; #define LAS __attribute__((address_space(3)))
; __device__ __forceinline__ float bflo(unsigned w) { return __uint_as_float(w << 16); }
; __device__ __forceinline__ float bfhi(unsigned w) { return __uint_as_float(w & 0xffff0000u); }
;     __device__ __forceinline__ void operator()(const f32x4 (&acc)[2][2][4][2], const Unit& u, int wr, int wc, int fr, int fq, const LAS float* rsl) const {
;         const int row0 = u.pm * 256 + wr * 64 + fr;
; #pragma unroll
;         for (int ai = 0; ai < 2; ++ai)
; #pragma unroll
;             for (int m = 0; m < 4; ++m) {
;                 const int row = row0 + ai * 128 + m * 16; float s = 0.f;
; #pragma unroll
;                 for (int bj = 0; bj < 2; ++bj) {
;                     bf16_t* ptr = xb + (size_t)row * 1024 + u.pn * 256 + bj * 128 + wc * 32 + 8 * fq;
;                     const u32x4 g = *(const u32x4*)ptr;
;                     f32x4 v0 = acc[ai][bj][m][0], v1 = acc[ai][bj][m][1];
;                     v0[0] += bflo(g.x); v0[1] += bfhi(g.x); v0[2] += bflo(g.y); v0[3] += bfhi(g.y);
;                     v1[0] += bflo(g.z); v1[1] += bfhi(g.z); v1[2] += bflo(g.w); v1[3] += bfhi(g.w);
;                     *(u32x4*)ptr = pack8(v0, v1);
;                     s += (v0[0] * v0[0] + v0[1] * v0[1]) + (v0[2] * v0[2] + v0[3] * v0[3]) + (v1[0] * v1[0] + v1[1] * v1[1]) + (v1[2] * v1[2] + v1[3] * v1[3]);
;                 }
;                 s += __shfl_xor(s, 16); s += __shfl_xor(s, 32);
;                 if (fq == 0) ssq[(size_t)row * 16 + u.pn * 4 + wc] = s;
;             }
;     }
.LBB0_93:
	s_or_b64 exec, exec, s[8:9]
	v_or_b32_e32 v80, 48, v142
	s_waitcnt lgkmcnt(0)
	v_ashrrev_i32_e32 v81, 31, v80
	v_readlane_b32 s8, v254, 28
	v_lshlrev_b64 v[82:83], 11, v[80:81]
	v_readlane_b32 s9, v254, 29
	s_nop 1
	v_lshl_add_u64 v[82:83], s[8:9], 0, v[82:83]
	v_lshl_add_u64 v[82:83], s[4:5], 1, v[82:83]
	v_lshl_add_u64 v[82:83], v[82:83], 0, s[68:69]
	v_lshl_add_u64 v[86:87], v[82:83], 0, v[146:147]
	s_waitcnt vmcnt(15)
	v_mov_b32_e32 v82, v192
	v_mov_b32_e32 v83, v193
	v_mov_b32_e32 v84, v194
	v_mov_b32_e32 v85, v195
	v_lshlrev_b32_e32 v88, 16, v82
	v_and_b32_e32 v89, 0xffff0000, v82
	v_lshlrev_b32_e32 v82, 16, v83
	v_and_b32_e32 v83, 0xffff0000, v83
	v_pk_add_f32 v[78:79], v[78:79], v[82:83]
	v_lshlrev_b32_e32 v82, 16, v84
	v_and_b32_e32 v83, 0xffff0000, v84
	v_pk_add_f32 v[82:83], v[72:73], v[82:83]
	v_lshlrev_b32_e32 v72, 16, v85
	v_and_b32_e32 v73, 0xffff0000, v85
	v_pk_add_f32 v[76:77], v[76:77], v[88:89]
	v_pk_add_f32 v[84:85], v[74:75], v[72:73]
	v_cvt_pk_bf16_f32 v72, v76, v77
	v_cvt_pk_bf16_f32 v73, v78, v79
	v_cvt_pk_bf16_f32 v74, v82, v83
	v_cvt_pk_bf16_f32 v75, v84, v85
	global_store_dwordx4 v[86:87], v[72:75], off sc0 sc1
	s_nop 1
	v_pk_mul_f32 v[74:75], v[76:77], v[76:77]
	v_pk_mul_f32 v[76:77], v[78:79], v[78:79]
	v_pk_mul_f32 v[72:73], v[82:83], v[82:83]
	v_pk_mul_f32 v[78:79], v[84:85], v[84:85]
	s_waitcnt vmcnt(15)
	v_mov_b32_e32 v82, v196
	v_mov_b32_e32 v83, v197
	v_mov_b32_e32 v84, v198
	v_mov_b32_e32 v85, v199
	v_lshlrev_b32_e32 v88, 16, v82
	v_and_b32_e32 v89, 0xffff0000, v82
	v_lshlrev_b32_e32 v82, 16, v83
	v_and_b32_e32 v83, 0xffff0000, v83
	v_pk_add_f32 v[70:71], v[70:71], v[82:83]
	v_lshlrev_b32_e32 v82, 16, v84
	v_and_b32_e32 v83, 0xffff0000, v84
	v_pk_add_f32 v[82:83], v[64:65], v[82:83]
	v_lshlrev_b32_e32 v64, 16, v85
	v_and_b32_e32 v65, 0xffff0000, v85
	v_pk_add_f32 v[68:69], v[68:69], v[88:89]
	v_pk_add_f32 v[84:85], v[66:67], v[64:65]
	v_cvt_pk_bf16_f32 v64, v68, v69
	v_cvt_pk_bf16_f32 v65, v70, v71
	v_cvt_pk_bf16_f32 v66, v82, v83
	v_cvt_pk_bf16_f32 v67, v84, v85
	global_store_dwordx4 v[86:87], v[64:67], off offset:256 sc0 sc1
	s_nop 1
	v_pk_mul_f32 v[64:65], v[68:69], v[68:69]
	v_pk_mul_f32 v[66:67], v[70:71], v[70:71]
	v_add_f32_e32 v64, v64, v65
	v_add_f32_e32 v66, v66, v67
	v_pk_mul_f32 v[68:69], v[82:83], v[82:83]
	v_add_f32_e32 v64, v64, v66
	v_add_f32_e32 v66, v76, v77
	v_add_f32_e32 v67, v74, v75
	v_pk_mul_f32 v[70:71], v[84:85], v[84:85]
	v_add_f32_e32 v65, v68, v69
	v_add_f32_e32 v66, v67, v66
	v_add_f32_e32 v67, v72, v73
	v_add_f32_e32 v70, v70, v71
	v_add_f32_e32 v64, v65, v64
	v_add_f32_e32 v65, v78, v79
	v_add_f32_e32 v66, v67, v66
	v_add_f32_e32 v64, v70, v64
	v_add_f32_e32 v65, v65, v66
	v_add_f32_e32 v64, v65, v64
	ds_bpermute_b32 v65, v161, v64
	s_waitcnt lgkmcnt(0)
	v_add_f32_e32 v64, v64, v65
	ds_bpermute_b32 v65, v160, v64
	s_and_saveexec_b64 s[8:9], s[10:11]
	s_cbranch_execz .LBB0_95
	v_readlane_b32 s14, v254, 30
	s_waitcnt lgkmcnt(0)
	v_add_f32_e32 v66, v64, v65
	v_lshlrev_b64 v[64:65], 6, v[80:81]
	v_readlane_b32 s15, v254, 31
	s_nop 1
	v_lshl_add_u64 v[64:65], s[14:15], 0, v[64:65]
	v_lshl_add_u64 v[64:65], s[0:1], 2, v[64:65]
	s_lshl_b32 s14, s41, 2
	s_mov_b32 s15, s69
	v_lshl_add_u64 v[64:65], v[64:65], 0, s[14:15]
	global_store_dword v[64:65], v66, off
.LBB0_95:
	s_or_b64 exec, exec, s[8:9]
	v_add_u32_e32 v64, 0x80, v142
	s_waitcnt lgkmcnt(0)
	v_ashrrev_i32_e32 v65, 31, v64
	v_readlane_b32 s8, v254, 28
	v_lshlrev_b64 v[66:67], 11, v[64:65]
	v_readlane_b32 s9, v254, 29
	s_nop 1
	v_lshl_add_u64 v[66:67], s[8:9], 0, v[66:67]
	v_lshl_add_u64 v[66:67], s[4:5], 1, v[66:67]
	v_lshl_add_u64 v[66:67], v[66:67], 0, s[68:69]
	v_lshl_add_u64 v[70:71], v[66:67], 0, v[146:147]
	s_waitcnt vmcnt(15)
	v_mov_b32_e32 v66, v200
	v_mov_b32_e32 v67, v201
	v_mov_b32_e32 v68, v202
	v_mov_b32_e32 v69, v203
	v_lshlrev_b32_e32 v72, 16, v66
	v_and_b32_e32 v73, 0xffff0000, v66
	v_lshlrev_b32_e32 v66, 16, v67
	v_and_b32_e32 v67, 0xffff0000, v67
	v_pk_add_f32 v[62:63], v[62:63], v[66:67]
	v_lshlrev_b32_e32 v66, 16, v68
	v_and_b32_e32 v67, 0xffff0000, v68
	v_pk_add_f32 v[66:67], v[56:57], v[66:67]
	v_lshlrev_b32_e32 v56, 16, v69
	v_and_b32_e32 v57, 0xffff0000, v69
	v_pk_add_f32 v[60:61], v[60:61], v[72:73]
	v_pk_add_f32 v[68:69], v[58:59], v[56:57]
	v_cvt_pk_bf16_f32 v56, v60, v61
	v_cvt_pk_bf16_f32 v57, v62, v63
	v_cvt_pk_bf16_f32 v58, v66, v67
	v_cvt_pk_bf16_f32 v59, v68, v69
	global_store_dwordx4 v[70:71], v[56:59], off sc0 sc1
	s_nop 1
	v_pk_mul_f32 v[58:59], v[60:61], v[60:61]
	v_pk_mul_f32 v[60:61], v[62:63], v[62:63]
	v_pk_mul_f32 v[56:57], v[66:67], v[66:67]
	v_pk_mul_f32 v[62:63], v[68:69], v[68:69]
	s_waitcnt vmcnt(15)
	v_mov_b32_e32 v66, v204
	v_mov_b32_e32 v67, v205
	v_mov_b32_e32 v68, v206
	v_mov_b32_e32 v69, v207
	v_lshlrev_b32_e32 v72, 16, v66
	v_and_b32_e32 v73, 0xffff0000, v66
	v_lshlrev_b32_e32 v66, 16, v67
	v_and_b32_e32 v67, 0xffff0000, v67
	v_pk_add_f32 v[54:55], v[54:55], v[66:67]
	v_lshlrev_b32_e32 v66, 16, v68
	v_and_b32_e32 v67, 0xffff0000, v68
	v_pk_add_f32 v[66:67], v[48:49], v[66:67]
	v_lshlrev_b32_e32 v48, 16, v69
	v_and_b32_e32 v49, 0xffff0000, v69
	v_pk_add_f32 v[52:53], v[52:53], v[72:73]
	v_pk_add_f32 v[68:69], v[50:51], v[48:49]
	v_cvt_pk_bf16_f32 v48, v52, v53
	v_cvt_pk_bf16_f32 v49, v54, v55
	v_cvt_pk_bf16_f32 v50, v66, v67
	v_cvt_pk_bf16_f32 v51, v68, v69
	global_store_dwordx4 v[70:71], v[48:51], off offset:256 sc0 sc1
	s_nop 1
	v_pk_mul_f32 v[48:49], v[52:53], v[52:53]
	v_pk_mul_f32 v[50:51], v[54:55], v[54:55]
	v_add_f32_e32 v48, v48, v49
	v_add_f32_e32 v50, v50, v51
	v_pk_mul_f32 v[52:53], v[66:67], v[66:67]
	v_add_f32_e32 v48, v48, v50
	v_add_f32_e32 v50, v60, v61
	v_add_f32_e32 v51, v58, v59
	v_pk_mul_f32 v[54:55], v[68:69], v[68:69]
	v_add_f32_e32 v49, v52, v53
	v_add_f32_e32 v50, v51, v50
	v_add_f32_e32 v51, v56, v57
	v_add_f32_e32 v54, v54, v55
	v_add_f32_e32 v48, v49, v48
	v_add_f32_e32 v49, v62, v63
	v_add_f32_e32 v50, v51, v50
	v_add_f32_e32 v48, v54, v48
	v_add_f32_e32 v49, v49, v50
	v_add_f32_e32 v48, v49, v48
	ds_bpermute_b32 v49, v161, v48
	s_waitcnt lgkmcnt(0)
	v_add_f32_e32 v48, v48, v49
	ds_bpermute_b32 v49, v160, v48
	s_and_saveexec_b64 s[8:9], s[10:11]
	s_cbranch_execz .LBB0_97
	v_readlane_b32 s14, v254, 30
	s_waitcnt lgkmcnt(0)
	v_add_f32_e32 v50, v48, v49
	v_lshlrev_b64 v[48:49], 6, v[64:65]
	v_readlane_b32 s15, v254, 31
	s_nop 1
	v_lshl_add_u64 v[48:49], s[14:15], 0, v[48:49]
	v_lshl_add_u64 v[48:49], s[0:1], 2, v[48:49]
	s_lshl_b32 s14, s41, 2
	s_mov_b32 s15, s69
	v_lshl_add_u64 v[48:49], v[48:49], 0, s[14:15]
	global_store_dword v[48:49], v50, off
; #define LAS __attribute__((address_space(3)))
; __device__ __forceinline__ float bflo(unsigned w) { return __uint_as_float(w << 16); }
; __device__ __forceinline__ float bfhi(unsigned w) { return __uint_as_float(w & 0xffff0000u); }
;     __device__ __forceinline__ void operator()(const f32x4 (&acc)[2][2][4][2], const Unit& u, int wr, int wc, int fr, int fq, const LAS float* rsl) const {
;         const int row0 = u.pm * 256 + wr * 64 + fr;
; #pragma unroll
;         for (int ai = 0; ai < 2; ++ai)
; #pragma unroll
;             for (int m = 0; m < 4; ++m) {
;                 const int row = row0 + ai * 128 + m * 16; float s = 0.f;
; #pragma unroll
;                 for (int bj = 0; bj < 2; ++bj) {
;                     bf16_t* ptr = xb + (size_t)row * 1024 + u.pn * 256 + bj * 128 + wc * 32 + 8 * fq;
;                     const u32x4 g = *(const u32x4*)ptr;
;                     f32x4 v0 = acc[ai][bj][m][0], v1 = acc[ai][bj][m][1];
;                     v0[0] += bflo(g.x); v0[1] += bfhi(g.x); v0[2] += bflo(g.y); v0[3] += bfhi(g.y);
;                     v1[0] += bflo(g.z); v1[1] += bfhi(g.z); v1[2] += bflo(g.w); v1[3] += bfhi(g.w);
;                     *(u32x4*)ptr = pack8(v0, v1);
;                     s += (v0[0] * v0[0] + v0[1] * v0[1]) + (v0[2] * v0[2] + v0[3] * v0[3]) + (v1[0] * v1[0] + v1[1] * v1[1]) + (v1[2] * v1[2] + v1[3] * v1[3]);
;                 }
;                 s += __shfl_xor(s, 16); s += __shfl_xor(s, 32);
;                 if (fq == 0) ssq[(size_t)row * 16 + u.pn * 4 + wc] = s;
;             }
;     }
.LBB0_97:
	s_or_b64 exec, exec, s[8:9]
	v_add_u32_e32 v48, 0x90, v142
	s_waitcnt lgkmcnt(0)
	v_ashrrev_i32_e32 v49, 31, v48
	v_readlane_b32 s8, v254, 28
	v_lshlrev_b64 v[50:51], 11, v[48:49]
	v_readlane_b32 s9, v254, 29
	s_nop 1
	v_lshl_add_u64 v[50:51], s[8:9], 0, v[50:51]
	v_lshl_add_u64 v[50:51], s[4:5], 1, v[50:51]
	v_lshl_add_u64 v[50:51], v[50:51], 0, s[68:69]
	v_lshl_add_u64 v[54:55], v[50:51], 0, v[146:147]
	s_waitcnt vmcnt(15)
	v_mov_b32_e32 v50, v208
	v_mov_b32_e32 v51, v209
	v_mov_b32_e32 v52, v210
	v_mov_b32_e32 v53, v211
	v_lshlrev_b32_e32 v56, 16, v50
	v_and_b32_e32 v57, 0xffff0000, v50
	v_lshlrev_b32_e32 v50, 16, v51
	v_and_b32_e32 v51, 0xffff0000, v51
	v_pk_add_f32 v[46:47], v[46:47], v[50:51]
	v_lshlrev_b32_e32 v50, 16, v52
	v_and_b32_e32 v51, 0xffff0000, v52
	v_pk_add_f32 v[50:51], v[40:41], v[50:51]
	v_lshlrev_b32_e32 v40, 16, v53
	v_and_b32_e32 v41, 0xffff0000, v53
	v_pk_add_f32 v[44:45], v[44:45], v[56:57]
	v_pk_add_f32 v[52:53], v[42:43], v[40:41]
	v_cvt_pk_bf16_f32 v40, v44, v45
	v_cvt_pk_bf16_f32 v41, v46, v47
	v_cvt_pk_bf16_f32 v42, v50, v51
	v_cvt_pk_bf16_f32 v43, v52, v53
	global_store_dwordx4 v[54:55], v[40:43], off sc0 sc1
	s_nop 1
	v_pk_mul_f32 v[42:43], v[44:45], v[44:45]
	v_pk_mul_f32 v[44:45], v[46:47], v[46:47]
	v_pk_mul_f32 v[40:41], v[50:51], v[50:51]
	v_pk_mul_f32 v[46:47], v[52:53], v[52:53]
	s_waitcnt vmcnt(15)
	v_mov_b32_e32 v50, v212
	v_mov_b32_e32 v51, v213
	v_mov_b32_e32 v52, v214
	v_mov_b32_e32 v53, v215
	v_lshlrev_b32_e32 v56, 16, v50
	v_and_b32_e32 v57, 0xffff0000, v50
	v_lshlrev_b32_e32 v50, 16, v51
	v_and_b32_e32 v51, 0xffff0000, v51
	v_pk_add_f32 v[38:39], v[38:39], v[50:51]
	v_lshlrev_b32_e32 v50, 16, v52
	v_and_b32_e32 v51, 0xffff0000, v52
	v_pk_add_f32 v[50:51], v[32:33], v[50:51]
	v_lshlrev_b32_e32 v32, 16, v53
	v_and_b32_e32 v33, 0xffff0000, v53
	v_pk_add_f32 v[36:37], v[36:37], v[56:57]
	v_pk_add_f32 v[52:53], v[34:35], v[32:33]
	v_cvt_pk_bf16_f32 v32, v36, v37
	v_cvt_pk_bf16_f32 v33, v38, v39
	v_cvt_pk_bf16_f32 v34, v50, v51
	v_cvt_pk_bf16_f32 v35, v52, v53
	global_store_dwordx4 v[54:55], v[32:35], off offset:256 sc0 sc1
	s_nop 1
	v_pk_mul_f32 v[32:33], v[36:37], v[36:37]
	v_pk_mul_f32 v[34:35], v[38:39], v[38:39]
	v_add_f32_e32 v32, v32, v33
	v_add_f32_e32 v34, v34, v35
	v_pk_mul_f32 v[36:37], v[50:51], v[50:51]
	v_add_f32_e32 v32, v32, v34
	v_add_f32_e32 v34, v44, v45
	v_add_f32_e32 v35, v42, v43
	v_pk_mul_f32 v[38:39], v[52:53], v[52:53]
	v_add_f32_e32 v33, v36, v37
	v_add_f32_e32 v34, v35, v34
	v_add_f32_e32 v35, v40, v41
	v_add_f32_e32 v38, v38, v39
	v_add_f32_e32 v32, v33, v32
	v_add_f32_e32 v33, v46, v47
	v_add_f32_e32 v34, v35, v34
	v_add_f32_e32 v32, v38, v32
	v_add_f32_e32 v33, v33, v34
	v_add_f32_e32 v32, v33, v32
	ds_bpermute_b32 v33, v161, v32
	s_waitcnt lgkmcnt(0)
	v_add_f32_e32 v32, v32, v33
	ds_bpermute_b32 v33, v160, v32
	s_and_saveexec_b64 s[8:9], s[10:11]
	s_cbranch_execz .LBB0_99
	v_readlane_b32 s14, v254, 30
	s_waitcnt lgkmcnt(0)
	v_add_f32_e32 v34, v32, v33
	v_lshlrev_b64 v[32:33], 6, v[48:49]
	v_readlane_b32 s15, v254, 31
	s_nop 1
	v_lshl_add_u64 v[32:33], s[14:15], 0, v[32:33]
	v_lshl_add_u64 v[32:33], s[0:1], 2, v[32:33]
	s_lshl_b32 s14, s41, 2
	s_mov_b32 s15, s69
	v_lshl_add_u64 v[32:33], v[32:33], 0, s[14:15]
	global_store_dword v[32:33], v34, off
; #define LAS __attribute__((address_space(3)))
; __device__ __forceinline__ float bflo(unsigned w) { return __uint_as_float(w << 16); }
; __device__ __forceinline__ float bfhi(unsigned w) { return __uint_as_float(w & 0xffff0000u); }
;     __device__ __forceinline__ void operator()(const f32x4 (&acc)[2][2][4][2], const Unit& u, int wr, int wc, int fr, int fq, const LAS float* rsl) const {
;         const int row0 = u.pm * 256 + wr * 64 + fr;
; #pragma unroll
;         for (int ai = 0; ai < 2; ++ai)
; #pragma unroll
;             for (int m = 0; m < 4; ++m) {
;                 const int row = row0 + ai * 128 + m * 16; float s = 0.f;
; #pragma unroll
;                 for (int bj = 0; bj < 2; ++bj) {
;                     bf16_t* ptr = xb + (size_t)row * 1024 + u.pn * 256 + bj * 128 + wc * 32 + 8 * fq;
;                     const u32x4 g = *(const u32x4*)ptr;
;                     f32x4 v0 = acc[ai][bj][m][0], v1 = acc[ai][bj][m][1];
;                     v0[0] += bflo(g.x); v0[1] += bfhi(g.x); v0[2] += bflo(g.y); v0[3] += bfhi(g.y);
;                     v1[0] += bflo(g.z); v1[1] += bfhi(g.z); v1[2] += bflo(g.w); v1[3] += bfhi(g.w);
;                     *(u32x4*)ptr = pack8(v0, v1);
;                     s += (v0[0] * v0[0] + v0[1] * v0[1]) + (v0[2] * v0[2] + v0[3] * v0[3]) + (v1[0] * v1[0] + v1[1] * v1[1]) + (v1[2] * v1[2] + v1[3] * v1[3]);
;                 }
;                 s += __shfl_xor(s, 16); s += __shfl_xor(s, 32);
;                 if (fq == 0) ssq[(size_t)row * 16 + u.pn * 4 + wc] = s;
;             }
;     }
.LBB0_99:
	s_or_b64 exec, exec, s[8:9]
	v_add_u32_e32 v32, 0xa0, v142
	s_waitcnt lgkmcnt(0)
	v_ashrrev_i32_e32 v33, 31, v32
	v_readlane_b32 s8, v254, 28
	v_lshlrev_b64 v[34:35], 11, v[32:33]
	v_readlane_b32 s9, v254, 29
	s_nop 1
	v_lshl_add_u64 v[34:35], s[8:9], 0, v[34:35]
	v_lshl_add_u64 v[34:35], s[4:5], 1, v[34:35]
	v_lshl_add_u64 v[34:35], v[34:35], 0, s[68:69]
	v_lshl_add_u64 v[38:39], v[34:35], 0, v[146:147]
	s_waitcnt vmcnt(15)
	v_mov_b32_e32 v34, v216
	v_mov_b32_e32 v35, v217
	v_mov_b32_e32 v36, v218
	v_mov_b32_e32 v37, v219
	v_lshlrev_b32_e32 v40, 16, v34
	v_and_b32_e32 v41, 0xffff0000, v34
	v_lshlrev_b32_e32 v34, 16, v35
	v_and_b32_e32 v35, 0xffff0000, v35
	v_pk_add_f32 v[30:31], v[30:31], v[34:35]
	v_lshlrev_b32_e32 v34, 16, v36
	v_and_b32_e32 v35, 0xffff0000, v36
	v_pk_add_f32 v[34:35], v[24:25], v[34:35]
	v_lshlrev_b32_e32 v24, 16, v37
	v_and_b32_e32 v25, 0xffff0000, v37
	v_pk_add_f32 v[28:29], v[28:29], v[40:41]
	v_pk_add_f32 v[36:37], v[26:27], v[24:25]
	v_cvt_pk_bf16_f32 v24, v28, v29
	v_cvt_pk_bf16_f32 v25, v30, v31
	v_cvt_pk_bf16_f32 v26, v34, v35
	v_cvt_pk_bf16_f32 v27, v36, v37
	global_store_dwordx4 v[38:39], v[24:27], off sc0 sc1
	s_nop 1
	v_pk_mul_f32 v[26:27], v[28:29], v[28:29]
	v_pk_mul_f32 v[28:29], v[30:31], v[30:31]
	v_pk_mul_f32 v[24:25], v[34:35], v[34:35]
	v_pk_mul_f32 v[30:31], v[36:37], v[36:37]
	s_waitcnt vmcnt(15)
	v_mov_b32_e32 v34, v228
	v_mov_b32_e32 v35, v229
	v_mov_b32_e32 v36, v230
	v_mov_b32_e32 v37, v231
	v_lshlrev_b32_e32 v40, 16, v34
	v_and_b32_e32 v41, 0xffff0000, v34
	v_lshlrev_b32_e32 v34, 16, v35
	v_and_b32_e32 v35, 0xffff0000, v35
	v_pk_add_f32 v[22:23], v[22:23], v[34:35]
	v_lshlrev_b32_e32 v34, 16, v36
	v_and_b32_e32 v35, 0xffff0000, v36
	v_pk_add_f32 v[34:35], v[16:17], v[34:35]
	v_lshlrev_b32_e32 v16, 16, v37
	v_and_b32_e32 v17, 0xffff0000, v37
	v_pk_add_f32 v[20:21], v[20:21], v[40:41]
	v_pk_add_f32 v[36:37], v[18:19], v[16:17]
	v_cvt_pk_bf16_f32 v16, v20, v21
	v_cvt_pk_bf16_f32 v17, v22, v23
	v_cvt_pk_bf16_f32 v18, v34, v35
	v_cvt_pk_bf16_f32 v19, v36, v37
	global_store_dwordx4 v[38:39], v[16:19], off offset:256 sc0 sc1
	s_nop 1
	v_pk_mul_f32 v[16:17], v[20:21], v[20:21]
	v_pk_mul_f32 v[18:19], v[22:23], v[22:23]
	v_add_f32_e32 v16, v16, v17
	v_add_f32_e32 v18, v18, v19
	v_pk_mul_f32 v[20:21], v[34:35], v[34:35]
	v_add_f32_e32 v16, v16, v18
	v_add_f32_e32 v18, v28, v29
	v_add_f32_e32 v19, v26, v27
	v_pk_mul_f32 v[22:23], v[36:37], v[36:37]
	v_add_f32_e32 v17, v20, v21
	v_add_f32_e32 v18, v19, v18
	v_add_f32_e32 v19, v24, v25
	v_add_f32_e32 v22, v22, v23
	v_add_f32_e32 v16, v17, v16
	v_add_f32_e32 v17, v30, v31
	v_add_f32_e32 v18, v19, v18
	v_add_f32_e32 v16, v22, v16
	v_add_f32_e32 v17, v17, v18
	v_add_f32_e32 v16, v17, v16
	ds_bpermute_b32 v17, v161, v16
	s_waitcnt lgkmcnt(0)
	v_add_f32_e32 v16, v16, v17
	ds_bpermute_b32 v17, v160, v16
	s_and_saveexec_b64 s[8:9], s[10:11]
	s_cbranch_execz .LBB0_101
	v_readlane_b32 s14, v254, 30
	s_waitcnt lgkmcnt(0)
	v_add_f32_e32 v18, v16, v17
	v_lshlrev_b64 v[16:17], 6, v[32:33]
	v_readlane_b32 s15, v254, 31
	s_nop 1
	v_lshl_add_u64 v[16:17], s[14:15], 0, v[16:17]
	v_lshl_add_u64 v[16:17], s[0:1], 2, v[16:17]
	s_lshl_b32 s14, s41, 2
	s_mov_b32 s15, s69
	v_lshl_add_u64 v[16:17], v[16:17], 0, s[14:15]
	global_store_dword v[16:17], v18, off
.LBB0_101:
	s_or_b64 exec, exec, s[8:9]
	v_add_u32_e32 v16, 0xb0, v142
	s_waitcnt lgkmcnt(0)
	v_ashrrev_i32_e32 v17, 31, v16
	v_readlane_b32 s8, v254, 28
	v_lshlrev_b64 v[18:19], 11, v[16:17]
	v_readlane_b32 s9, v254, 29
	s_nop 1
	v_lshl_add_u64 v[18:19], s[8:9], 0, v[18:19]
	v_lshl_add_u64 v[18:19], s[4:5], 1, v[18:19]
	v_lshl_add_u64 v[18:19], v[18:19], 0, s[68:69]
	v_lshl_add_u64 v[22:23], v[18:19], 0, v[146:147]
	s_waitcnt vmcnt(15)
	v_mov_b32_e32 v18, v232
	v_mov_b32_e32 v19, v233
	v_mov_b32_e32 v20, v234
	v_mov_b32_e32 v21, v235
	v_lshlrev_b32_e32 v24, 16, v18
	v_and_b32_e32 v25, 0xffff0000, v18
	v_lshlrev_b32_e32 v18, 16, v19
	v_and_b32_e32 v19, 0xffff0000, v19
	v_pk_add_f32 v[14:15], v[14:15], v[18:19]
	v_lshlrev_b32_e32 v18, 16, v20
	v_and_b32_e32 v19, 0xffff0000, v20
	v_pk_add_f32 v[18:19], v[8:9], v[18:19]
	v_lshlrev_b32_e32 v8, 16, v21
	v_and_b32_e32 v9, 0xffff0000, v21
	v_pk_add_f32 v[12:13], v[12:13], v[24:25]
	v_pk_add_f32 v[20:21], v[10:11], v[8:9]
	v_cvt_pk_bf16_f32 v8, v12, v13
	v_cvt_pk_bf16_f32 v9, v14, v15
	v_cvt_pk_bf16_f32 v10, v18, v19
	v_cvt_pk_bf16_f32 v11, v20, v21
	global_store_dwordx4 v[22:23], v[8:11], off sc0 sc1
	s_nop 1
	v_pk_mul_f32 v[10:11], v[12:13], v[12:13]
	v_pk_mul_f32 v[12:13], v[14:15], v[14:15]
	v_pk_mul_f32 v[8:9], v[18:19], v[18:19]
	v_pk_mul_f32 v[14:15], v[20:21], v[20:21]
	s_waitcnt vmcnt(15)
	v_mov_b32_e32 v18, v236
	v_mov_b32_e32 v19, v237
	v_mov_b32_e32 v20, v238
	v_mov_b32_e32 v21, v239
	v_lshlrev_b32_e32 v24, 16, v18
	v_and_b32_e32 v25, 0xffff0000, v18
	v_lshlrev_b32_e32 v18, 16, v19
	v_and_b32_e32 v19, 0xffff0000, v19
	v_pk_add_f32 v[6:7], v[6:7], v[18:19]
	v_lshlrev_b32_e32 v18, 16, v20
	v_and_b32_e32 v19, 0xffff0000, v20
	v_pk_add_f32 v[18:19], v[0:1], v[18:19]
	v_lshlrev_b32_e32 v0, 16, v21
	v_and_b32_e32 v1, 0xffff0000, v21
	v_pk_add_f32 v[4:5], v[4:5], v[24:25]
	v_pk_add_f32 v[20:21], v[2:3], v[0:1]
	v_cvt_pk_bf16_f32 v0, v4, v5
	v_cvt_pk_bf16_f32 v1, v6, v7
	v_cvt_pk_bf16_f32 v2, v18, v19
	v_cvt_pk_bf16_f32 v3, v20, v21
	global_store_dwordx4 v[22:23], v[0:3], off offset:256 sc0 sc1
	s_nop 1
	v_pk_mul_f32 v[0:1], v[4:5], v[4:5]
	v_pk_mul_f32 v[2:3], v[6:7], v[6:7]
	v_add_f32_e32 v0, v0, v1
	v_add_f32_e32 v2, v2, v3
	v_pk_mul_f32 v[4:5], v[18:19], v[18:19]
	v_add_f32_e32 v0, v0, v2
	v_add_f32_e32 v2, v12, v13
	v_add_f32_e32 v3, v10, v11
	v_pk_mul_f32 v[6:7], v[20:21], v[20:21]
	v_add_f32_e32 v1, v4, v5
	v_add_f32_e32 v2, v3, v2
	v_add_f32_e32 v3, v8, v9
	v_add_f32_e32 v6, v6, v7
	v_add_f32_e32 v0, v1, v0
	v_add_f32_e32 v1, v14, v15
	v_add_f32_e32 v2, v3, v2
	v_add_f32_e32 v0, v6, v0
	v_add_f32_e32 v1, v1, v2
	v_add_f32_e32 v0, v1, v0
	ds_bpermute_b32 v1, v161, v0
	s_waitcnt lgkmcnt(0)
	v_add_f32_e32 v0, v0, v1
	ds_bpermute_b32 v1, v160, v0
	s_and_saveexec_b64 s[4:5], s[10:11]
	s_cbranch_execz .LBB0_103
	v_readlane_b32 s8, v254, 30
	s_waitcnt lgkmcnt(0)
	v_add_f32_e32 v2, v0, v1
	v_lshlrev_b64 v[0:1], 6, v[16:17]
	v_readlane_b32 s9, v254, 31
	s_lshl_b32 s68, s41, 2
	s_nop 0
	v_lshl_add_u64 v[0:1], s[8:9], 0, v[0:1]
	v_lshl_add_u64 v[0:1], s[0:1], 2, v[0:1]
	v_lshl_add_u64 v[0:1], v[0:1], 0, s[68:69]
	global_store_dword v[0:1], v2, off

; #define LAS __attribute__((address_space(3)))
; __device__ __forceinline__ float sigmoidf_(float x) { return __builtin_amdgcn_rcpf(1.f + __expf(-x)); }
;     __device__ __forceinline__ void operator()(const f32x4 (&acc)[2][2][4][2], const Unit& u, int wr, int wc, int fr, int fq, const LAS float* rsl) const {
;         const int row0 = u.pm * 256 + wr * 64 + fr;
; #pragma unroll
;         for (int ai = 0; ai < 2; ++ai)
; #pragma unroll
;             for (int m = 0; m < 4; ++m) {
;                 const int row = row0 + ai * 128 + m * 16; const float rs = rsl[ai * 128 + wr * 64 + m * 16 + fr];
;                 f32x4 o[2];
; #pragma unroll
;                 for (int n = 0; n < 2; ++n)
; #pragma unroll
;                     for (int j = 0; j < 4; ++j) { const float gt = acc[ai][0][m][n][j] * rs, up = acc[ai][1][m][n][j] * rs; o[n][j] = gt * sigmoidf_(gt) * up; }
;                 *(u32x4*)(ACT + (size_t)row * DFF + u.pn * 128 + wc * 32 + 8 * fq) = pack8(o[0], o[1]);
;                 asm volatile("" ::: "memory");
;             }
;     }
.LBB0_209:
	v_add_u32_e32 v159, s51, v156
	ds_read_b32 v160, v159
	s_lshl_b32 s12, s50, 7
	v_lshl_add_u32 v158, s24, 8, v142
	s_ashr_i32 s13, s12, 31
	s_movk_i32 s17, 0x1600
	s_waitcnt lgkmcnt(0)
	v_pk_mul_f32 v[124:125], v[124:125], v[160:161] op_sel_hi:[1,0]
	v_pk_mul_f32 v[120:121], v[120:121], v[160:161] op_sel_hi:[1,0]
	v_mul_f32_e32 v152, 0xbfb8aa3b, v124
	v_exp_f32_e32 v152, v152
	v_pk_mul_f32 v[122:123], v[122:123], v[160:161] op_sel_hi:[1,0]
	v_pk_mul_f32 v[116:117], v[116:117], v[160:161] op_sel_hi:[1,0]
	v_pk_mul_f32 v[112:113], v[112:113], v[160:161] op_sel_hi:[1,0]
	v_add_f32_e32 v152, 1.0, v152
	v_rcp_f32_e32 v162, v152
	v_mul_f32_e32 v152, 0xbfb8aa3b, v125
	v_exp_f32_e32 v152, v152
	v_pk_mul_f32 v[114:115], v[114:115], v[160:161] op_sel_hi:[1,0]
	s_lshl_b64 s[12:13], s[12:13], 1
	s_and_b64 vcc, exec, s[10:11]
	v_add_f32_e32 v152, 1.0, v152
	v_rcp_f32_e32 v163, v152
	s_nop 0
	v_pk_mul_f32 v[124:125], v[124:125], v[162:163]
	s_nop 0
	v_pk_mul_f32 v[120:121], v[120:121], v[124:125]
	v_pk_mul_f32 v[124:125], v[126:127], v[160:161] op_sel_hi:[1,0]
	s_nop 0
	v_mul_f32_e32 v126, 0xbfb8aa3b, v124
	v_mul_f32_e32 v127, 0xbfb8aa3b, v125
	v_exp_f32_e32 v126, v126
	v_exp_f32_e32 v127, v127
	v_add_f32_e32 v126, 1.0, v126
	v_add_f32_e32 v127, 1.0, v127
	v_rcp_f32_e32 v126, v126
	v_rcp_f32_e32 v127, v127
	s_nop 0
	v_pk_mul_f32 v[124:125], v[124:125], v[126:127]
	s_nop 0
	v_pk_mul_f32 v[122:123], v[122:123], v[124:125]
	v_mul_f32_e32 v124, 0xbfb8aa3b, v116
	v_mul_f32_e32 v125, 0xbfb8aa3b, v117
	v_exp_f32_e32 v124, v124
	v_exp_f32_e32 v125, v125
	v_add_f32_e32 v124, 1.0, v124
	v_add_f32_e32 v125, 1.0, v125
	v_rcp_f32_e32 v124, v124
	v_rcp_f32_e32 v125, v125
	s_nop 0
	v_pk_mul_f32 v[116:117], v[116:117], v[124:125]
	s_nop 0
	v_pk_mul_f32 v[112:113], v[112:113], v[116:117]
	v_pk_mul_f32 v[116:117], v[118:119], v[160:161] op_sel_hi:[1,0]
	s_nop 0
	v_mul_f32_e32 v118, 0xbfb8aa3b, v116
	v_mul_f32_e32 v119, 0xbfb8aa3b, v117
	v_exp_f32_e32 v118, v118
	v_exp_f32_e32 v119, v119
	v_add_f32_e32 v118, 1.0, v118
	v_add_f32_e32 v119, 1.0, v119
	v_rcp_f32_e32 v118, v118
	v_rcp_f32_e32 v119, v119
	s_nop 0
	v_pk_mul_f32 v[116:117], v[116:117], v[118:119]
	s_nop 0
	v_pk_mul_f32 v[118:119], v[114:115], v[116:117]
	v_cvt_pk_bf16_f32 v116, v112, v113
	v_mov_b64_e32 v[112:113], s[72:73]
	v_cvt_pk_bf16_f32 v117, v118, v119
	v_mad_i64_i32 v[118:119], s[26:27], v158, s17, v[112:113]
	v_lshl_add_u64 v[118:119], v[118:119], 0, s[12:13]
	v_lshl_add_u64 v[118:119], v[118:119], 0, s[68:69]
	v_cvt_pk_bf16_f32 v114, v120, v121
	v_cvt_pk_bf16_f32 v115, v122, v123
	v_lshl_add_u64 v[118:119], v[118:119], 0, v[146:147]
	global_store_dwordx4 v[118:119], v[114:117], off sc0 sc1
	ds_read_b32 v114, v159 offset:64
	s_waitcnt lgkmcnt(0)
	v_pk_mul_f32 v[108:109], v[108:109], v[114:115] op_sel_hi:[1,0]
	s_nop 0
	v_mul_f32_e32 v115, 0xbfb8aa3b, v108
	v_exp_f32_e32 v115, v115
	s_nop 0
	v_add_f32_e32 v115, 1.0, v115
	v_rcp_f32_e32 v116, v115
	v_pk_mul_f32 v[104:105], v[104:105], v[114:115] op_sel_hi:[1,0]
	v_mul_f32_e32 v115, 0xbfb8aa3b, v109
	v_exp_f32_e32 v115, v115
	s_nop 0
	v_add_f32_e32 v115, 1.0, v115
	v_rcp_f32_e32 v117, v115
	v_pk_mul_f32 v[106:107], v[106:107], v[114:115] op_sel_hi:[1,0]
	v_pk_mul_f32 v[100:101], v[100:101], v[114:115] op_sel_hi:[1,0]
	v_pk_mul_f32 v[96:97], v[96:97], v[114:115] op_sel_hi:[1,0]
	v_pk_mul_f32 v[108:109], v[108:109], v[116:117]
	v_pk_mul_f32 v[98:99], v[98:99], v[114:115] op_sel_hi:[1,0]
	v_pk_mul_f32 v[104:105], v[104:105], v[108:109]
	v_pk_mul_f32 v[108:109], v[110:111], v[114:115] op_sel_hi:[1,0]
	s_nop 0
	v_mul_f32_e32 v110, 0xbfb8aa3b, v108
	v_mul_f32_e32 v111, 0xbfb8aa3b, v109
	v_exp_f32_e32 v110, v110
	v_exp_f32_e32 v111, v111
	v_add_f32_e32 v110, 1.0, v110
	v_add_f32_e32 v111, 1.0, v111
	v_rcp_f32_e32 v110, v110
	v_rcp_f32_e32 v111, v111
	s_nop 0
	v_pk_mul_f32 v[108:109], v[108:109], v[110:111]
	s_nop 0
	v_pk_mul_f32 v[106:107], v[106:107], v[108:109]
	v_mul_f32_e32 v108, 0xbfb8aa3b, v100
	v_mul_f32_e32 v109, 0xbfb8aa3b, v101
	v_exp_f32_e32 v108, v108
	v_exp_f32_e32 v109, v109
	v_add_f32_e32 v108, 1.0, v108
	v_add_f32_e32 v109, 1.0, v109
	v_rcp_f32_e32 v108, v108
	v_rcp_f32_e32 v109, v109
	s_nop 0
	v_pk_mul_f32 v[100:101], v[100:101], v[108:109]
	s_nop 0
	v_pk_mul_f32 v[100:101], v[96:97], v[100:101]
	v_pk_mul_f32 v[96:97], v[102:103], v[114:115] op_sel_hi:[1,0]
	v_or_b32_e32 v108, 16, v158
	v_mul_f32_e32 v102, 0xbfb8aa3b, v96
	v_mul_f32_e32 v103, 0xbfb8aa3b, v97
	v_exp_f32_e32 v102, v102
	v_exp_f32_e32 v103, v103
	v_add_f32_e32 v102, 1.0, v102
	v_add_f32_e32 v103, 1.0, v103
	v_rcp_f32_e32 v102, v102
	v_rcp_f32_e32 v103, v103
	s_nop 0
	v_pk_mul_f32 v[96:97], v[96:97], v[102:103]
	s_nop 0
	v_pk_mul_f32 v[102:103], v[98:99], v[96:97]
	v_cvt_pk_bf16_f32 v98, v100, v101
	v_mad_i64_i32 v[100:101], s[26:27], v108, s17, v[112:113]
	v_lshl_add_u64 v[100:101], v[100:101], 0, s[12:13]
	v_lshl_add_u64 v[100:101], v[100:101], 0, s[68:69]
	v_cvt_pk_bf16_f32 v96, v104, v105
	v_cvt_pk_bf16_f32 v97, v106, v107
	v_cvt_pk_bf16_f32 v99, v102, v103
	v_lshl_add_u64 v[100:101], v[100:101], 0, v[146:147]
	global_store_dwordx4 v[100:101], v[96:99], off sc0 sc1
	ds_read_b32 v96, v159 offset:128
	s_waitcnt lgkmcnt(0)
; #define LAS __attribute__((address_space(3)))
; __device__ __forceinline__ float sigmoidf_(float x) { return __builtin_amdgcn_rcpf(1.f + __expf(-x)); }
;     __device__ __forceinline__ void operator()(const f32x4 (&acc)[2][2][4][2], const Unit& u, int wr, int wc, int fr, int fq, const LAS float* rsl) const {
;         const int row0 = u.pm * 256 + wr * 64 + fr;
; #pragma unroll
;         for (int ai = 0; ai < 2; ++ai)
; #pragma unroll
;             for (int m = 0; m < 4; ++m) {
;                 const int row = row0 + ai * 128 + m * 16; const float rs = rsl[ai * 128 + wr * 64 + m * 16 + fr];
;                 f32x4 o[2];
; #pragma unroll
;                 for (int n = 0; n < 2; ++n)
; #pragma unroll
;                     for (int j = 0; j < 4; ++j) { const float gt = acc[ai][0][m][n][j] * rs, up = acc[ai][1][m][n][j] * rs; o[n][j] = gt * sigmoidf_(gt) * up; }
;                 *(u32x4*)(ACT + (size_t)row * DFF + u.pn * 128 + wc * 32 + 8 * fq) = pack8(o[0], o[1]);
;                 asm volatile("" ::: "memory");
;             }
;     }
	v_pk_mul_f32 v[92:93], v[92:93], v[96:97] op_sel_hi:[1,0]
	s_nop 0
	v_mul_f32_e32 v97, 0xbfb8aa3b, v92
	v_exp_f32_e32 v97, v97
	s_nop 0
	v_add_f32_e32 v97, 1.0, v97
	v_rcp_f32_e32 v98, v97
	v_pk_mul_f32 v[88:89], v[88:89], v[96:97] op_sel_hi:[1,0]
	v_mul_f32_e32 v97, 0xbfb8aa3b, v93
	v_exp_f32_e32 v97, v97
	s_nop 0
	v_add_f32_e32 v97, 1.0, v97
	v_rcp_f32_e32 v99, v97
	v_pk_mul_f32 v[90:91], v[90:91], v[96:97] op_sel_hi:[1,0]
	v_pk_mul_f32 v[84:85], v[84:85], v[96:97] op_sel_hi:[1,0]
	v_pk_mul_f32 v[80:81], v[80:81], v[96:97] op_sel_hi:[1,0]
	v_pk_mul_f32 v[92:93], v[92:93], v[98:99]
	v_pk_mul_f32 v[82:83], v[82:83], v[96:97] op_sel_hi:[1,0]
	v_pk_mul_f32 v[88:89], v[88:89], v[92:93]
	v_pk_mul_f32 v[92:93], v[94:95], v[96:97] op_sel_hi:[1,0]
	s_nop 0
	v_mul_f32_e32 v94, 0xbfb8aa3b, v92
	v_mul_f32_e32 v95, 0xbfb8aa3b, v93
	v_exp_f32_e32 v94, v94
	v_exp_f32_e32 v95, v95
	v_add_f32_e32 v94, 1.0, v94
	v_add_f32_e32 v95, 1.0, v95
	v_rcp_f32_e32 v94, v94
	v_rcp_f32_e32 v95, v95
	s_nop 0
	v_pk_mul_f32 v[92:93], v[92:93], v[94:95]
	s_nop 0
	v_pk_mul_f32 v[90:91], v[90:91], v[92:93]
	v_mul_f32_e32 v92, 0xbfb8aa3b, v84
	v_mul_f32_e32 v93, 0xbfb8aa3b, v85
	v_exp_f32_e32 v92, v92
	v_exp_f32_e32 v93, v93
	v_add_f32_e32 v92, 1.0, v92
	v_add_f32_e32 v93, 1.0, v93
	v_rcp_f32_e32 v92, v92
	v_rcp_f32_e32 v93, v93
	s_nop 0
	v_pk_mul_f32 v[84:85], v[84:85], v[92:93]
	s_nop 0
	v_pk_mul_f32 v[84:85], v[80:81], v[84:85]
	v_pk_mul_f32 v[80:81], v[86:87], v[96:97] op_sel_hi:[1,0]
	v_or_b32_e32 v92, 32, v158
	v_mul_f32_e32 v86, 0xbfb8aa3b, v80
	v_mul_f32_e32 v87, 0xbfb8aa3b, v81
	v_exp_f32_e32 v86, v86
	v_exp_f32_e32 v87, v87
	v_add_f32_e32 v86, 1.0, v86
	v_add_f32_e32 v87, 1.0, v87
	v_rcp_f32_e32 v86, v86
	v_rcp_f32_e32 v87, v87
	s_nop 0
	v_pk_mul_f32 v[80:81], v[80:81], v[86:87]
	s_nop 0
	v_pk_mul_f32 v[86:87], v[82:83], v[80:81]
	v_cvt_pk_bf16_f32 v82, v84, v85
	v_mad_i64_i32 v[84:85], s[26:27], v92, s17, v[112:113]
	v_lshl_add_u64 v[84:85], v[84:85], 0, s[12:13]
	v_lshl_add_u64 v[84:85], v[84:85], 0, s[68:69]
	v_cvt_pk_bf16_f32 v80, v88, v89
	v_cvt_pk_bf16_f32 v81, v90, v91
	v_cvt_pk_bf16_f32 v83, v86, v87
	v_lshl_add_u64 v[84:85], v[84:85], 0, v[146:147]
	global_store_dwordx4 v[84:85], v[80:83], off sc0 sc1
	ds_read_b32 v80, v159 offset:192
	s_waitcnt lgkmcnt(0)
	v_pk_mul_f32 v[76:77], v[76:77], v[80:81] op_sel_hi:[1,0]
	s_nop 0
	v_mul_f32_e32 v81, 0xbfb8aa3b, v76
	v_exp_f32_e32 v81, v81
	s_nop 0
	v_add_f32_e32 v81, 1.0, v81
	v_rcp_f32_e32 v82, v81
	v_pk_mul_f32 v[72:73], v[72:73], v[80:81] op_sel_hi:[1,0]
	v_mul_f32_e32 v81, 0xbfb8aa3b, v77
	v_exp_f32_e32 v81, v81
	s_nop 0
	v_add_f32_e32 v81, 1.0, v81
	v_rcp_f32_e32 v83, v81
	v_pk_mul_f32 v[74:75], v[74:75], v[80:81] op_sel_hi:[1,0]
	v_pk_mul_f32 v[68:69], v[68:69], v[80:81] op_sel_hi:[1,0]
	v_pk_mul_f32 v[64:65], v[64:65], v[80:81] op_sel_hi:[1,0]
	v_pk_mul_f32 v[76:77], v[76:77], v[82:83]
	v_pk_mul_f32 v[66:67], v[66:67], v[80:81] op_sel_hi:[1,0]
	v_pk_mul_f32 v[72:73], v[72:73], v[76:77]
	v_pk_mul_f32 v[76:77], v[78:79], v[80:81] op_sel_hi:[1,0]
	s_nop 0
	v_mul_f32_e32 v78, 0xbfb8aa3b, v76
	v_mul_f32_e32 v79, 0xbfb8aa3b, v77
	v_exp_f32_e32 v78, v78
	v_exp_f32_e32 v79, v79
	v_add_f32_e32 v78, 1.0, v78
	v_add_f32_e32 v79, 1.0, v79
	v_rcp_f32_e32 v78, v78
	v_rcp_f32_e32 v79, v79
	s_nop 0
	v_pk_mul_f32 v[76:77], v[76:77], v[78:79]
	s_nop 0
	v_pk_mul_f32 v[74:75], v[74:75], v[76:77]
	v_mul_f32_e32 v76, 0xbfb8aa3b, v68
	v_mul_f32_e32 v77, 0xbfb8aa3b, v69
	v_exp_f32_e32 v76, v76
	v_exp_f32_e32 v77, v77
	v_add_f32_e32 v76, 1.0, v76
	v_add_f32_e32 v77, 1.0, v77
	v_rcp_f32_e32 v76, v76
	v_rcp_f32_e32 v77, v77
	s_nop 0
	v_pk_mul_f32 v[68:69], v[68:69], v[76:77]
	s_nop 0
	v_pk_mul_f32 v[68:69], v[64:65], v[68:69]
	v_pk_mul_f32 v[64:65], v[70:71], v[80:81] op_sel_hi:[1,0]
	v_or_b32_e32 v76, 48, v158
	v_mul_f32_e32 v70, 0xbfb8aa3b, v64
	v_mul_f32_e32 v71, 0xbfb8aa3b, v65
	v_exp_f32_e32 v70, v70
	v_exp_f32_e32 v71, v71
	v_add_f32_e32 v70, 1.0, v70
	v_add_f32_e32 v71, 1.0, v71
	v_rcp_f32_e32 v70, v70
	v_rcp_f32_e32 v71, v71
	s_nop 0
	v_pk_mul_f32 v[64:65], v[64:65], v[70:71]
	s_nop 0
	v_pk_mul_f32 v[70:71], v[66:67], v[64:65]
	v_cvt_pk_bf16_f32 v66, v68, v69
	v_mad_i64_i32 v[68:69], s[26:27], v76, s17, v[112:113]
	v_lshl_add_u64 v[68:69], v[68:69], 0, s[12:13]
	v_lshl_add_u64 v[68:69], v[68:69], 0, s[68:69]
	v_cvt_pk_bf16_f32 v64, v72, v73
	v_cvt_pk_bf16_f32 v65, v74, v75
	v_cvt_pk_bf16_f32 v67, v70, v71
	v_lshl_add_u64 v[68:69], v[68:69], 0, v[146:147]
	global_store_dwordx4 v[68:69], v[64:67], off sc0 sc1
	ds_read_b32 v64, v159 offset:512
	s_nop 0
	v_add_u32_e32 v65, 0x80, v158
	s_waitcnt lgkmcnt(0)
; #define LAS __attribute__((address_space(3)))
; __device__ __forceinline__ float sigmoidf_(float x) { return __builtin_amdgcn_rcpf(1.f + __expf(-x)); }
;     __device__ __forceinline__ void operator()(const f32x4 (&acc)[2][2][4][2], const Unit& u, int wr, int wc, int fr, int fq, const LAS float* rsl) const {
;         const int row0 = u.pm * 256 + wr * 64 + fr;
; #pragma unroll
;         for (int ai = 0; ai < 2; ++ai)
; #pragma unroll
;             for (int m = 0; m < 4; ++m) {
;                 const int row = row0 + ai * 128 + m * 16; const float rs = rsl[ai * 128 + wr * 64 + m * 16 + fr];
;                 f32x4 o[2];
; #pragma unroll
;                 for (int n = 0; n < 2; ++n)
; #pragma unroll
;                     for (int j = 0; j < 4; ++j) { const float gt = acc[ai][0][m][n][j] * rs, up = acc[ai][1][m][n][j] * rs; o[n][j] = gt * sigmoidf_(gt) * up; }
;                 *(u32x4*)(ACT + (size_t)row * DFF + u.pn * 128 + wc * 32 + 8 * fq) = pack8(o[0], o[1]);
;                 asm volatile("" ::: "memory");
;             }
;     }
	v_pk_mul_f32 v[60:61], v[60:61], v[64:65] op_sel_hi:[1,0]
	s_nop 0
	v_mul_f32_e32 v66, 0xbfb8aa3b, v60
	v_mul_f32_e32 v67, 0xbfb8aa3b, v61
	v_exp_f32_e32 v66, v66
	v_exp_f32_e32 v67, v67
	v_pk_mul_f32 v[56:57], v[56:57], v[64:65] op_sel_hi:[1,0]
	v_pk_mul_f32 v[58:59], v[58:59], v[64:65] op_sel_hi:[1,0]
	v_add_f32_e32 v66, 1.0, v66
	v_add_f32_e32 v67, 1.0, v67
	v_rcp_f32_e32 v66, v66
	v_rcp_f32_e32 v67, v67
	v_pk_mul_f32 v[52:53], v[52:53], v[64:65] op_sel_hi:[1,0]
	v_pk_mul_f32 v[48:49], v[48:49], v[64:65] op_sel_hi:[1,0]
	v_pk_mul_f32 v[50:51], v[50:51], v[64:65] op_sel_hi:[1,0]
	v_pk_mul_f32 v[60:61], v[60:61], v[66:67]
	s_nop 0
	v_pk_mul_f32 v[56:57], v[56:57], v[60:61]
	v_pk_mul_f32 v[60:61], v[62:63], v[64:65] op_sel_hi:[1,0]
	s_nop 0
	v_mul_f32_e32 v62, 0xbfb8aa3b, v60
	v_mul_f32_e32 v63, 0xbfb8aa3b, v61
	v_exp_f32_e32 v62, v62
	v_exp_f32_e32 v63, v63
	v_add_f32_e32 v62, 1.0, v62
	v_add_f32_e32 v63, 1.0, v63
	v_rcp_f32_e32 v62, v62
	v_rcp_f32_e32 v63, v63
	s_nop 0
	v_pk_mul_f32 v[60:61], v[60:61], v[62:63]
	s_nop 0
	v_pk_mul_f32 v[58:59], v[58:59], v[60:61]
	v_mul_f32_e32 v60, 0xbfb8aa3b, v52
	v_mul_f32_e32 v61, 0xbfb8aa3b, v53
	v_exp_f32_e32 v60, v60
	v_exp_f32_e32 v61, v61
	v_add_f32_e32 v60, 1.0, v60
	v_add_f32_e32 v61, 1.0, v61
	v_rcp_f32_e32 v60, v60
	v_rcp_f32_e32 v61, v61
	s_nop 0
	v_pk_mul_f32 v[52:53], v[52:53], v[60:61]
	s_nop 0
	v_pk_mul_f32 v[52:53], v[48:49], v[52:53]
	v_pk_mul_f32 v[48:49], v[54:55], v[64:65] op_sel_hi:[1,0]
	s_nop 0
	v_mul_f32_e32 v54, 0xbfb8aa3b, v48
	v_mul_f32_e32 v55, 0xbfb8aa3b, v49
	v_exp_f32_e32 v54, v54
	v_exp_f32_e32 v55, v55
	v_add_f32_e32 v54, 1.0, v54
	v_add_f32_e32 v55, 1.0, v55
	v_rcp_f32_e32 v54, v54
	v_rcp_f32_e32 v55, v55
	s_nop 0
	v_pk_mul_f32 v[48:49], v[48:49], v[54:55]
	s_nop 0
	v_pk_mul_f32 v[54:55], v[50:51], v[48:49]
	v_cvt_pk_bf16_f32 v50, v52, v53
	v_mad_i64_i32 v[52:53], s[26:27], v65, s17, v[112:113]
	v_lshl_add_u64 v[52:53], v[52:53], 0, s[12:13]
	v_lshl_add_u64 v[52:53], v[52:53], 0, s[68:69]
	v_cvt_pk_bf16_f32 v48, v56, v57
	v_cvt_pk_bf16_f32 v49, v58, v59
	v_cvt_pk_bf16_f32 v51, v54, v55
	v_lshl_add_u64 v[52:53], v[52:53], 0, v[146:147]
	global_store_dwordx4 v[52:53], v[48:51], off sc0 sc1
	ds_read_b32 v48, v159 offset:576
	s_waitcnt lgkmcnt(0)
	v_pk_mul_f32 v[44:45], v[44:45], v[48:49] op_sel_hi:[1,0]
	s_nop 0
	v_mul_f32_e32 v49, 0xbfb8aa3b, v44
	v_exp_f32_e32 v49, v49
	s_nop 0
	v_add_f32_e32 v49, 1.0, v49
	v_rcp_f32_e32 v50, v49
	v_pk_mul_f32 v[40:41], v[40:41], v[48:49] op_sel_hi:[1,0]
	v_mul_f32_e32 v49, 0xbfb8aa3b, v45
	v_exp_f32_e32 v49, v49
	s_nop 0
	v_add_f32_e32 v49, 1.0, v49
	v_rcp_f32_e32 v51, v49
	v_pk_mul_f32 v[42:43], v[42:43], v[48:49] op_sel_hi:[1,0]
	v_pk_mul_f32 v[36:37], v[36:37], v[48:49] op_sel_hi:[1,0]
	v_pk_mul_f32 v[32:33], v[32:33], v[48:49] op_sel_hi:[1,0]
	v_pk_mul_f32 v[44:45], v[44:45], v[50:51]
	v_pk_mul_f32 v[34:35], v[34:35], v[48:49] op_sel_hi:[1,0]
	v_pk_mul_f32 v[40:41], v[40:41], v[44:45]
	v_pk_mul_f32 v[44:45], v[46:47], v[48:49] op_sel_hi:[1,0]
	s_nop 0
	v_mul_f32_e32 v46, 0xbfb8aa3b, v44
	v_mul_f32_e32 v47, 0xbfb8aa3b, v45
	v_exp_f32_e32 v46, v46
	v_exp_f32_e32 v47, v47
	v_add_f32_e32 v46, 1.0, v46
	v_add_f32_e32 v47, 1.0, v47
	v_rcp_f32_e32 v46, v46
	v_rcp_f32_e32 v47, v47
	s_nop 0
	v_pk_mul_f32 v[44:45], v[44:45], v[46:47]
	s_nop 0
	v_pk_mul_f32 v[42:43], v[42:43], v[44:45]
	v_mul_f32_e32 v44, 0xbfb8aa3b, v36
	v_mul_f32_e32 v45, 0xbfb8aa3b, v37
	v_exp_f32_e32 v44, v44
	v_exp_f32_e32 v45, v45
	v_add_f32_e32 v44, 1.0, v44
	v_add_f32_e32 v45, 1.0, v45
	v_rcp_f32_e32 v44, v44
	v_rcp_f32_e32 v45, v45
	s_nop 0
	v_pk_mul_f32 v[36:37], v[36:37], v[44:45]
	s_nop 0
	v_pk_mul_f32 v[36:37], v[32:33], v[36:37]
	v_pk_mul_f32 v[32:33], v[38:39], v[48:49] op_sel_hi:[1,0]
	v_add_u32_e32 v44, 0x90, v158
	v_mul_f32_e32 v38, 0xbfb8aa3b, v32
	v_mul_f32_e32 v39, 0xbfb8aa3b, v33
	v_exp_f32_e32 v38, v38
	v_exp_f32_e32 v39, v39
	v_add_f32_e32 v38, 1.0, v38
	v_add_f32_e32 v39, 1.0, v39
	v_rcp_f32_e32 v38, v38
	v_rcp_f32_e32 v39, v39
	s_nop 0
	v_pk_mul_f32 v[32:33], v[32:33], v[38:39]
	s_nop 0
	v_pk_mul_f32 v[38:39], v[34:35], v[32:33]
	v_cvt_pk_bf16_f32 v34, v36, v37
	v_mad_i64_i32 v[36:37], s[26:27], v44, s17, v[112:113]
	v_lshl_add_u64 v[36:37], v[36:37], 0, s[12:13]
	v_lshl_add_u64 v[36:37], v[36:37], 0, s[68:69]
	v_cvt_pk_bf16_f32 v32, v40, v41
	v_cvt_pk_bf16_f32 v33, v42, v43
	v_cvt_pk_bf16_f32 v35, v38, v39
	v_lshl_add_u64 v[36:37], v[36:37], 0, v[146:147]
	global_store_dwordx4 v[36:37], v[32:35], off sc0 sc1
	ds_read_b32 v32, v159 offset:640
	s_waitcnt lgkmcnt(0)
; #define LAS __attribute__((address_space(3)))
; __device__ __forceinline__ float sigmoidf_(float x) { return __builtin_amdgcn_rcpf(1.f + __expf(-x)); }
;     __device__ __forceinline__ void operator()(const f32x4 (&acc)[2][2][4][2], const Unit& u, int wr, int wc, int fr, int fq, const LAS float* rsl) const {
;         const int row0 = u.pm * 256 + wr * 64 + fr;
; #pragma unroll
;         for (int ai = 0; ai < 2; ++ai)
; #pragma unroll
;             for (int m = 0; m < 4; ++m) {
;                 const int row = row0 + ai * 128 + m * 16; const float rs = rsl[ai * 128 + wr * 64 + m * 16 + fr];
;                 f32x4 o[2];
; #pragma unroll
;                 for (int n = 0; n < 2; ++n)
; #pragma unroll
;                     for (int j = 0; j < 4; ++j) { const float gt = acc[ai][0][m][n][j] * rs, up = acc[ai][1][m][n][j] * rs; o[n][j] = gt * sigmoidf_(gt) * up; }
;                 *(u32x4*)(ACT + (size_t)row * DFF + u.pn * 128 + wc * 32 + 8 * fq) = pack8(o[0], o[1]);
;                 asm volatile("" ::: "memory");
;             }
;     }
	v_pk_mul_f32 v[28:29], v[28:29], v[32:33] op_sel_hi:[1,0]
	s_nop 0
	v_mul_f32_e32 v33, 0xbfb8aa3b, v28
	v_exp_f32_e32 v33, v33
	s_nop 0
	v_add_f32_e32 v33, 1.0, v33
	v_rcp_f32_e32 v34, v33
	v_pk_mul_f32 v[24:25], v[24:25], v[32:33] op_sel_hi:[1,0]
	v_mul_f32_e32 v33, 0xbfb8aa3b, v29
	v_exp_f32_e32 v33, v33
	s_nop 0
	v_add_f32_e32 v33, 1.0, v33
	v_rcp_f32_e32 v35, v33
	v_pk_mul_f32 v[26:27], v[26:27], v[32:33] op_sel_hi:[1,0]
	v_pk_mul_f32 v[20:21], v[20:21], v[32:33] op_sel_hi:[1,0]
	v_pk_mul_f32 v[16:17], v[16:17], v[32:33] op_sel_hi:[1,0]
	v_pk_mul_f32 v[28:29], v[28:29], v[34:35]
	v_pk_mul_f32 v[18:19], v[18:19], v[32:33] op_sel_hi:[1,0]
	v_pk_mul_f32 v[24:25], v[24:25], v[28:29]
	v_pk_mul_f32 v[28:29], v[30:31], v[32:33] op_sel_hi:[1,0]
	s_nop 0
	v_mul_f32_e32 v30, 0xbfb8aa3b, v28
	v_mul_f32_e32 v31, 0xbfb8aa3b, v29
	v_exp_f32_e32 v30, v30
	v_exp_f32_e32 v31, v31
	v_add_f32_e32 v30, 1.0, v30
	v_add_f32_e32 v31, 1.0, v31
	v_rcp_f32_e32 v30, v30
	v_rcp_f32_e32 v31, v31
	s_nop 0
	v_pk_mul_f32 v[28:29], v[28:29], v[30:31]
	s_nop 0
	v_pk_mul_f32 v[26:27], v[26:27], v[28:29]
	v_mul_f32_e32 v28, 0xbfb8aa3b, v20
	v_mul_f32_e32 v29, 0xbfb8aa3b, v21
	v_exp_f32_e32 v28, v28
	v_exp_f32_e32 v29, v29
	v_add_f32_e32 v28, 1.0, v28
	v_add_f32_e32 v29, 1.0, v29
	v_rcp_f32_e32 v28, v28
	v_rcp_f32_e32 v29, v29
	s_nop 0
	v_pk_mul_f32 v[20:21], v[20:21], v[28:29]
	s_nop 0
	v_pk_mul_f32 v[20:21], v[16:17], v[20:21]
	v_pk_mul_f32 v[16:17], v[22:23], v[32:33] op_sel_hi:[1,0]
	v_add_u32_e32 v28, 0xa0, v158
	v_mul_f32_e32 v22, 0xbfb8aa3b, v16
	v_mul_f32_e32 v23, 0xbfb8aa3b, v17
	v_exp_f32_e32 v22, v22
	v_exp_f32_e32 v23, v23
	v_add_f32_e32 v22, 1.0, v22
	v_add_f32_e32 v23, 1.0, v23
	v_rcp_f32_e32 v22, v22
	v_rcp_f32_e32 v23, v23
	s_nop 0
	v_pk_mul_f32 v[16:17], v[16:17], v[22:23]
	s_nop 0
	v_pk_mul_f32 v[22:23], v[18:19], v[16:17]
	v_cvt_pk_bf16_f32 v18, v20, v21
	v_mad_i64_i32 v[20:21], s[26:27], v28, s17, v[112:113]
	v_lshl_add_u64 v[20:21], v[20:21], 0, s[12:13]
	v_lshl_add_u64 v[20:21], v[20:21], 0, s[68:69]
	v_cvt_pk_bf16_f32 v16, v24, v25
	v_cvt_pk_bf16_f32 v17, v26, v27
	v_cvt_pk_bf16_f32 v19, v22, v23
	v_lshl_add_u64 v[20:21], v[20:21], 0, v[146:147]
	global_store_dwordx4 v[20:21], v[16:19], off sc0 sc1
	ds_read_b32 v16, v159 offset:704
	s_waitcnt lgkmcnt(0)
	v_pk_mul_f32 v[12:13], v[12:13], v[16:17] op_sel_hi:[1,0]
	s_nop 0
	v_mul_f32_e32 v17, 0xbfb8aa3b, v12
	v_exp_f32_e32 v17, v17
	s_nop 0
	v_add_f32_e32 v17, 1.0, v17
	v_rcp_f32_e32 v18, v17
	v_pk_mul_f32 v[8:9], v[8:9], v[16:17] op_sel_hi:[1,0]
	v_mul_f32_e32 v17, 0xbfb8aa3b, v13
	v_exp_f32_e32 v17, v17
	s_nop 0
	v_add_f32_e32 v17, 1.0, v17
	v_rcp_f32_e32 v19, v17
	v_pk_mul_f32 v[10:11], v[10:11], v[16:17] op_sel_hi:[1,0]
	v_pk_mul_f32 v[4:5], v[4:5], v[16:17] op_sel_hi:[1,0]
	v_pk_mul_f32 v[0:1], v[0:1], v[16:17] op_sel_hi:[1,0]
	v_pk_mul_f32 v[12:13], v[12:13], v[18:19]
	v_pk_mul_f32 v[2:3], v[2:3], v[16:17] op_sel_hi:[1,0]
	v_pk_mul_f32 v[8:9], v[8:9], v[12:13]
	v_pk_mul_f32 v[12:13], v[14:15], v[16:17] op_sel_hi:[1,0]
	s_nop 0
	v_mul_f32_e32 v14, 0xbfb8aa3b, v12
	v_mul_f32_e32 v15, 0xbfb8aa3b, v13
	v_exp_f32_e32 v14, v14
	v_exp_f32_e32 v15, v15
	v_add_f32_e32 v14, 1.0, v14
	v_add_f32_e32 v15, 1.0, v15
	v_rcp_f32_e32 v14, v14
	v_rcp_f32_e32 v15, v15
	s_nop 0
	v_pk_mul_f32 v[12:13], v[12:13], v[14:15]
	s_nop 0
	v_pk_mul_f32 v[10:11], v[10:11], v[12:13]
	v_mul_f32_e32 v12, 0xbfb8aa3b, v4
	v_mul_f32_e32 v13, 0xbfb8aa3b, v5
	v_exp_f32_e32 v12, v12
	v_exp_f32_e32 v13, v13
	v_add_f32_e32 v12, 1.0, v12
	v_add_f32_e32 v13, 1.0, v13
	v_rcp_f32_e32 v12, v12
	v_rcp_f32_e32 v13, v13
	s_nop 0
	v_pk_mul_f32 v[4:5], v[4:5], v[12:13]
	s_nop 0
	v_pk_mul_f32 v[4:5], v[0:1], v[4:5]
	v_pk_mul_f32 v[0:1], v[6:7], v[16:17] op_sel_hi:[1,0]
	v_add_u32_e32 v12, 0xb0, v158
	v_mul_f32_e32 v6, 0xbfb8aa3b, v0
	v_mul_f32_e32 v7, 0xbfb8aa3b, v1
	v_exp_f32_e32 v6, v6
	v_exp_f32_e32 v7, v7
	v_add_f32_e32 v6, 1.0, v6
	v_add_f32_e32 v7, 1.0, v7
	v_rcp_f32_e32 v6, v6
	v_rcp_f32_e32 v7, v7
	s_nop 0
	v_pk_mul_f32 v[0:1], v[0:1], v[6:7]
	s_nop 0
	v_pk_mul_f32 v[6:7], v[2:3], v[0:1]
	v_cvt_pk_bf16_f32 v2, v4, v5
	v_mad_i64_i32 v[4:5], s[26:27], v12, s17, v[112:113]
	v_lshl_add_u64 v[4:5], v[4:5], 0, s[12:13]
	v_lshl_add_u64 v[4:5], v[4:5], 0, s[68:69]
	v_cvt_pk_bf16_f32 v0, v8, v9
	v_cvt_pk_bf16_f32 v1, v10, v11
	v_cvt_pk_bf16_f32 v3, v6, v7
	v_lshl_add_u64 v[4:5], v[4:5], 0, v[146:147]
	global_store_dwordx4 v[4:5], v[0:3], off sc0 sc1
	s_mov_b64 s[12:13], -1
	s_cbranch_vccnz .LBB0_197
	s_andn2_b64 vcc, exec, s[4:5]
	s_cbranch_vccnz .LBB0_196
	s_barrier
	s_branch .LBB0_196

; #define LAS __attribute__((address_space(3)))
; __device__ __forceinline__ float bflo(unsigned w) { return __uint_as_float(w << 16); }
; __device__ __forceinline__ float bfhi(unsigned w) { return __uint_as_float(w & 0xffff0000u); }
;     __device__ __forceinline__ void operator()(const f32x4 (&acc)[2][2][4][2], const Unit& u, int wr, int wc, int fr, int fq, const LAS float* rsl) const {
;         const int row0 = u.pm * 256 + wr * 64 + fr;
; #pragma unroll
;         for (int ai = 0; ai < 2; ++ai)
; #pragma unroll
;             for (int m = 0; m < 4; ++m) {
;                 const int row = row0 + ai * 128 + m * 16; float s = 0.f;
; #pragma unroll
;                 for (int bj = 0; bj < 2; ++bj) {
;                     bf16_t* ptr = xb + (size_t)row * 1024 + u.pn * 256 + bj * 128 + wc * 32 + 8 * fq;
;                     const u32x4 g = *(const u32x4*)ptr;
;                     f32x4 v0 = acc[ai][bj][m][0], v1 = acc[ai][bj][m][1];
;                     v0[0] += bflo(g.x); v0[1] += bfhi(g.x); v0[2] += bflo(g.y); v0[3] += bfhi(g.y);
;                     v1[0] += bflo(g.z); v1[1] += bfhi(g.z); v1[2] += bflo(g.w); v1[3] += bfhi(g.w);
;                     *(u32x4*)ptr = pack8(v0, v1);
;                     s += (v0[0] * v0[0] + v0[1] * v0[1]) + (v0[2] * v0[2] + v0[3] * v0[3]) + (v1[0] * v1[0] + v1[1] * v1[1]) + (v1[2] * v1[2] + v1[3] * v1[3]);
;                 }
;                 s += __shfl_xor(s, 16); s += __shfl_xor(s, 32);
;                 if (fq == 0) ssq[(size_t)row * 16 + u.pn * 4 + wc] = s;
;             }
;     }
.LBB0_242:
	v_and_b32_e32 v146, 64, v223
	v_xor_b32_e32 v143, 16, v223
	v_add_u32_e32 v146, 64, v146
	v_cmp_lt_i32_e32 vcc, v143, v146
	v_lshl_add_u32 v142, s51, 8, v137
	v_readlane_b32 s8, v254, 28
	v_cndmask_b32_e32 v143, v223, v143, vcc
	v_lshlrev_b32_e32 v161, 2, v143
	v_xor_b32_e32 v143, 32, v223
	v_cmp_lt_i32_e32 vcc, v143, v146
	s_lshl_b32 s4, s50, 8
	v_readlane_b32 s9, v254, 29
	v_cndmask_b32_e32 v143, v223, v143, vcc
	v_lshlrev_b32_e32 v160, 2, v143
	v_ashrrev_i32_e32 v143, 31, v142
	v_lshlrev_b64 v[156:157], 11, v[142:143]
	s_ashr_i32 s5, s4, 31
	v_lshl_add_u64 v[156:157], s[8:9], 0, v[156:157]
	v_lshl_add_u64 v[156:157], s[4:5], 1, v[156:157]
	s_lshl_b32 s68, s43, 1
	v_lshl_add_u64 v[156:157], v[156:157], 0, s[68:69]
	v_lshlrev_b32_e32 v146, 1, v136
	v_lshl_add_u64 v[156:157], v[156:157], 0, v[146:147]
	v_mbcnt_lo_u32_b32 v163, -1, 0
	v_mbcnt_hi_u32_b32 v163, -1, v163
	v_and_b32_e32 v162, 15, v163
	v_lshrrev_b32_e32 v163, 4, v163
	v_lshlrev_b32_e32 v162, 11, v162
	v_readfirstlane_b32 s8, v156
	v_readfirstlane_b32 s9, v157
	v_lshl_or_b32 v162, v163, 4, v162
	s_nop 4
	global_load_dwordx4 v[168:171], v162, s[8:9]
	global_load_dwordx4 v[172:175], v162, s[8:9] offset:256
	s_add_u32 s8, s8, 0x8000
	s_addc_u32 s9, s9, 0
	global_load_dwordx4 v[176:179], v162, s[8:9]
	global_load_dwordx4 v[180:183], v162, s[8:9] offset:256
	s_add_u32 s8, s8, 0x8000
	s_addc_u32 s9, s9, 0
	global_load_dwordx4 v[184:187], v162, s[8:9]
	global_load_dwordx4 v[188:191], v162, s[8:9] offset:256
	s_add_u32 s8, s8, 0x8000
	s_addc_u32 s9, s9, 0
	global_load_dwordx4 v[192:195], v162, s[8:9]
	global_load_dwordx4 v[196:199], v162, s[8:9] offset:256
	s_add_u32 s8, s8, 0x28000
	s_addc_u32 s9, s9, 0
	global_load_dwordx4 v[200:203], v162, s[8:9]
	global_load_dwordx4 v[204:207], v162, s[8:9] offset:256
	s_add_u32 s8, s8, 0x8000
	s_addc_u32 s9, s9, 0
	global_load_dwordx4 v[208:211], v162, s[8:9]
	global_load_dwordx4 v[212:215], v162, s[8:9] offset:256
	s_add_u32 s8, s8, 0x8000
	s_addc_u32 s9, s9, 0
	global_load_dwordx4 v[216:219], v162, s[8:9]
	global_load_dwordx4 v[228:231], v162, s[8:9] offset:256
	s_add_u32 s8, s8, 0x8000
	s_addc_u32 s9, s9, 0
	global_load_dwordx4 v[232:235], v162, s[8:9]
	global_load_dwordx4 v[236:239], v162, s[8:9] offset:256
	s_waitcnt vmcnt(15)
	v_mov_b32_e32 v162, v168
	v_mov_b32_e32 v163, v169
	v_mov_b32_e32 v164, v170
	v_mov_b32_e32 v165, v171
	s_lshl_b32 s0, s50, 2
	s_ashr_i32 s1, s0, 31
	v_lshlrev_b32_e32 v166, 16, v162
	v_and_b32_e32 v167, 0xffff0000, v162
	v_lshlrev_b32_e32 v162, 16, v163
	v_and_b32_e32 v163, 0xffff0000, v163
	v_pk_add_f32 v[126:127], v[126:127], v[162:163]
	v_lshlrev_b32_e32 v162, 16, v164
	v_and_b32_e32 v163, 0xffff0000, v164
	v_pk_add_f32 v[162:163], v[120:121], v[162:163]
	v_lshlrev_b32_e32 v120, 16, v165
	v_and_b32_e32 v121, 0xffff0000, v165
	v_pk_add_f32 v[124:125], v[124:125], v[166:167]
	v_pk_add_f32 v[164:165], v[122:123], v[120:121]
	v_cvt_pk_bf16_f32 v120, v124, v125
	v_cvt_pk_bf16_f32 v121, v126, v127
	v_cvt_pk_bf16_f32 v122, v162, v163
	v_cvt_pk_bf16_f32 v123, v164, v165
	global_store_dwordx4 v[156:157], v[120:123], off sc0 sc1
	s_nop 1
	v_pk_mul_f32 v[122:123], v[124:125], v[124:125]
	v_pk_mul_f32 v[124:125], v[126:127], v[126:127]
	v_pk_mul_f32 v[120:121], v[162:163], v[162:163]
	v_pk_mul_f32 v[126:127], v[164:165], v[164:165]
	s_waitcnt vmcnt(15)
	v_mov_b32_e32 v162, v172
	v_mov_b32_e32 v163, v173
	v_mov_b32_e32 v164, v174
	v_mov_b32_e32 v165, v175
	v_lshlrev_b32_e32 v166, 16, v162
	v_and_b32_e32 v167, 0xffff0000, v162
	v_lshlrev_b32_e32 v162, 16, v163
	v_and_b32_e32 v163, 0xffff0000, v163
	v_pk_add_f32 v[118:119], v[118:119], v[162:163]
	v_lshlrev_b32_e32 v162, 16, v164
	v_and_b32_e32 v163, 0xffff0000, v164
	v_pk_add_f32 v[162:163], v[112:113], v[162:163]
	v_lshlrev_b32_e32 v112, 16, v165
	v_and_b32_e32 v113, 0xffff0000, v165
	v_pk_add_f32 v[116:117], v[116:117], v[166:167]
	v_pk_add_f32 v[164:165], v[114:115], v[112:113]
	v_cvt_pk_bf16_f32 v112, v116, v117
	v_cvt_pk_bf16_f32 v113, v118, v119
	v_cvt_pk_bf16_f32 v114, v162, v163
	v_cvt_pk_bf16_f32 v115, v164, v165
	global_store_dwordx4 v[156:157], v[112:115], off offset:256 sc0 sc1
	s_nop 1
	v_pk_mul_f32 v[112:113], v[116:117], v[116:117]
	v_pk_mul_f32 v[114:115], v[118:119], v[118:119]
	v_add_f32_e32 v112, v112, v113
	v_add_f32_e32 v114, v114, v115
	v_pk_mul_f32 v[116:117], v[162:163], v[162:163]
	v_add_f32_e32 v112, v112, v114
	v_add_f32_e32 v114, v124, v125
	v_add_f32_e32 v115, v122, v123
	v_pk_mul_f32 v[118:119], v[164:165], v[164:165]
	v_add_f32_e32 v113, v116, v117
	v_add_f32_e32 v114, v115, v114
	v_add_f32_e32 v115, v120, v121
	v_add_f32_e32 v118, v118, v119
	v_add_f32_e32 v112, v113, v112
	v_add_f32_e32 v113, v126, v127
	v_add_f32_e32 v114, v115, v114
	v_add_f32_e32 v112, v118, v112
	v_add_f32_e32 v113, v113, v114
	v_add_f32_e32 v112, v113, v112
	ds_bpermute_b32 v113, v161, v112
	s_waitcnt lgkmcnt(0)
	v_add_f32_e32 v112, v112, v113
	ds_bpermute_b32 v113, v160, v112
	s_and_saveexec_b64 s[8:9], s[10:11]
	s_cbranch_execz .LBB0_244
	v_readlane_b32 s14, v254, 30
	s_waitcnt lgkmcnt(0)
	v_add_f32_e32 v114, v112, v113
	v_lshlrev_b64 v[112:113], 6, v[142:143]
	v_readlane_b32 s15, v254, 31
	s_nop 1
	v_lshl_add_u64 v[112:113], s[14:15], 0, v[112:113]
	v_lshl_add_u64 v[112:113], s[0:1], 2, v[112:113]
	s_lshl_b32 s14, s41, 2
	s_mov_b32 s15, s69
	v_lshl_add_u64 v[112:113], v[112:113], 0, s[14:15]
	global_store_dword v[112:113], v114, off

; #define LAS __attribute__((address_space(3)))
; __device__ __forceinline__ float bflo(unsigned w) { return __uint_as_float(w << 16); }
; __device__ __forceinline__ float bfhi(unsigned w) { return __uint_as_float(w & 0xffff0000u); }
;     __device__ __forceinline__ void operator()(const f32x4 (&acc)[2][2][4][2], const Unit& u, int wr, int wc, int fr, int fq, const LAS float* rsl) const {
;         const int row0 = u.pm * 256 + wr * 64 + fr;
; #pragma unroll
;         for (int ai = 0; ai < 2; ++ai)
; #pragma unroll
;             for (int m = 0; m < 4; ++m) {
;                 const int row = row0 + ai * 128 + m * 16;
; #pragma unroll
;                 for (int bj = 0; bj < 2; ++bj) {
;                     bf16_t* ptr = P + (size_t)row * PW + u.pn * 256 + bj * 128 + wc * 32 + 8 * fq;
;                     const u32x4 g = *(const u32x4*)ptr; const u32x4 t = *(const u32x4*)(ptr + 1024);
;                     f32x4 v0 = acc[ai][bj][m][0], v1 = acc[ai][bj][m][1];
;                     v0[0] = v0[0] * bflo(g.x) + bflo(t.x); v0[1] = v0[1] * bfhi(g.x) + bfhi(t.x); v0[2] = v0[2] * bflo(g.y) + bflo(t.y); v0[3] = v0[3] * bfhi(g.y) + bfhi(t.y);
;                     v1[0] = v1[0] * bflo(g.z) + bflo(t.z); v1[1] = v1[1] * bfhi(g.z) + bfhi(t.z); v1[2] = v1[2] * bflo(g.w) + bflo(t.w); v1[3] = v1[3] * bfhi(g.w) + bfhi(t.w);
;                     *(u32x4*)ptr = pack8(v0, v1);
;                 }
;                 asm volatile("" ::: "memory");
;             }
;     }
.LBB0_317:
	s_lshl_b32 s0, s47, 8
	v_lshl_add_u32 v157, s46, 8, v142
	s_ashr_i32 s1, s0, 31
	v_mov_b64_e32 v[140:141], s[72:73]
	v_mad_i64_i32 v[158:159], s[2:3], v157, s80, v[140:141]
	s_lshl_b64 s[0:1], s[0:1], 1
	v_lshl_add_u64 v[158:159], v[158:159], 0, s[0:1]
	v_lshl_add_u64 v[158:159], v[158:159], 0, s[68:69]
	v_lshl_add_u64 v[166:167], v[158:159], 0, v[146:147]
	global_load_dwordx4 v[158:161], v[166:167], off
	global_load_dwordx4 v[162:165], v[166:167], off offset:2048
	s_and_b64 vcc, exec, s[10:11]
	s_waitcnt vmcnt(0)
	v_lshlrev_b32_e32 v168, 16, v158
	v_and_b32_e32 v169, 0xffff0000, v158
	v_lshlrev_b32_e32 v170, 16, v162
	v_and_b32_e32 v171, 0xffff0000, v162
	v_lshlrev_b32_e32 v158, 16, v159
	v_and_b32_e32 v159, 0xffff0000, v159
	v_lshlrev_b32_e32 v162, 16, v163
	v_and_b32_e32 v163, 0xffff0000, v163
	v_pk_fma_f32 v[126:127], v[126:127], v[158:159], v[162:163]
	v_lshlrev_b32_e32 v158, 16, v160
	v_and_b32_e32 v159, 0xffff0000, v160
	v_lshlrev_b32_e32 v162, 16, v164
	v_and_b32_e32 v163, 0xffff0000, v164
	v_pk_fma_f32 v[158:159], v[120:121], v[158:159], v[162:163]
	v_lshlrev_b32_e32 v120, 16, v161
	v_and_b32_e32 v121, 0xffff0000, v161
	v_lshlrev_b32_e32 v160, 16, v165
	v_and_b32_e32 v161, 0xffff0000, v165
	v_pk_fma_f32 v[124:125], v[124:125], v[168:169], v[170:171]
	v_pk_fma_f32 v[160:161], v[122:123], v[120:121], v[160:161]
	v_cvt_pk_bf16_f32 v120, v124, v125
	v_cvt_pk_bf16_f32 v121, v126, v127
	v_cvt_pk_bf16_f32 v122, v158, v159
	v_cvt_pk_bf16_f32 v123, v160, v161
	global_store_dwordx4 v[166:167], v[120:123], off sc0 sc1
	global_load_dwordx4 v[120:123], v[166:167], off offset:256
	s_nop 0
	global_load_dwordx4 v[124:127], v[166:167], off offset:2304
	s_waitcnt vmcnt(0)
	v_lshlrev_b32_e32 v158, 16, v120
	v_and_b32_e32 v159, 0xffff0000, v120
	v_lshlrev_b32_e32 v160, 16, v124
	v_and_b32_e32 v161, 0xffff0000, v124
	v_lshlrev_b32_e32 v120, 16, v121
	v_and_b32_e32 v121, 0xffff0000, v121
	v_lshlrev_b32_e32 v124, 16, v125
	v_and_b32_e32 v125, 0xffff0000, v125
	v_pk_fma_f32 v[118:119], v[118:119], v[120:121], v[124:125]
	v_lshlrev_b32_e32 v120, 16, v122
	v_and_b32_e32 v121, 0xffff0000, v122
	v_lshlrev_b32_e32 v124, 16, v126
	v_and_b32_e32 v125, 0xffff0000, v126
	v_pk_fma_f32 v[120:121], v[112:113], v[120:121], v[124:125]
	v_lshlrev_b32_e32 v112, 16, v123
	v_and_b32_e32 v113, 0xffff0000, v123
	v_lshlrev_b32_e32 v122, 16, v127
	v_and_b32_e32 v123, 0xffff0000, v127
	v_pk_fma_f32 v[116:117], v[116:117], v[158:159], v[160:161]
	v_pk_fma_f32 v[122:123], v[114:115], v[112:113], v[122:123]
	v_cvt_pk_bf16_f32 v112, v116, v117
	v_cvt_pk_bf16_f32 v113, v118, v119
	v_cvt_pk_bf16_f32 v114, v120, v121
	v_cvt_pk_bf16_f32 v115, v122, v123
	global_store_dwordx4 v[166:167], v[112:115], off offset:256 sc0 sc1
	s_nop 1
	v_or_b32_e32 v112, 16, v157
	v_mad_i64_i32 v[112:113], s[2:3], v112, s80, v[140:141]
	v_lshl_add_u64 v[112:113], v[112:113], 0, s[0:1]
	v_lshl_add_u64 v[112:113], v[112:113], 0, s[68:69]
	v_lshl_add_u64 v[112:113], v[112:113], 0, v[146:147]
	global_load_dwordx4 v[114:117], v[112:113], off
	global_load_dwordx4 v[118:121], v[112:113], off offset:2048
	s_waitcnt vmcnt(0)
	v_lshlrev_b32_e32 v122, 16, v114
	v_and_b32_e32 v123, 0xffff0000, v114
	v_lshlrev_b32_e32 v124, 16, v118
	v_and_b32_e32 v125, 0xffff0000, v118
	v_lshlrev_b32_e32 v114, 16, v115
	v_and_b32_e32 v115, 0xffff0000, v115
	v_lshlrev_b32_e32 v118, 16, v119
	v_and_b32_e32 v119, 0xffff0000, v119
	v_pk_fma_f32 v[110:111], v[110:111], v[114:115], v[118:119]
	v_lshlrev_b32_e32 v114, 16, v116
	v_and_b32_e32 v115, 0xffff0000, v116
	v_lshlrev_b32_e32 v118, 16, v120
	v_and_b32_e32 v119, 0xffff0000, v120
	v_pk_fma_f32 v[114:115], v[104:105], v[114:115], v[118:119]
	v_lshlrev_b32_e32 v104, 16, v117
	v_and_b32_e32 v105, 0xffff0000, v117
	v_lshlrev_b32_e32 v116, 16, v121
	v_and_b32_e32 v117, 0xffff0000, v121
	v_pk_fma_f32 v[108:109], v[108:109], v[122:123], v[124:125]
	v_pk_fma_f32 v[116:117], v[106:107], v[104:105], v[116:117]
	v_cvt_pk_bf16_f32 v104, v108, v109
	v_cvt_pk_bf16_f32 v105, v110, v111
	v_cvt_pk_bf16_f32 v106, v114, v115
	v_cvt_pk_bf16_f32 v107, v116, v117
	global_store_dwordx4 v[112:113], v[104:107], off sc0 sc1
	global_load_dwordx4 v[104:107], v[112:113], off offset:256
	s_nop 0
	global_load_dwordx4 v[108:111], v[112:113], off offset:2304
	s_waitcnt vmcnt(0)
	v_lshlrev_b32_e32 v114, 16, v104
	v_and_b32_e32 v115, 0xffff0000, v104
	v_lshlrev_b32_e32 v116, 16, v108
	v_and_b32_e32 v117, 0xffff0000, v108
	v_lshlrev_b32_e32 v104, 16, v105
	v_and_b32_e32 v105, 0xffff0000, v105
	v_lshlrev_b32_e32 v108, 16, v109
	v_and_b32_e32 v109, 0xffff0000, v109
	v_pk_fma_f32 v[102:103], v[102:103], v[104:105], v[108:109]
	v_lshlrev_b32_e32 v104, 16, v106
	v_and_b32_e32 v105, 0xffff0000, v106
	v_lshlrev_b32_e32 v108, 16, v110
	v_and_b32_e32 v109, 0xffff0000, v110
	v_pk_fma_f32 v[104:105], v[96:97], v[104:105], v[108:109]
	v_lshlrev_b32_e32 v96, 16, v107
	v_and_b32_e32 v97, 0xffff0000, v107
	v_lshlrev_b32_e32 v106, 16, v111
	v_and_b32_e32 v107, 0xffff0000, v111
	v_pk_fma_f32 v[100:101], v[100:101], v[114:115], v[116:117]
	v_pk_fma_f32 v[106:107], v[98:99], v[96:97], v[106:107]
	v_cvt_pk_bf16_f32 v96, v100, v101
	v_cvt_pk_bf16_f32 v97, v102, v103
	v_cvt_pk_bf16_f32 v98, v104, v105
	v_cvt_pk_bf16_f32 v99, v106, v107
	global_store_dwordx4 v[112:113], v[96:99], off offset:256 sc0 sc1
	s_nop 1
	v_or_b32_e32 v96, 32, v157
	v_mad_i64_i32 v[96:97], s[2:3], v96, s80, v[140:141]
	v_lshl_add_u64 v[96:97], v[96:97], 0, s[0:1]
	v_lshl_add_u64 v[96:97], v[96:97], 0, s[68:69]
	v_lshl_add_u64 v[96:97], v[96:97], 0, v[146:147]
	global_load_dwordx4 v[98:101], v[96:97], off
	global_load_dwordx4 v[102:105], v[96:97], off offset:2048
	s_waitcnt vmcnt(0)
; #define LAS __attribute__((address_space(3)))
; __device__ __forceinline__ float bflo(unsigned w) { return __uint_as_float(w << 16); }
; __device__ __forceinline__ float bfhi(unsigned w) { return __uint_as_float(w & 0xffff0000u); }
;     __device__ __forceinline__ void operator()(const f32x4 (&acc)[2][2][4][2], const Unit& u, int wr, int wc, int fr, int fq, const LAS float* rsl) const {
;         const int row0 = u.pm * 256 + wr * 64 + fr;
; #pragma unroll
;         for (int ai = 0; ai < 2; ++ai)
; #pragma unroll
;             for (int m = 0; m < 4; ++m) {
;                 const int row = row0 + ai * 128 + m * 16;
; #pragma unroll
;                 for (int bj = 0; bj < 2; ++bj) {
;                     bf16_t* ptr = P + (size_t)row * PW + u.pn * 256 + bj * 128 + wc * 32 + 8 * fq;
;                     const u32x4 g = *(const u32x4*)ptr; const u32x4 t = *(const u32x4*)(ptr + 1024);
;                     f32x4 v0 = acc[ai][bj][m][0], v1 = acc[ai][bj][m][1];
;                     v0[0] = v0[0] * bflo(g.x) + bflo(t.x); v0[1] = v0[1] * bfhi(g.x) + bfhi(t.x); v0[2] = v0[2] * bflo(g.y) + bflo(t.y); v0[3] = v0[3] * bfhi(g.y) + bfhi(t.y);
;                     v1[0] = v1[0] * bflo(g.z) + bflo(t.z); v1[1] = v1[1] * bfhi(g.z) + bfhi(t.z); v1[2] = v1[2] * bflo(g.w) + bflo(t.w); v1[3] = v1[3] * bfhi(g.w) + bfhi(t.w);
;                     *(u32x4*)ptr = pack8(v0, v1);
;                 }
;                 asm volatile("" ::: "memory");
;             }
;     }
	v_lshlrev_b32_e32 v106, 16, v98
	v_and_b32_e32 v107, 0xffff0000, v98
	v_lshlrev_b32_e32 v108, 16, v102
	v_and_b32_e32 v109, 0xffff0000, v102
	v_lshlrev_b32_e32 v98, 16, v99
	v_and_b32_e32 v99, 0xffff0000, v99
	v_lshlrev_b32_e32 v102, 16, v103
	v_and_b32_e32 v103, 0xffff0000, v103
	v_pk_fma_f32 v[94:95], v[94:95], v[98:99], v[102:103]
	v_lshlrev_b32_e32 v98, 16, v100
	v_and_b32_e32 v99, 0xffff0000, v100
	v_lshlrev_b32_e32 v102, 16, v104
	v_and_b32_e32 v103, 0xffff0000, v104
	v_pk_fma_f32 v[98:99], v[88:89], v[98:99], v[102:103]
	v_lshlrev_b32_e32 v88, 16, v101
	v_and_b32_e32 v89, 0xffff0000, v101
	v_lshlrev_b32_e32 v100, 16, v105
	v_and_b32_e32 v101, 0xffff0000, v105
	v_pk_fma_f32 v[92:93], v[92:93], v[106:107], v[108:109]
	v_pk_fma_f32 v[100:101], v[90:91], v[88:89], v[100:101]
	v_cvt_pk_bf16_f32 v88, v92, v93
	v_cvt_pk_bf16_f32 v89, v94, v95
	v_cvt_pk_bf16_f32 v90, v98, v99
	v_cvt_pk_bf16_f32 v91, v100, v101
	global_store_dwordx4 v[96:97], v[88:91], off sc0 sc1
	global_load_dwordx4 v[88:91], v[96:97], off offset:256
	s_nop 0
	global_load_dwordx4 v[92:95], v[96:97], off offset:2304
	s_waitcnt vmcnt(0)
	v_lshlrev_b32_e32 v98, 16, v88
	v_and_b32_e32 v99, 0xffff0000, v88
	v_lshlrev_b32_e32 v100, 16, v92
	v_and_b32_e32 v101, 0xffff0000, v92
	v_lshlrev_b32_e32 v88, 16, v89
	v_and_b32_e32 v89, 0xffff0000, v89
	v_lshlrev_b32_e32 v92, 16, v93
	v_and_b32_e32 v93, 0xffff0000, v93
	v_pk_fma_f32 v[86:87], v[86:87], v[88:89], v[92:93]
	v_lshlrev_b32_e32 v88, 16, v90
	v_and_b32_e32 v89, 0xffff0000, v90
	v_lshlrev_b32_e32 v92, 16, v94
	v_and_b32_e32 v93, 0xffff0000, v94
	v_pk_fma_f32 v[88:89], v[80:81], v[88:89], v[92:93]
	v_lshlrev_b32_e32 v80, 16, v91
	v_and_b32_e32 v81, 0xffff0000, v91
	v_lshlrev_b32_e32 v90, 16, v95
	v_and_b32_e32 v91, 0xffff0000, v95
	v_pk_fma_f32 v[84:85], v[84:85], v[98:99], v[100:101]
	v_pk_fma_f32 v[90:91], v[82:83], v[80:81], v[90:91]
	v_cvt_pk_bf16_f32 v80, v84, v85
	v_cvt_pk_bf16_f32 v81, v86, v87
	v_cvt_pk_bf16_f32 v82, v88, v89
	v_cvt_pk_bf16_f32 v83, v90, v91
	global_store_dwordx4 v[96:97], v[80:83], off offset:256 sc0 sc1
	s_nop 1
	v_or_b32_e32 v80, 48, v157
	v_mad_i64_i32 v[80:81], s[2:3], v80, s80, v[140:141]
	v_lshl_add_u64 v[80:81], v[80:81], 0, s[0:1]
	v_lshl_add_u64 v[80:81], v[80:81], 0, s[68:69]
	v_lshl_add_u64 v[80:81], v[80:81], 0, v[146:147]
	global_load_dwordx4 v[82:85], v[80:81], off
	global_load_dwordx4 v[86:89], v[80:81], off offset:2048
	s_waitcnt vmcnt(0)
	v_lshlrev_b32_e32 v90, 16, v82
	v_and_b32_e32 v91, 0xffff0000, v82
	v_lshlrev_b32_e32 v92, 16, v86
	v_and_b32_e32 v93, 0xffff0000, v86
	v_lshlrev_b32_e32 v82, 16, v83
	v_and_b32_e32 v83, 0xffff0000, v83
	v_lshlrev_b32_e32 v86, 16, v87
	v_and_b32_e32 v87, 0xffff0000, v87
	v_pk_fma_f32 v[78:79], v[78:79], v[82:83], v[86:87]
	v_lshlrev_b32_e32 v82, 16, v84
	v_and_b32_e32 v83, 0xffff0000, v84
	v_lshlrev_b32_e32 v86, 16, v88
	v_and_b32_e32 v87, 0xffff0000, v88
	v_pk_fma_f32 v[82:83], v[72:73], v[82:83], v[86:87]
	v_lshlrev_b32_e32 v72, 16, v85
	v_and_b32_e32 v73, 0xffff0000, v85
	v_lshlrev_b32_e32 v84, 16, v89
	v_and_b32_e32 v85, 0xffff0000, v89
	v_pk_fma_f32 v[76:77], v[76:77], v[90:91], v[92:93]
	v_pk_fma_f32 v[84:85], v[74:75], v[72:73], v[84:85]
	v_cvt_pk_bf16_f32 v72, v76, v77
	v_cvt_pk_bf16_f32 v73, v78, v79
	v_cvt_pk_bf16_f32 v74, v82, v83
	v_cvt_pk_bf16_f32 v75, v84, v85
	global_store_dwordx4 v[80:81], v[72:75], off sc0 sc1
	global_load_dwordx4 v[72:75], v[80:81], off offset:256
	s_nop 0
	global_load_dwordx4 v[76:79], v[80:81], off offset:2304
	s_waitcnt vmcnt(0)
	v_lshlrev_b32_e32 v82, 16, v72
	v_and_b32_e32 v83, 0xffff0000, v72
	v_lshlrev_b32_e32 v84, 16, v76
	v_and_b32_e32 v85, 0xffff0000, v76
	v_lshlrev_b32_e32 v72, 16, v73
	v_and_b32_e32 v73, 0xffff0000, v73
	v_lshlrev_b32_e32 v76, 16, v77
	v_and_b32_e32 v77, 0xffff0000, v77
	v_pk_fma_f32 v[70:71], v[70:71], v[72:73], v[76:77]
	v_lshlrev_b32_e32 v72, 16, v74
	v_and_b32_e32 v73, 0xffff0000, v74
	v_lshlrev_b32_e32 v76, 16, v78
	v_and_b32_e32 v77, 0xffff0000, v78
	v_pk_fma_f32 v[72:73], v[64:65], v[72:73], v[76:77]
	v_lshlrev_b32_e32 v64, 16, v75
	v_and_b32_e32 v65, 0xffff0000, v75
	v_lshlrev_b32_e32 v74, 16, v79
	v_and_b32_e32 v75, 0xffff0000, v79
	v_pk_fma_f32 v[68:69], v[68:69], v[82:83], v[84:85]
	v_pk_fma_f32 v[74:75], v[66:67], v[64:65], v[74:75]
	v_cvt_pk_bf16_f32 v64, v68, v69
	v_cvt_pk_bf16_f32 v65, v70, v71
	v_cvt_pk_bf16_f32 v66, v72, v73
	v_cvt_pk_bf16_f32 v67, v74, v75
	global_store_dwordx4 v[80:81], v[64:67], off offset:256 sc0 sc1
	s_nop 1
	v_add_u32_e32 v64, 0x80, v157
	v_mad_i64_i32 v[64:65], s[2:3], v64, s80, v[140:141]
	v_lshl_add_u64 v[64:65], v[64:65], 0, s[0:1]
	v_lshl_add_u64 v[64:65], v[64:65], 0, s[68:69]
	v_lshl_add_u64 v[64:65], v[64:65], 0, v[146:147]
	global_load_dwordx4 v[66:69], v[64:65], off
	global_load_dwordx4 v[70:73], v[64:65], off offset:2048
	s_waitcnt vmcnt(0)
	v_lshlrev_b32_e32 v74, 16, v66
	v_and_b32_e32 v75, 0xffff0000, v66
	v_lshlrev_b32_e32 v76, 16, v70
	v_and_b32_e32 v77, 0xffff0000, v70
	v_lshlrev_b32_e32 v66, 16, v67
	v_and_b32_e32 v67, 0xffff0000, v67
	v_lshlrev_b32_e32 v70, 16, v71
	v_and_b32_e32 v71, 0xffff0000, v71
	v_pk_fma_f32 v[62:63], v[62:63], v[66:67], v[70:71]
	v_lshlrev_b32_e32 v66, 16, v68
	v_and_b32_e32 v67, 0xffff0000, v68
	v_lshlrev_b32_e32 v70, 16, v72
	v_and_b32_e32 v71, 0xffff0000, v72
	v_pk_fma_f32 v[66:67], v[56:57], v[66:67], v[70:71]
	v_lshlrev_b32_e32 v56, 16, v69
	v_and_b32_e32 v57, 0xffff0000, v69
	v_lshlrev_b32_e32 v68, 16, v73
	v_and_b32_e32 v69, 0xffff0000, v73
	v_pk_fma_f32 v[60:61], v[60:61], v[74:75], v[76:77]
	v_pk_fma_f32 v[68:69], v[58:59], v[56:57], v[68:69]
	v_cvt_pk_bf16_f32 v56, v60, v61
	v_cvt_pk_bf16_f32 v57, v62, v63
	v_cvt_pk_bf16_f32 v58, v66, v67
	v_cvt_pk_bf16_f32 v59, v68, v69
	global_store_dwordx4 v[64:65], v[56:59], off sc0 sc1
	global_load_dwordx4 v[56:59], v[64:65], off offset:256
	s_nop 0
	global_load_dwordx4 v[60:63], v[64:65], off offset:2304
	s_waitcnt vmcnt(0)
; #define LAS __attribute__((address_space(3)))
; __device__ __forceinline__ float bflo(unsigned w) { return __uint_as_float(w << 16); }
; __device__ __forceinline__ float bfhi(unsigned w) { return __uint_as_float(w & 0xffff0000u); }
;     __device__ __forceinline__ void operator()(const f32x4 (&acc)[2][2][4][2], const Unit& u, int wr, int wc, int fr, int fq, const LAS float* rsl) const {
;         const int row0 = u.pm * 256 + wr * 64 + fr;
; #pragma unroll
;         for (int ai = 0; ai < 2; ++ai)
; #pragma unroll
;             for (int m = 0; m < 4; ++m) {
;                 const int row = row0 + ai * 128 + m * 16;
; #pragma unroll
;                 for (int bj = 0; bj < 2; ++bj) {
;                     bf16_t* ptr = P + (size_t)row * PW + u.pn * 256 + bj * 128 + wc * 32 + 8 * fq;
;                     const u32x4 g = *(const u32x4*)ptr; const u32x4 t = *(const u32x4*)(ptr + 1024);
;                     f32x4 v0 = acc[ai][bj][m][0], v1 = acc[ai][bj][m][1];
;                     v0[0] = v0[0] * bflo(g.x) + bflo(t.x); v0[1] = v0[1] * bfhi(g.x) + bfhi(t.x); v0[2] = v0[2] * bflo(g.y) + bflo(t.y); v0[3] = v0[3] * bfhi(g.y) + bfhi(t.y);
;                     v1[0] = v1[0] * bflo(g.z) + bflo(t.z); v1[1] = v1[1] * bfhi(g.z) + bfhi(t.z); v1[2] = v1[2] * bflo(g.w) + bflo(t.w); v1[3] = v1[3] * bfhi(g.w) + bfhi(t.w);
;                     *(u32x4*)ptr = pack8(v0, v1);
;                 }
;                 asm volatile("" ::: "memory");
;             }
;     }
	v_lshlrev_b32_e32 v66, 16, v56
	v_and_b32_e32 v67, 0xffff0000, v56
	v_lshlrev_b32_e32 v68, 16, v60
	v_and_b32_e32 v69, 0xffff0000, v60
	v_lshlrev_b32_e32 v56, 16, v57
	v_and_b32_e32 v57, 0xffff0000, v57
	v_lshlrev_b32_e32 v60, 16, v61
	v_and_b32_e32 v61, 0xffff0000, v61
	v_pk_fma_f32 v[54:55], v[54:55], v[56:57], v[60:61]
	v_lshlrev_b32_e32 v56, 16, v58
	v_and_b32_e32 v57, 0xffff0000, v58
	v_lshlrev_b32_e32 v60, 16, v62
	v_and_b32_e32 v61, 0xffff0000, v62
	v_pk_fma_f32 v[56:57], v[48:49], v[56:57], v[60:61]
	v_lshlrev_b32_e32 v48, 16, v59
	v_and_b32_e32 v49, 0xffff0000, v59
	v_lshlrev_b32_e32 v58, 16, v63
	v_and_b32_e32 v59, 0xffff0000, v63
	v_pk_fma_f32 v[52:53], v[52:53], v[66:67], v[68:69]
	v_pk_fma_f32 v[58:59], v[50:51], v[48:49], v[58:59]
	v_cvt_pk_bf16_f32 v48, v52, v53
	v_cvt_pk_bf16_f32 v49, v54, v55
	v_cvt_pk_bf16_f32 v50, v56, v57
	v_cvt_pk_bf16_f32 v51, v58, v59
	global_store_dwordx4 v[64:65], v[48:51], off offset:256 sc0 sc1
	s_nop 1
	v_add_u32_e32 v48, 0x90, v157
	v_mad_i64_i32 v[48:49], s[2:3], v48, s80, v[140:141]
	v_lshl_add_u64 v[48:49], v[48:49], 0, s[0:1]
	v_lshl_add_u64 v[48:49], v[48:49], 0, s[68:69]
	v_lshl_add_u64 v[48:49], v[48:49], 0, v[146:147]
	global_load_dwordx4 v[50:53], v[48:49], off
	global_load_dwordx4 v[54:57], v[48:49], off offset:2048
	s_waitcnt vmcnt(0)
	v_lshlrev_b32_e32 v58, 16, v50
	v_and_b32_e32 v59, 0xffff0000, v50
	v_lshlrev_b32_e32 v60, 16, v54
	v_and_b32_e32 v61, 0xffff0000, v54
	v_lshlrev_b32_e32 v50, 16, v51
	v_and_b32_e32 v51, 0xffff0000, v51
	v_lshlrev_b32_e32 v54, 16, v55
	v_and_b32_e32 v55, 0xffff0000, v55
	v_pk_fma_f32 v[46:47], v[46:47], v[50:51], v[54:55]
	v_lshlrev_b32_e32 v50, 16, v52
	v_and_b32_e32 v51, 0xffff0000, v52
	v_lshlrev_b32_e32 v54, 16, v56
	v_and_b32_e32 v55, 0xffff0000, v56
	v_pk_fma_f32 v[50:51], v[40:41], v[50:51], v[54:55]
	v_lshlrev_b32_e32 v40, 16, v53
	v_and_b32_e32 v41, 0xffff0000, v53
	v_lshlrev_b32_e32 v52, 16, v57
	v_and_b32_e32 v53, 0xffff0000, v57
	v_pk_fma_f32 v[44:45], v[44:45], v[58:59], v[60:61]
	v_pk_fma_f32 v[52:53], v[42:43], v[40:41], v[52:53]
	v_cvt_pk_bf16_f32 v40, v44, v45
	v_cvt_pk_bf16_f32 v41, v46, v47
	v_cvt_pk_bf16_f32 v42, v50, v51
	v_cvt_pk_bf16_f32 v43, v52, v53
	global_store_dwordx4 v[48:49], v[40:43], off sc0 sc1
	global_load_dwordx4 v[40:43], v[48:49], off offset:256
	s_nop 0
	global_load_dwordx4 v[44:47], v[48:49], off offset:2304
	s_waitcnt vmcnt(0)
	v_lshlrev_b32_e32 v50, 16, v40
	v_and_b32_e32 v51, 0xffff0000, v40
	v_lshlrev_b32_e32 v52, 16, v44
	v_and_b32_e32 v53, 0xffff0000, v44
	v_lshlrev_b32_e32 v40, 16, v41
	v_and_b32_e32 v41, 0xffff0000, v41
	v_lshlrev_b32_e32 v44, 16, v45
	v_and_b32_e32 v45, 0xffff0000, v45
	v_pk_fma_f32 v[38:39], v[38:39], v[40:41], v[44:45]
	v_lshlrev_b32_e32 v40, 16, v42
	v_and_b32_e32 v41, 0xffff0000, v42
	v_lshlrev_b32_e32 v44, 16, v46
	v_and_b32_e32 v45, 0xffff0000, v46
	v_pk_fma_f32 v[40:41], v[32:33], v[40:41], v[44:45]
	v_lshlrev_b32_e32 v32, 16, v43
	v_and_b32_e32 v33, 0xffff0000, v43
	v_lshlrev_b32_e32 v42, 16, v47
	v_and_b32_e32 v43, 0xffff0000, v47
	v_pk_fma_f32 v[36:37], v[36:37], v[50:51], v[52:53]
	v_pk_fma_f32 v[42:43], v[34:35], v[32:33], v[42:43]
	v_cvt_pk_bf16_f32 v32, v36, v37
	v_cvt_pk_bf16_f32 v33, v38, v39
	v_cvt_pk_bf16_f32 v34, v40, v41
	v_cvt_pk_bf16_f32 v35, v42, v43
	global_store_dwordx4 v[48:49], v[32:35], off offset:256 sc0 sc1
	s_nop 1
	v_add_u32_e32 v32, 0xa0, v157
	v_mad_i64_i32 v[32:33], s[2:3], v32, s80, v[140:141]
	v_lshl_add_u64 v[32:33], v[32:33], 0, s[0:1]
	v_lshl_add_u64 v[32:33], v[32:33], 0, s[68:69]
	v_lshl_add_u64 v[32:33], v[32:33], 0, v[146:147]
	global_load_dwordx4 v[34:37], v[32:33], off
	global_load_dwordx4 v[38:41], v[32:33], off offset:2048
	s_waitcnt vmcnt(0)
; #define LAS __attribute__((address_space(3)))
; __device__ __forceinline__ float bflo(unsigned w) { return __uint_as_float(w << 16); }
; __device__ __forceinline__ float bfhi(unsigned w) { return __uint_as_float(w & 0xffff0000u); }
;     __device__ __forceinline__ void operator()(const f32x4 (&acc)[2][2][4][2], const Unit& u, int wr, int wc, int fr, int fq, const LAS float* rsl) const {
;         const int row0 = u.pm * 256 + wr * 64 + fr;
; #pragma unroll
;         for (int ai = 0; ai < 2; ++ai)
; #pragma unroll
;             for (int m = 0; m < 4; ++m) {
;                 const int row = row0 + ai * 128 + m * 16;
; #pragma unroll
;                 for (int bj = 0; bj < 2; ++bj) {
;                     bf16_t* ptr = P + (size_t)row * PW + u.pn * 256 + bj * 128 + wc * 32 + 8 * fq;
;                     const u32x4 g = *(const u32x4*)ptr; const u32x4 t = *(const u32x4*)(ptr + 1024);
;                     f32x4 v0 = acc[ai][bj][m][0], v1 = acc[ai][bj][m][1];
;                     v0[0] = v0[0] * bflo(g.x) + bflo(t.x); v0[1] = v0[1] * bfhi(g.x) + bfhi(t.x); v0[2] = v0[2] * bflo(g.y) + bflo(t.y); v0[3] = v0[3] * bfhi(g.y) + bfhi(t.y);
;                     v1[0] = v1[0] * bflo(g.z) + bflo(t.z); v1[1] = v1[1] * bfhi(g.z) + bfhi(t.z); v1[2] = v1[2] * bflo(g.w) + bflo(t.w); v1[3] = v1[3] * bfhi(g.w) + bfhi(t.w);
;                     *(u32x4*)ptr = pack8(v0, v1);
;                 }
;                 asm volatile("" ::: "memory");
;             }
;     }
	v_lshlrev_b32_e32 v42, 16, v34
	v_and_b32_e32 v43, 0xffff0000, v34
	v_lshlrev_b32_e32 v44, 16, v38
	v_and_b32_e32 v45, 0xffff0000, v38
	v_lshlrev_b32_e32 v34, 16, v35
	v_and_b32_e32 v35, 0xffff0000, v35
	v_lshlrev_b32_e32 v38, 16, v39
	v_and_b32_e32 v39, 0xffff0000, v39
	v_pk_fma_f32 v[30:31], v[30:31], v[34:35], v[38:39]
	v_lshlrev_b32_e32 v34, 16, v36
	v_and_b32_e32 v35, 0xffff0000, v36
	v_lshlrev_b32_e32 v38, 16, v40
	v_and_b32_e32 v39, 0xffff0000, v40
	v_pk_fma_f32 v[34:35], v[24:25], v[34:35], v[38:39]
	v_lshlrev_b32_e32 v24, 16, v37
	v_and_b32_e32 v25, 0xffff0000, v37
	v_lshlrev_b32_e32 v36, 16, v41
	v_and_b32_e32 v37, 0xffff0000, v41
	v_pk_fma_f32 v[28:29], v[28:29], v[42:43], v[44:45]
	v_pk_fma_f32 v[36:37], v[26:27], v[24:25], v[36:37]
	v_cvt_pk_bf16_f32 v24, v28, v29
	v_cvt_pk_bf16_f32 v25, v30, v31
	v_cvt_pk_bf16_f32 v26, v34, v35
	v_cvt_pk_bf16_f32 v27, v36, v37
	global_store_dwordx4 v[32:33], v[24:27], off sc0 sc1
	global_load_dwordx4 v[24:27], v[32:33], off offset:256
	s_nop 0
	global_load_dwordx4 v[28:31], v[32:33], off offset:2304
	s_waitcnt vmcnt(0)
	v_lshlrev_b32_e32 v34, 16, v24
	v_and_b32_e32 v35, 0xffff0000, v24
	v_lshlrev_b32_e32 v36, 16, v28
	v_and_b32_e32 v37, 0xffff0000, v28
	v_lshlrev_b32_e32 v24, 16, v25
	v_and_b32_e32 v25, 0xffff0000, v25
	v_lshlrev_b32_e32 v28, 16, v29
	v_and_b32_e32 v29, 0xffff0000, v29
	v_pk_fma_f32 v[22:23], v[22:23], v[24:25], v[28:29]
	v_lshlrev_b32_e32 v24, 16, v26
	v_and_b32_e32 v25, 0xffff0000, v26
	v_lshlrev_b32_e32 v28, 16, v30
	v_and_b32_e32 v29, 0xffff0000, v30
	v_pk_fma_f32 v[24:25], v[16:17], v[24:25], v[28:29]
	v_lshlrev_b32_e32 v16, 16, v27
	v_and_b32_e32 v17, 0xffff0000, v27
	v_lshlrev_b32_e32 v26, 16, v31
	v_and_b32_e32 v27, 0xffff0000, v31
	v_pk_fma_f32 v[20:21], v[20:21], v[34:35], v[36:37]
	v_pk_fma_f32 v[26:27], v[18:19], v[16:17], v[26:27]
	v_cvt_pk_bf16_f32 v16, v20, v21
	v_cvt_pk_bf16_f32 v17, v22, v23
	v_cvt_pk_bf16_f32 v18, v24, v25
	v_cvt_pk_bf16_f32 v19, v26, v27
	global_store_dwordx4 v[32:33], v[16:19], off offset:256 sc0 sc1
	s_nop 1
	v_add_u32_e32 v16, 0xb0, v157
	v_mad_i64_i32 v[16:17], s[2:3], v16, s80, v[140:141]
	v_lshl_add_u64 v[16:17], v[16:17], 0, s[0:1]
	v_lshl_add_u64 v[16:17], v[16:17], 0, s[68:69]
	v_lshl_add_u64 v[16:17], v[16:17], 0, v[146:147]
	global_load_dwordx4 v[18:21], v[16:17], off
	global_load_dwordx4 v[22:25], v[16:17], off offset:2048
	s_mov_b64 s[0:1], -1
	s_waitcnt vmcnt(0)
	v_lshlrev_b32_e32 v26, 16, v18
	v_and_b32_e32 v27, 0xffff0000, v18
	v_lshlrev_b32_e32 v28, 16, v22
	v_and_b32_e32 v29, 0xffff0000, v22
	v_lshlrev_b32_e32 v18, 16, v19
	v_and_b32_e32 v19, 0xffff0000, v19
	v_lshlrev_b32_e32 v22, 16, v23
	v_and_b32_e32 v23, 0xffff0000, v23
	v_pk_fma_f32 v[14:15], v[14:15], v[18:19], v[22:23]
	v_lshlrev_b32_e32 v18, 16, v20
	v_and_b32_e32 v19, 0xffff0000, v20
	v_lshlrev_b32_e32 v22, 16, v24
	v_and_b32_e32 v23, 0xffff0000, v24
	v_pk_fma_f32 v[18:19], v[8:9], v[18:19], v[22:23]
	v_lshlrev_b32_e32 v8, 16, v21
	v_and_b32_e32 v9, 0xffff0000, v21
	v_lshlrev_b32_e32 v20, 16, v25
	v_and_b32_e32 v21, 0xffff0000, v25
	v_pk_fma_f32 v[12:13], v[12:13], v[26:27], v[28:29]
	v_pk_fma_f32 v[20:21], v[10:11], v[8:9], v[20:21]
	v_cvt_pk_bf16_f32 v8, v12, v13
	v_cvt_pk_bf16_f32 v9, v14, v15
	v_cvt_pk_bf16_f32 v10, v18, v19
	v_cvt_pk_bf16_f32 v11, v20, v21
	global_store_dwordx4 v[16:17], v[8:11], off sc0 sc1
	global_load_dwordx4 v[8:11], v[16:17], off offset:256
	s_nop 0
	global_load_dwordx4 v[12:15], v[16:17], off offset:2304
	s_waitcnt vmcnt(0)
	v_lshlrev_b32_e32 v18, 16, v8
	v_and_b32_e32 v19, 0xffff0000, v8
	v_lshlrev_b32_e32 v20, 16, v12
	v_and_b32_e32 v21, 0xffff0000, v12
	v_lshlrev_b32_e32 v8, 16, v9
	v_and_b32_e32 v9, 0xffff0000, v9
	v_lshlrev_b32_e32 v12, 16, v13
	v_and_b32_e32 v13, 0xffff0000, v13
	v_pk_fma_f32 v[6:7], v[6:7], v[8:9], v[12:13]
	v_lshlrev_b32_e32 v8, 16, v10
	v_and_b32_e32 v9, 0xffff0000, v10
	v_lshlrev_b32_e32 v12, 16, v14
	v_and_b32_e32 v13, 0xffff0000, v14
	v_pk_fma_f32 v[8:9], v[0:1], v[8:9], v[12:13]
	v_lshlrev_b32_e32 v0, 16, v11
	v_and_b32_e32 v1, 0xffff0000, v11
	v_lshlrev_b32_e32 v10, 16, v15
	v_and_b32_e32 v11, 0xffff0000, v15
	v_pk_fma_f32 v[4:5], v[4:5], v[18:19], v[20:21]
	v_pk_fma_f32 v[10:11], v[2:3], v[0:1], v[10:11]
	v_cvt_pk_bf16_f32 v0, v4, v5
	v_cvt_pk_bf16_f32 v1, v6, v7
	v_cvt_pk_bf16_f32 v2, v8, v9
	v_cvt_pk_bf16_f32 v3, v10, v11
	global_store_dwordx4 v[16:17], v[0:3], off offset:256 sc0 sc1
	s_cbranch_vccnz .LBB0_301
	s_andn2_b64 vcc, exec, s[18:19]
	s_cbranch_vccnz .LBB0_300
	s_barrier
	s_branch .LBB0_300

; #define LAS __attribute__((address_space(3)))
; __device__ __forceinline__ float sigmoidf_(float x) { return __builtin_amdgcn_rcpf(1.f + __expf(-x)); }
;     __device__ __forceinline__ void operator()(const f32x4 (&acc)[2][2][4][2], const Unit& u, int wr, int wc, int fr, int fq, const LAS float* rsl) const {
;         const int row0 = u.pm * 256 + wr * 64 + fr;
; #pragma unroll
;         for (int ai = 0; ai < 2; ++ai)
; #pragma unroll
;             for (int m = 0; m < 4; ++m) {
;                 const int row = row0 + ai * 128 + m * 16; const float rs = rsl[ai * 128 + wr * 64 + m * 16 + fr];
; #pragma unroll
;                 for (int bj = 0; bj < 2; ++bj) {
;                     f32x4 v0 = acc[ai][bj][m][0] * rs, v1 = acc[ai][bj][m][1] * rs;
; #pragma unroll
;                     for (int j = 0; j < 4; ++j) { v0[j] = sigmoidf_(v0[j]); v1[j] = sigmoidf_(v1[j]); }
;                     *(u32x4*)(P + (size_t)row * PW + u.pn * 256 + bj * 128 + wc * 32 + 8 * fq) = pack8(v0, v1);
;                 }
;                 asm volatile("" ::: "memory");
;             }
;     }
.LBB0_348:
	v_add_u32_e32 v158, s51, v156
	ds_read_b32 v160, v158
	s_lshl_b32 s12, s50, 8
	v_lshl_add_u32 v159, s24, 8, v142
	s_ashr_i32 s13, s12, 31
	s_lshl_b64 s[12:13], s[12:13], 1
	s_waitcnt lgkmcnt(0)
	v_pk_mul_f32 v[124:125], v[124:125], v[160:161] op_sel_hi:[1,0]
	v_pk_mul_f32 v[120:121], v[120:121], v[160:161] op_sel_hi:[1,0]
	v_pk_mul_f32 v[122:123], v[122:123], v[160:161] op_sel_hi:[1,0]
	v_pk_mul_f32 v[126:127], v[126:127], v[160:161] op_sel_hi:[1,0]
	v_mul_f32_e32 v124, 0xbfb8aa3b, v124
	v_mul_f32_e32 v120, 0xbfb8aa3b, v120
	v_mul_f32_e32 v125, 0xbfb8aa3b, v125
	v_mul_f32_e32 v121, 0xbfb8aa3b, v121
	v_mul_f32_e32 v122, 0xbfb8aa3b, v122
	v_exp_f32_e32 v124, v124
	v_exp_f32_e32 v120, v120
	v_exp_f32_e32 v125, v125
	v_exp_f32_e32 v121, v121
	v_mul_f32_e32 v126, 0xbfb8aa3b, v126
	v_exp_f32_e32 v122, v122
	v_mul_f32_e32 v127, 0xbfb8aa3b, v127
	v_exp_f32_e32 v126, v126
	v_exp_f32_e32 v127, v127
	v_mul_f32_e32 v123, 0xbfb8aa3b, v123
	v_add_f32_e32 v124, 1.0, v124
	v_add_f32_e32 v120, 1.0, v120
	v_add_f32_e32 v125, 1.0, v125
	v_add_f32_e32 v121, 1.0, v121
	v_add_f32_e32 v122, 1.0, v122
	v_exp_f32_e32 v123, v123
	v_rcp_f32_e32 v124, v124
	v_rcp_f32_e32 v120, v120
	v_rcp_f32_e32 v125, v125
	v_rcp_f32_e32 v121, v121
	v_add_f32_e32 v126, 1.0, v126
	v_rcp_f32_e32 v152, v122
	v_add_f32_e32 v122, 1.0, v127
	v_rcp_f32_e32 v126, v126
	v_rcp_f32_e32 v127, v122
	v_pk_mul_f32 v[112:113], v[112:113], v[160:161] op_sel_hi:[1,0]
	v_add_f32_e32 v122, 1.0, v123
	v_pk_mul_f32 v[116:117], v[116:117], v[160:161] op_sel_hi:[1,0]
	v_mul_f32_e32 v112, 0xbfb8aa3b, v112
	v_rcp_f32_e32 v153, v122
	v_cvt_pk_bf16_f32 v122, v124, v125
	v_cvt_pk_bf16_f32 v124, v120, v121
	v_mov_b64_e32 v[120:121], s[72:73]
	v_exp_f32_e32 v112, v112
	v_mul_f32_e32 v117, 0xbfb8aa3b, v117
	v_cvt_pk_bf16_f32 v123, v126, v127
	v_mad_i64_i32 v[126:127], s[26:27], v159, s80, v[120:121]
	v_exp_f32_e32 v117, v117
	v_lshl_add_u64 v[126:127], v[126:127], 0, s[12:13]
	v_lshl_add_u64 v[126:127], v[126:127], 0, s[68:69]
	v_cvt_pk_bf16_f32 v125, v152, v153
	v_lshl_add_u64 v[126:127], v[126:127], 0, v[146:147]
	v_pk_mul_f32 v[118:119], v[118:119], v[160:161] op_sel_hi:[1,0]
	v_add_f32_e32 v112, 1.0, v112
	v_mul_f32_e32 v113, 0xbfb8aa3b, v113
	global_store_dwordx4 v[126:127], v[122:125], off sc0 sc1
	v_exp_f32_e32 v113, v113
	v_pk_mul_f32 v[114:115], v[114:115], v[160:161] op_sel_hi:[1,0]
	v_rcp_f32_e32 v122, v112
	v_add_f32_e32 v112, 1.0, v117
	v_mul_f32_e32 v117, 0xbfb8aa3b, v118
	v_exp_f32_e32 v117, v117
	v_add_f32_e32 v113, 1.0, v113
	v_mul_f32_e32 v114, 0xbfb8aa3b, v114
	v_mul_f32_e32 v116, 0xbfb8aa3b, v116
	v_exp_f32_e32 v114, v114
	v_rcp_f32_e32 v118, v113
	v_add_f32_e32 v113, 1.0, v117
	v_mul_f32_e32 v117, 0xbfb8aa3b, v119
	v_mul_f32_e32 v115, 0xbfb8aa3b, v115
	v_exp_f32_e32 v116, v116
	v_exp_f32_e32 v117, v117
	v_exp_f32_e32 v115, v115
	v_add_f32_e32 v114, 1.0, v114
	v_add_f32_e32 v116, 1.0, v116
	v_rcp_f32_e32 v119, v114
	v_add_f32_e32 v114, 1.0, v117
	v_add_f32_e32 v115, 1.0, v115
	v_rcp_f32_e32 v116, v116
	v_rcp_f32_e32 v112, v112
	v_rcp_f32_e32 v113, v113
	v_rcp_f32_e32 v114, v114
	v_rcp_f32_e32 v115, v115
	v_cvt_pk_bf16_f32 v112, v116, v112
	s_and_b64 vcc, exec, s[10:11]
	v_cvt_pk_bf16_f32 v113, v113, v114
	v_cvt_pk_bf16_f32 v114, v122, v118
	v_cvt_pk_bf16_f32 v115, v119, v115
	global_store_dwordx4 v[126:127], v[112:115], off offset:256 sc0 sc1
	ds_read_b32 v112, v158 offset:64
	s_mov_b64 s[10:11], -1
	v_or_b32_e32 v113, 16, v159
	s_waitcnt lgkmcnt(0)
	v_pk_mul_f32 v[104:105], v[104:105], v[112:113] op_sel_hi:[1,0]
	v_pk_mul_f32 v[108:109], v[108:109], v[112:113] op_sel_hi:[1,0]
	v_mul_f32_e32 v104, 0xbfb8aa3b, v104
	v_exp_f32_e32 v104, v104
	v_mul_f32_e32 v109, 0xbfb8aa3b, v109
	v_exp_f32_e32 v109, v109
	v_pk_mul_f32 v[110:111], v[110:111], v[112:113] op_sel_hi:[1,0]
	v_add_f32_e32 v104, 1.0, v104
	v_mul_f32_e32 v105, 0xbfb8aa3b, v105
	v_exp_f32_e32 v105, v105
	v_rcp_f32_e32 v114, v104
	v_add_f32_e32 v104, 1.0, v109
	v_mul_f32_e32 v109, 0xbfb8aa3b, v110
	v_exp_f32_e32 v109, v109
	v_mul_f32_e32 v108, 0xbfb8aa3b, v108
	v_exp_f32_e32 v108, v108
	v_pk_mul_f32 v[106:107], v[106:107], v[112:113] op_sel_hi:[1,0]
	v_add_f32_e32 v105, 1.0, v105
	v_mul_f32_e32 v106, 0xbfb8aa3b, v106
	v_exp_f32_e32 v106, v106
	v_rcp_f32_e32 v110, v105
	v_add_f32_e32 v105, 1.0, v109
	v_mul_f32_e32 v109, 0xbfb8aa3b, v111
	v_mul_f32_e32 v107, 0xbfb8aa3b, v107
	v_exp_f32_e32 v109, v109
	v_exp_f32_e32 v107, v107
	v_add_f32_e32 v108, 1.0, v108
	v_rcp_f32_e32 v108, v108
	v_rcp_f32_e32 v104, v104
	v_add_f32_e32 v106, 1.0, v106
	v_pk_mul_f32 v[96:97], v[96:97], v[112:113] op_sel_hi:[1,0]
	v_rcp_f32_e32 v111, v106
	v_add_f32_e32 v106, 1.0, v109
	v_add_f32_e32 v107, 1.0, v107
	v_pk_mul_f32 v[100:101], v[100:101], v[112:113] op_sel_hi:[1,0]
	v_mul_f32_e32 v96, 0xbfb8aa3b, v96
	v_rcp_f32_e32 v105, v105
	v_rcp_f32_e32 v106, v106
	v_rcp_f32_e32 v107, v107
	v_exp_f32_e32 v96, v96
	v_mul_f32_e32 v101, 0xbfb8aa3b, v101
	v_cvt_pk_bf16_f32 v104, v108, v104
	v_mad_i64_i32 v[108:109], s[26:27], v113, s80, v[120:121]
	v_exp_f32_e32 v101, v101
	v_lshl_add_u64 v[108:109], v[108:109], 0, s[12:13]
	v_lshl_add_u64 v[108:109], v[108:109], 0, s[68:69]
	v_cvt_pk_bf16_f32 v105, v105, v106
	v_cvt_pk_bf16_f32 v106, v114, v110
	v_cvt_pk_bf16_f32 v107, v111, v107
	v_lshl_add_u64 v[108:109], v[108:109], 0, v[146:147]
	v_pk_mul_f32 v[102:103], v[102:103], v[112:113] op_sel_hi:[1,0]
	v_add_f32_e32 v96, 1.0, v96
	v_mul_f32_e32 v97, 0xbfb8aa3b, v97
	global_store_dwordx4 v[108:109], v[104:107], off sc0 sc1
	v_exp_f32_e32 v97, v97
	v_pk_mul_f32 v[98:99], v[98:99], v[112:113] op_sel_hi:[1,0]
	v_rcp_f32_e32 v104, v96
	v_add_f32_e32 v96, 1.0, v101
	v_mul_f32_e32 v101, 0xbfb8aa3b, v102
	v_exp_f32_e32 v101, v101
	v_add_f32_e32 v97, 1.0, v97
	v_mul_f32_e32 v98, 0xbfb8aa3b, v98
	v_mul_f32_e32 v100, 0xbfb8aa3b, v100
	v_exp_f32_e32 v98, v98
	v_rcp_f32_e32 v102, v97
	v_add_f32_e32 v97, 1.0, v101
	v_mul_f32_e32 v101, 0xbfb8aa3b, v103
	v_mul_f32_e32 v99, 0xbfb8aa3b, v99
	v_exp_f32_e32 v100, v100
	v_exp_f32_e32 v101, v101
	v_exp_f32_e32 v99, v99
	v_add_f32_e32 v98, 1.0, v98
	v_add_f32_e32 v100, 1.0, v100
	v_rcp_f32_e32 v103, v98
	v_add_f32_e32 v98, 1.0, v101
	v_add_f32_e32 v99, 1.0, v99
	v_rcp_f32_e32 v100, v100
	v_rcp_f32_e32 v96, v96
	v_rcp_f32_e32 v97, v97
	v_rcp_f32_e32 v98, v98
	v_rcp_f32_e32 v99, v99
	v_cvt_pk_bf16_f32 v96, v100, v96
	v_cvt_pk_bf16_f32 v97, v97, v98
	v_cvt_pk_bf16_f32 v98, v104, v102
	v_cvt_pk_bf16_f32 v99, v103, v99
	global_store_dwordx4 v[108:109], v[96:99], off offset:256 sc0 sc1
	ds_read_b32 v96, v158 offset:128
	s_nop 0
	v_or_b32_e32 v97, 32, v159
	s_waitcnt lgkmcnt(0)
; #define LAS __attribute__((address_space(3)))
; __device__ __forceinline__ float sigmoidf_(float x) { return __builtin_amdgcn_rcpf(1.f + __expf(-x)); }
;     __device__ __forceinline__ void operator()(const f32x4 (&acc)[2][2][4][2], const Unit& u, int wr, int wc, int fr, int fq, const LAS float* rsl) const {
;         const int row0 = u.pm * 256 + wr * 64 + fr;
; #pragma unroll
;         for (int ai = 0; ai < 2; ++ai)
; #pragma unroll
;             for (int m = 0; m < 4; ++m) {
;                 const int row = row0 + ai * 128 + m * 16; const float rs = rsl[ai * 128 + wr * 64 + m * 16 + fr];
; #pragma unroll
;                 for (int bj = 0; bj < 2; ++bj) {
;                     f32x4 v0 = acc[ai][bj][m][0] * rs, v1 = acc[ai][bj][m][1] * rs;
; #pragma unroll
;                     for (int j = 0; j < 4; ++j) { v0[j] = sigmoidf_(v0[j]); v1[j] = sigmoidf_(v1[j]); }
;                     *(u32x4*)(P + (size_t)row * PW + u.pn * 256 + bj * 128 + wc * 32 + 8 * fq) = pack8(v0, v1);
;                 }
;                 asm volatile("" ::: "memory");
;             }
;     }
	v_pk_mul_f32 v[88:89], v[88:89], v[96:97] op_sel_hi:[1,0]
	v_pk_mul_f32 v[92:93], v[92:93], v[96:97] op_sel_hi:[1,0]
	v_mul_f32_e32 v88, 0xbfb8aa3b, v88
	v_exp_f32_e32 v88, v88
	v_mul_f32_e32 v93, 0xbfb8aa3b, v93
	v_exp_f32_e32 v93, v93
	v_pk_mul_f32 v[94:95], v[94:95], v[96:97] op_sel_hi:[1,0]
	v_add_f32_e32 v88, 1.0, v88
	v_mul_f32_e32 v89, 0xbfb8aa3b, v89
	v_exp_f32_e32 v89, v89
	v_rcp_f32_e32 v98, v88
	v_add_f32_e32 v88, 1.0, v93
	v_mul_f32_e32 v93, 0xbfb8aa3b, v94
	v_exp_f32_e32 v93, v93
	v_mul_f32_e32 v92, 0xbfb8aa3b, v92
	v_exp_f32_e32 v92, v92
	v_pk_mul_f32 v[90:91], v[90:91], v[96:97] op_sel_hi:[1,0]
	v_add_f32_e32 v89, 1.0, v89
	v_mul_f32_e32 v90, 0xbfb8aa3b, v90
	v_exp_f32_e32 v90, v90
	v_rcp_f32_e32 v94, v89
	v_add_f32_e32 v89, 1.0, v93
	v_mul_f32_e32 v93, 0xbfb8aa3b, v95
	v_mul_f32_e32 v91, 0xbfb8aa3b, v91
	v_exp_f32_e32 v93, v93
	v_exp_f32_e32 v91, v91
	v_add_f32_e32 v92, 1.0, v92
	v_rcp_f32_e32 v92, v92
	v_rcp_f32_e32 v88, v88
	v_add_f32_e32 v90, 1.0, v90
	v_pk_mul_f32 v[80:81], v[80:81], v[96:97] op_sel_hi:[1,0]
	v_rcp_f32_e32 v95, v90
	v_add_f32_e32 v90, 1.0, v93
	v_add_f32_e32 v91, 1.0, v91
	v_pk_mul_f32 v[84:85], v[84:85], v[96:97] op_sel_hi:[1,0]
	v_mul_f32_e32 v80, 0xbfb8aa3b, v80
	v_rcp_f32_e32 v89, v89
	v_rcp_f32_e32 v90, v90
	v_rcp_f32_e32 v91, v91
	v_exp_f32_e32 v80, v80
	v_mul_f32_e32 v85, 0xbfb8aa3b, v85
	v_cvt_pk_bf16_f32 v88, v92, v88
	v_mad_i64_i32 v[92:93], s[26:27], v97, s80, v[120:121]
	v_exp_f32_e32 v85, v85
	v_lshl_add_u64 v[92:93], v[92:93], 0, s[12:13]
	v_lshl_add_u64 v[92:93], v[92:93], 0, s[68:69]
	v_cvt_pk_bf16_f32 v89, v89, v90
	v_cvt_pk_bf16_f32 v90, v98, v94
	v_cvt_pk_bf16_f32 v91, v95, v91
	v_lshl_add_u64 v[92:93], v[92:93], 0, v[146:147]
	v_pk_mul_f32 v[86:87], v[86:87], v[96:97] op_sel_hi:[1,0]
	v_add_f32_e32 v80, 1.0, v80
	v_mul_f32_e32 v81, 0xbfb8aa3b, v81
	global_store_dwordx4 v[92:93], v[88:91], off sc0 sc1
	v_exp_f32_e32 v81, v81
	v_pk_mul_f32 v[82:83], v[82:83], v[96:97] op_sel_hi:[1,0]
	v_rcp_f32_e32 v88, v80
	v_add_f32_e32 v80, 1.0, v85
	v_mul_f32_e32 v85, 0xbfb8aa3b, v86
	v_exp_f32_e32 v85, v85
	v_add_f32_e32 v81, 1.0, v81
	v_mul_f32_e32 v82, 0xbfb8aa3b, v82
	v_mul_f32_e32 v84, 0xbfb8aa3b, v84
	v_exp_f32_e32 v82, v82
	v_rcp_f32_e32 v86, v81
	v_add_f32_e32 v81, 1.0, v85
	v_mul_f32_e32 v85, 0xbfb8aa3b, v87
	v_mul_f32_e32 v83, 0xbfb8aa3b, v83
	v_exp_f32_e32 v84, v84
	v_exp_f32_e32 v85, v85
	v_exp_f32_e32 v83, v83
	v_add_f32_e32 v82, 1.0, v82
	v_add_f32_e32 v84, 1.0, v84
	v_rcp_f32_e32 v87, v82
	v_add_f32_e32 v82, 1.0, v85
	v_add_f32_e32 v83, 1.0, v83
	v_rcp_f32_e32 v84, v84
	v_rcp_f32_e32 v80, v80
	v_rcp_f32_e32 v81, v81
	v_rcp_f32_e32 v82, v82
	v_rcp_f32_e32 v83, v83
	v_cvt_pk_bf16_f32 v80, v84, v80
	v_cvt_pk_bf16_f32 v81, v81, v82
	v_cvt_pk_bf16_f32 v82, v88, v86
	v_cvt_pk_bf16_f32 v83, v87, v83
	global_store_dwordx4 v[92:93], v[80:83], off offset:256 sc0 sc1
	ds_read_b32 v80, v158 offset:192
	s_nop 0
	v_or_b32_e32 v81, 48, v159
	s_waitcnt lgkmcnt(0)
	v_pk_mul_f32 v[72:73], v[72:73], v[80:81] op_sel_hi:[1,0]
	v_pk_mul_f32 v[76:77], v[76:77], v[80:81] op_sel_hi:[1,0]
	v_mul_f32_e32 v72, 0xbfb8aa3b, v72
	v_exp_f32_e32 v72, v72
	v_mul_f32_e32 v77, 0xbfb8aa3b, v77
	v_exp_f32_e32 v77, v77
	v_pk_mul_f32 v[78:79], v[78:79], v[80:81] op_sel_hi:[1,0]
	v_add_f32_e32 v72, 1.0, v72
	v_mul_f32_e32 v73, 0xbfb8aa3b, v73
	v_exp_f32_e32 v73, v73
	v_rcp_f32_e32 v82, v72
	v_add_f32_e32 v72, 1.0, v77
	v_mul_f32_e32 v77, 0xbfb8aa3b, v78
	v_exp_f32_e32 v77, v77
	v_mul_f32_e32 v76, 0xbfb8aa3b, v76
	v_exp_f32_e32 v76, v76
	v_pk_mul_f32 v[74:75], v[74:75], v[80:81] op_sel_hi:[1,0]
	v_add_f32_e32 v73, 1.0, v73
	v_mul_f32_e32 v74, 0xbfb8aa3b, v74
	v_exp_f32_e32 v74, v74
	v_rcp_f32_e32 v78, v73
	v_add_f32_e32 v73, 1.0, v77
	v_mul_f32_e32 v77, 0xbfb8aa3b, v79
	v_mul_f32_e32 v75, 0xbfb8aa3b, v75
	v_exp_f32_e32 v77, v77
	v_exp_f32_e32 v75, v75
	v_add_f32_e32 v76, 1.0, v76
	v_rcp_f32_e32 v76, v76
	v_rcp_f32_e32 v72, v72
	v_add_f32_e32 v74, 1.0, v74
	v_pk_mul_f32 v[64:65], v[64:65], v[80:81] op_sel_hi:[1,0]
	v_rcp_f32_e32 v79, v74
	v_add_f32_e32 v74, 1.0, v77
	v_add_f32_e32 v75, 1.0, v75
	v_pk_mul_f32 v[68:69], v[68:69], v[80:81] op_sel_hi:[1,0]
	v_mul_f32_e32 v64, 0xbfb8aa3b, v64
	v_rcp_f32_e32 v73, v73
	v_rcp_f32_e32 v74, v74
	v_rcp_f32_e32 v75, v75
	v_exp_f32_e32 v64, v64
	v_mul_f32_e32 v69, 0xbfb8aa3b, v69
	v_cvt_pk_bf16_f32 v72, v76, v72
	v_mad_i64_i32 v[76:77], s[26:27], v81, s80, v[120:121]
	v_exp_f32_e32 v69, v69
	v_lshl_add_u64 v[76:77], v[76:77], 0, s[12:13]
	v_lshl_add_u64 v[76:77], v[76:77], 0, s[68:69]
	v_cvt_pk_bf16_f32 v73, v73, v74
	v_cvt_pk_bf16_f32 v74, v82, v78
	v_cvt_pk_bf16_f32 v75, v79, v75
	v_lshl_add_u64 v[76:77], v[76:77], 0, v[146:147]
	v_pk_mul_f32 v[70:71], v[70:71], v[80:81] op_sel_hi:[1,0]
	v_add_f32_e32 v64, 1.0, v64
	v_mul_f32_e32 v65, 0xbfb8aa3b, v65
	global_store_dwordx4 v[76:77], v[72:75], off sc0 sc1
	v_exp_f32_e32 v65, v65
	v_pk_mul_f32 v[66:67], v[66:67], v[80:81] op_sel_hi:[1,0]
	v_rcp_f32_e32 v72, v64
	v_add_f32_e32 v64, 1.0, v69
	v_mul_f32_e32 v69, 0xbfb8aa3b, v70
	v_exp_f32_e32 v69, v69
	v_add_f32_e32 v65, 1.0, v65
	v_mul_f32_e32 v66, 0xbfb8aa3b, v66
	v_mul_f32_e32 v68, 0xbfb8aa3b, v68
	v_exp_f32_e32 v66, v66
	v_rcp_f32_e32 v70, v65
	v_add_f32_e32 v65, 1.0, v69
	v_mul_f32_e32 v69, 0xbfb8aa3b, v71
	v_mul_f32_e32 v67, 0xbfb8aa3b, v67
	v_exp_f32_e32 v68, v68
	v_exp_f32_e32 v69, v69
	v_exp_f32_e32 v67, v67
	v_add_f32_e32 v66, 1.0, v66
	v_add_f32_e32 v68, 1.0, v68
	v_rcp_f32_e32 v71, v66
	v_add_f32_e32 v66, 1.0, v69
	v_add_f32_e32 v67, 1.0, v67
	v_rcp_f32_e32 v68, v68
	v_rcp_f32_e32 v64, v64
	v_rcp_f32_e32 v65, v65
	v_rcp_f32_e32 v66, v66
	v_rcp_f32_e32 v67, v67
	v_cvt_pk_bf16_f32 v64, v68, v64
	v_cvt_pk_bf16_f32 v65, v65, v66
	v_cvt_pk_bf16_f32 v66, v72, v70
	v_cvt_pk_bf16_f32 v67, v71, v67
	global_store_dwordx4 v[76:77], v[64:67], off offset:256 sc0 sc1
	ds_read_b32 v64, v158 offset:512
	s_nop 0
	v_add_u32_e32 v65, 0x80, v159
	s_waitcnt lgkmcnt(0)
; #define LAS __attribute__((address_space(3)))
; __device__ __forceinline__ float sigmoidf_(float x) { return __builtin_amdgcn_rcpf(1.f + __expf(-x)); }
;     __device__ __forceinline__ void operator()(const f32x4 (&acc)[2][2][4][2], const Unit& u, int wr, int wc, int fr, int fq, const LAS float* rsl) const {
;         const int row0 = u.pm * 256 + wr * 64 + fr;
; #pragma unroll
;         for (int ai = 0; ai < 2; ++ai)
; #pragma unroll
;             for (int m = 0; m < 4; ++m) {
;                 const int row = row0 + ai * 128 + m * 16; const float rs = rsl[ai * 128 + wr * 64 + m * 16 + fr];
; #pragma unroll
;                 for (int bj = 0; bj < 2; ++bj) {
;                     f32x4 v0 = acc[ai][bj][m][0] * rs, v1 = acc[ai][bj][m][1] * rs;
; #pragma unroll
;                     for (int j = 0; j < 4; ++j) { v0[j] = sigmoidf_(v0[j]); v1[j] = sigmoidf_(v1[j]); }
;                     *(u32x4*)(P + (size_t)row * PW + u.pn * 256 + bj * 128 + wc * 32 + 8 * fq) = pack8(v0, v1);
;                 }
;                 asm volatile("" ::: "memory");
;             }
;     }
	v_pk_mul_f32 v[56:57], v[56:57], v[64:65] op_sel_hi:[1,0]
	v_pk_mul_f32 v[60:61], v[60:61], v[64:65] op_sel_hi:[1,0]
	v_mul_f32_e32 v56, 0xbfb8aa3b, v56
	v_exp_f32_e32 v56, v56
	v_mul_f32_e32 v61, 0xbfb8aa3b, v61
	v_exp_f32_e32 v61, v61
	v_pk_mul_f32 v[62:63], v[62:63], v[64:65] op_sel_hi:[1,0]
	v_add_f32_e32 v56, 1.0, v56
	v_mul_f32_e32 v57, 0xbfb8aa3b, v57
	v_exp_f32_e32 v57, v57
	v_rcp_f32_e32 v66, v56
	v_add_f32_e32 v56, 1.0, v61
	v_mul_f32_e32 v61, 0xbfb8aa3b, v62
	v_exp_f32_e32 v61, v61
	v_mul_f32_e32 v60, 0xbfb8aa3b, v60
	v_exp_f32_e32 v60, v60
	v_pk_mul_f32 v[58:59], v[58:59], v[64:65] op_sel_hi:[1,0]
	v_add_f32_e32 v57, 1.0, v57
	v_mul_f32_e32 v58, 0xbfb8aa3b, v58
	v_exp_f32_e32 v58, v58
	v_rcp_f32_e32 v62, v57
	v_add_f32_e32 v57, 1.0, v61
	v_mul_f32_e32 v61, 0xbfb8aa3b, v63
	v_mul_f32_e32 v59, 0xbfb8aa3b, v59
	v_exp_f32_e32 v61, v61
	v_exp_f32_e32 v59, v59
	v_add_f32_e32 v60, 1.0, v60
	v_rcp_f32_e32 v60, v60
	v_rcp_f32_e32 v56, v56
	v_add_f32_e32 v58, 1.0, v58
	v_pk_mul_f32 v[48:49], v[48:49], v[64:65] op_sel_hi:[1,0]
	v_rcp_f32_e32 v63, v58
	v_add_f32_e32 v58, 1.0, v61
	v_add_f32_e32 v59, 1.0, v59
	v_pk_mul_f32 v[52:53], v[52:53], v[64:65] op_sel_hi:[1,0]
	v_mul_f32_e32 v48, 0xbfb8aa3b, v48
	v_rcp_f32_e32 v57, v57
	v_rcp_f32_e32 v58, v58
	v_rcp_f32_e32 v59, v59
	v_exp_f32_e32 v48, v48
	v_mul_f32_e32 v53, 0xbfb8aa3b, v53
	v_cvt_pk_bf16_f32 v56, v60, v56
	v_mad_i64_i32 v[60:61], s[26:27], v65, s80, v[120:121]
	v_exp_f32_e32 v53, v53
	v_lshl_add_u64 v[60:61], v[60:61], 0, s[12:13]
	v_lshl_add_u64 v[60:61], v[60:61], 0, s[68:69]
	v_cvt_pk_bf16_f32 v57, v57, v58
	v_cvt_pk_bf16_f32 v58, v66, v62
	v_cvt_pk_bf16_f32 v59, v63, v59
	v_lshl_add_u64 v[60:61], v[60:61], 0, v[146:147]
	v_pk_mul_f32 v[54:55], v[54:55], v[64:65] op_sel_hi:[1,0]
	v_add_f32_e32 v48, 1.0, v48
	v_mul_f32_e32 v49, 0xbfb8aa3b, v49
	global_store_dwordx4 v[60:61], v[56:59], off sc0 sc1
	v_exp_f32_e32 v49, v49
	v_pk_mul_f32 v[50:51], v[50:51], v[64:65] op_sel_hi:[1,0]
	v_rcp_f32_e32 v56, v48
	v_add_f32_e32 v48, 1.0, v53
	v_mul_f32_e32 v53, 0xbfb8aa3b, v54
	v_exp_f32_e32 v53, v53
	v_add_f32_e32 v49, 1.0, v49
	v_mul_f32_e32 v50, 0xbfb8aa3b, v50
	v_mul_f32_e32 v52, 0xbfb8aa3b, v52
	v_exp_f32_e32 v50, v50
	v_rcp_f32_e32 v54, v49
	v_add_f32_e32 v49, 1.0, v53
	v_mul_f32_e32 v53, 0xbfb8aa3b, v55
	v_mul_f32_e32 v51, 0xbfb8aa3b, v51
	v_exp_f32_e32 v52, v52
	v_exp_f32_e32 v53, v53
	v_exp_f32_e32 v51, v51
	v_add_f32_e32 v50, 1.0, v50
	v_add_f32_e32 v52, 1.0, v52
	v_rcp_f32_e32 v55, v50
	v_add_f32_e32 v50, 1.0, v53
	v_add_f32_e32 v51, 1.0, v51
	v_rcp_f32_e32 v52, v52
	v_rcp_f32_e32 v48, v48
	v_rcp_f32_e32 v49, v49
	v_rcp_f32_e32 v50, v50
	v_rcp_f32_e32 v51, v51
	v_cvt_pk_bf16_f32 v48, v52, v48
	v_cvt_pk_bf16_f32 v49, v49, v50
	v_cvt_pk_bf16_f32 v50, v56, v54
	v_cvt_pk_bf16_f32 v51, v55, v51
	global_store_dwordx4 v[60:61], v[48:51], off offset:256 sc0 sc1
	ds_read_b32 v48, v158 offset:576
	s_nop 0
	v_add_u32_e32 v49, 0x90, v159
	s_waitcnt lgkmcnt(0)
	v_pk_mul_f32 v[40:41], v[40:41], v[48:49] op_sel_hi:[1,0]
	v_pk_mul_f32 v[44:45], v[44:45], v[48:49] op_sel_hi:[1,0]
	v_mul_f32_e32 v40, 0xbfb8aa3b, v40
	v_exp_f32_e32 v40, v40
	v_mul_f32_e32 v45, 0xbfb8aa3b, v45
	v_exp_f32_e32 v45, v45
	v_pk_mul_f32 v[46:47], v[46:47], v[48:49] op_sel_hi:[1,0]
	v_add_f32_e32 v40, 1.0, v40
	v_mul_f32_e32 v41, 0xbfb8aa3b, v41
	v_exp_f32_e32 v41, v41
	v_rcp_f32_e32 v50, v40
	v_add_f32_e32 v40, 1.0, v45
	v_mul_f32_e32 v45, 0xbfb8aa3b, v46
	v_exp_f32_e32 v45, v45
	v_mul_f32_e32 v44, 0xbfb8aa3b, v44
	v_exp_f32_e32 v44, v44
	v_pk_mul_f32 v[42:43], v[42:43], v[48:49] op_sel_hi:[1,0]
	v_add_f32_e32 v41, 1.0, v41
	v_mul_f32_e32 v42, 0xbfb8aa3b, v42
	v_exp_f32_e32 v42, v42
	v_rcp_f32_e32 v46, v41
	v_add_f32_e32 v41, 1.0, v45
	v_mul_f32_e32 v45, 0xbfb8aa3b, v47
	v_mul_f32_e32 v43, 0xbfb8aa3b, v43
	v_exp_f32_e32 v45, v45
	v_exp_f32_e32 v43, v43
	v_add_f32_e32 v44, 1.0, v44
	v_rcp_f32_e32 v44, v44
	v_rcp_f32_e32 v40, v40
	v_add_f32_e32 v42, 1.0, v42
	v_pk_mul_f32 v[32:33], v[32:33], v[48:49] op_sel_hi:[1,0]
	v_rcp_f32_e32 v47, v42
	v_add_f32_e32 v42, 1.0, v45
	v_add_f32_e32 v43, 1.0, v43
	v_pk_mul_f32 v[36:37], v[36:37], v[48:49] op_sel_hi:[1,0]
	v_mul_f32_e32 v32, 0xbfb8aa3b, v32
	v_rcp_f32_e32 v41, v41
	v_rcp_f32_e32 v42, v42
	v_rcp_f32_e32 v43, v43
	v_exp_f32_e32 v32, v32
	v_mul_f32_e32 v37, 0xbfb8aa3b, v37
	v_cvt_pk_bf16_f32 v40, v44, v40
	v_mad_i64_i32 v[44:45], s[26:27], v49, s80, v[120:121]
	v_exp_f32_e32 v37, v37
	v_lshl_add_u64 v[44:45], v[44:45], 0, s[12:13]
	v_lshl_add_u64 v[44:45], v[44:45], 0, s[68:69]
	v_cvt_pk_bf16_f32 v41, v41, v42
	v_cvt_pk_bf16_f32 v42, v50, v46
	v_cvt_pk_bf16_f32 v43, v47, v43
	v_lshl_add_u64 v[44:45], v[44:45], 0, v[146:147]
	v_pk_mul_f32 v[38:39], v[38:39], v[48:49] op_sel_hi:[1,0]
	v_add_f32_e32 v32, 1.0, v32
	v_mul_f32_e32 v33, 0xbfb8aa3b, v33
	global_store_dwordx4 v[44:45], v[40:43], off sc0 sc1
	v_exp_f32_e32 v33, v33
	v_pk_mul_f32 v[34:35], v[34:35], v[48:49] op_sel_hi:[1,0]
	v_rcp_f32_e32 v40, v32
	v_add_f32_e32 v32, 1.0, v37
	v_mul_f32_e32 v37, 0xbfb8aa3b, v38
	v_exp_f32_e32 v37, v37
	v_add_f32_e32 v33, 1.0, v33
	v_mul_f32_e32 v34, 0xbfb8aa3b, v34
	v_mul_f32_e32 v36, 0xbfb8aa3b, v36
	v_exp_f32_e32 v34, v34
	v_rcp_f32_e32 v38, v33
	v_add_f32_e32 v33, 1.0, v37
	v_mul_f32_e32 v37, 0xbfb8aa3b, v39
	v_mul_f32_e32 v35, 0xbfb8aa3b, v35
	v_exp_f32_e32 v36, v36
	v_exp_f32_e32 v37, v37
	v_exp_f32_e32 v35, v35
	v_add_f32_e32 v34, 1.0, v34
	v_add_f32_e32 v36, 1.0, v36
	v_rcp_f32_e32 v39, v34
	v_add_f32_e32 v34, 1.0, v37
	v_add_f32_e32 v35, 1.0, v35
	v_rcp_f32_e32 v36, v36
	v_rcp_f32_e32 v32, v32
	v_rcp_f32_e32 v33, v33
	v_rcp_f32_e32 v34, v34
	v_rcp_f32_e32 v35, v35
	v_cvt_pk_bf16_f32 v32, v36, v32
	v_cvt_pk_bf16_f32 v33, v33, v34
	v_cvt_pk_bf16_f32 v34, v40, v38
	v_cvt_pk_bf16_f32 v35, v39, v35
	global_store_dwordx4 v[44:45], v[32:35], off offset:256 sc0 sc1
	ds_read_b32 v32, v158 offset:640
	s_nop 0
	v_add_u32_e32 v33, 0xa0, v159
	s_waitcnt lgkmcnt(0)
; #define LAS __attribute__((address_space(3)))
; __device__ __forceinline__ float sigmoidf_(float x) { return __builtin_amdgcn_rcpf(1.f + __expf(-x)); }
;     __device__ __forceinline__ void operator()(const f32x4 (&acc)[2][2][4][2], const Unit& u, int wr, int wc, int fr, int fq, const LAS float* rsl) const {
;         const int row0 = u.pm * 256 + wr * 64 + fr;
; #pragma unroll
;         for (int ai = 0; ai < 2; ++ai)
; #pragma unroll
;             for (int m = 0; m < 4; ++m) {
;                 const int row = row0 + ai * 128 + m * 16; const float rs = rsl[ai * 128 + wr * 64 + m * 16 + fr];
; #pragma unroll
;                 for (int bj = 0; bj < 2; ++bj) {
;                     f32x4 v0 = acc[ai][bj][m][0] * rs, v1 = acc[ai][bj][m][1] * rs;
; #pragma unroll
;                     for (int j = 0; j < 4; ++j) { v0[j] = sigmoidf_(v0[j]); v1[j] = sigmoidf_(v1[j]); }
;                     *(u32x4*)(P + (size_t)row * PW + u.pn * 256 + bj * 128 + wc * 32 + 8 * fq) = pack8(v0, v1);
;                 }
;                 asm volatile("" ::: "memory");
;             }
;     }
	v_pk_mul_f32 v[24:25], v[24:25], v[32:33] op_sel_hi:[1,0]
	v_pk_mul_f32 v[28:29], v[28:29], v[32:33] op_sel_hi:[1,0]
	v_mul_f32_e32 v24, 0xbfb8aa3b, v24
	v_exp_f32_e32 v24, v24
	v_mul_f32_e32 v29, 0xbfb8aa3b, v29
	v_exp_f32_e32 v29, v29
	v_pk_mul_f32 v[30:31], v[30:31], v[32:33] op_sel_hi:[1,0]
	v_add_f32_e32 v24, 1.0, v24
	v_mul_f32_e32 v25, 0xbfb8aa3b, v25
	v_exp_f32_e32 v25, v25
	v_rcp_f32_e32 v34, v24
	v_add_f32_e32 v24, 1.0, v29
	v_mul_f32_e32 v29, 0xbfb8aa3b, v30
	v_exp_f32_e32 v29, v29
	v_mul_f32_e32 v28, 0xbfb8aa3b, v28
	v_exp_f32_e32 v28, v28
	v_pk_mul_f32 v[26:27], v[26:27], v[32:33] op_sel_hi:[1,0]
	v_add_f32_e32 v25, 1.0, v25
	v_mul_f32_e32 v26, 0xbfb8aa3b, v26
	v_exp_f32_e32 v26, v26
	v_rcp_f32_e32 v30, v25
	v_add_f32_e32 v25, 1.0, v29
	v_mul_f32_e32 v29, 0xbfb8aa3b, v31
	v_mul_f32_e32 v27, 0xbfb8aa3b, v27
	v_exp_f32_e32 v29, v29
	v_exp_f32_e32 v27, v27
	v_add_f32_e32 v28, 1.0, v28
	v_rcp_f32_e32 v28, v28
	v_rcp_f32_e32 v24, v24
	v_add_f32_e32 v26, 1.0, v26
	v_pk_mul_f32 v[16:17], v[16:17], v[32:33] op_sel_hi:[1,0]
	v_rcp_f32_e32 v31, v26
	v_add_f32_e32 v26, 1.0, v29
	v_add_f32_e32 v27, 1.0, v27
	v_pk_mul_f32 v[20:21], v[20:21], v[32:33] op_sel_hi:[1,0]
	v_mul_f32_e32 v16, 0xbfb8aa3b, v16
	v_rcp_f32_e32 v25, v25
	v_rcp_f32_e32 v26, v26
	v_rcp_f32_e32 v27, v27
	v_exp_f32_e32 v16, v16
	v_mul_f32_e32 v21, 0xbfb8aa3b, v21
	v_cvt_pk_bf16_f32 v24, v28, v24
	v_mad_i64_i32 v[28:29], s[26:27], v33, s80, v[120:121]
	v_exp_f32_e32 v21, v21
	v_lshl_add_u64 v[28:29], v[28:29], 0, s[12:13]
	v_lshl_add_u64 v[28:29], v[28:29], 0, s[68:69]
	v_cvt_pk_bf16_f32 v25, v25, v26
	v_cvt_pk_bf16_f32 v26, v34, v30
	v_cvt_pk_bf16_f32 v27, v31, v27
	v_lshl_add_u64 v[28:29], v[28:29], 0, v[146:147]
	v_pk_mul_f32 v[22:23], v[22:23], v[32:33] op_sel_hi:[1,0]
	v_add_f32_e32 v16, 1.0, v16
	v_mul_f32_e32 v17, 0xbfb8aa3b, v17
	global_store_dwordx4 v[28:29], v[24:27], off sc0 sc1
	v_exp_f32_e32 v17, v17
	v_pk_mul_f32 v[18:19], v[18:19], v[32:33] op_sel_hi:[1,0]
	v_rcp_f32_e32 v24, v16
	v_add_f32_e32 v16, 1.0, v21
	v_mul_f32_e32 v21, 0xbfb8aa3b, v22
	v_exp_f32_e32 v21, v21
	v_add_f32_e32 v17, 1.0, v17
	v_mul_f32_e32 v18, 0xbfb8aa3b, v18
	v_mul_f32_e32 v20, 0xbfb8aa3b, v20
	v_exp_f32_e32 v18, v18
	v_rcp_f32_e32 v22, v17
	v_add_f32_e32 v17, 1.0, v21
	v_mul_f32_e32 v21, 0xbfb8aa3b, v23
	v_mul_f32_e32 v19, 0xbfb8aa3b, v19
	v_exp_f32_e32 v20, v20
	v_exp_f32_e32 v21, v21
	v_exp_f32_e32 v19, v19
	v_add_f32_e32 v18, 1.0, v18
	v_add_f32_e32 v20, 1.0, v20
	v_rcp_f32_e32 v23, v18
	v_add_f32_e32 v18, 1.0, v21
	v_add_f32_e32 v19, 1.0, v19
	v_rcp_f32_e32 v20, v20
	v_rcp_f32_e32 v16, v16
	v_rcp_f32_e32 v17, v17
	v_rcp_f32_e32 v18, v18
	v_rcp_f32_e32 v19, v19
	v_cvt_pk_bf16_f32 v16, v20, v16
	v_cvt_pk_bf16_f32 v17, v17, v18
	v_cvt_pk_bf16_f32 v18, v24, v22
	v_cvt_pk_bf16_f32 v19, v23, v19
	global_store_dwordx4 v[28:29], v[16:19], off offset:256 sc0 sc1
	ds_read_b32 v16, v158 offset:704
	s_nop 0
	v_add_u32_e32 v17, 0xb0, v159
	s_waitcnt lgkmcnt(0)
	v_pk_mul_f32 v[8:9], v[8:9], v[16:17] op_sel_hi:[1,0]
	v_pk_mul_f32 v[12:13], v[12:13], v[16:17] op_sel_hi:[1,0]
	v_mul_f32_e32 v8, 0xbfb8aa3b, v8
	v_exp_f32_e32 v8, v8
	v_mul_f32_e32 v13, 0xbfb8aa3b, v13
	v_exp_f32_e32 v13, v13
	v_pk_mul_f32 v[14:15], v[14:15], v[16:17] op_sel_hi:[1,0]
	v_add_f32_e32 v8, 1.0, v8
	v_mul_f32_e32 v9, 0xbfb8aa3b, v9
	v_exp_f32_e32 v9, v9
	v_rcp_f32_e32 v18, v8
	v_add_f32_e32 v8, 1.0, v13
	v_mul_f32_e32 v13, 0xbfb8aa3b, v14
	v_exp_f32_e32 v13, v13
	v_mul_f32_e32 v12, 0xbfb8aa3b, v12
	v_exp_f32_e32 v12, v12
	v_pk_mul_f32 v[10:11], v[10:11], v[16:17] op_sel_hi:[1,0]
	v_add_f32_e32 v9, 1.0, v9
	v_mul_f32_e32 v10, 0xbfb8aa3b, v10
	v_exp_f32_e32 v10, v10
	v_rcp_f32_e32 v14, v9
	v_add_f32_e32 v9, 1.0, v13
	v_mul_f32_e32 v13, 0xbfb8aa3b, v15
	v_mul_f32_e32 v11, 0xbfb8aa3b, v11
	v_exp_f32_e32 v13, v13
	v_exp_f32_e32 v11, v11
	v_add_f32_e32 v12, 1.0, v12
	v_rcp_f32_e32 v12, v12
	v_rcp_f32_e32 v8, v8
	v_add_f32_e32 v10, 1.0, v10
	v_pk_mul_f32 v[0:1], v[0:1], v[16:17] op_sel_hi:[1,0]
	v_rcp_f32_e32 v15, v10
	v_add_f32_e32 v10, 1.0, v13
	v_add_f32_e32 v11, 1.0, v11
	v_pk_mul_f32 v[4:5], v[4:5], v[16:17] op_sel_hi:[1,0]
	v_mul_f32_e32 v0, 0xbfb8aa3b, v0
	v_rcp_f32_e32 v9, v9
	v_rcp_f32_e32 v10, v10
	v_rcp_f32_e32 v11, v11
	v_exp_f32_e32 v0, v0
	v_mul_f32_e32 v5, 0xbfb8aa3b, v5
	v_cvt_pk_bf16_f32 v8, v12, v8
	v_mad_i64_i32 v[12:13], s[26:27], v17, s80, v[120:121]
	v_exp_f32_e32 v5, v5
	v_lshl_add_u64 v[12:13], v[12:13], 0, s[12:13]
	v_lshl_add_u64 v[12:13], v[12:13], 0, s[68:69]
	v_cvt_pk_bf16_f32 v9, v9, v10
	v_cvt_pk_bf16_f32 v10, v18, v14
	v_cvt_pk_bf16_f32 v11, v15, v11
	v_lshl_add_u64 v[12:13], v[12:13], 0, v[146:147]
	v_pk_mul_f32 v[6:7], v[6:7], v[16:17] op_sel_hi:[1,0]
	v_add_f32_e32 v0, 1.0, v0
	v_mul_f32_e32 v1, 0xbfb8aa3b, v1
	global_store_dwordx4 v[12:13], v[8:11], off sc0 sc1
	v_exp_f32_e32 v1, v1
	v_pk_mul_f32 v[2:3], v[2:3], v[16:17] op_sel_hi:[1,0]
	v_rcp_f32_e32 v8, v0
	v_add_f32_e32 v0, 1.0, v5
	v_mul_f32_e32 v5, 0xbfb8aa3b, v6
	v_exp_f32_e32 v5, v5
	v_add_f32_e32 v1, 1.0, v1
	v_mul_f32_e32 v2, 0xbfb8aa3b, v2
	v_mul_f32_e32 v4, 0xbfb8aa3b, v4
	v_exp_f32_e32 v2, v2
	v_rcp_f32_e32 v6, v1
	v_add_f32_e32 v1, 1.0, v5
	v_mul_f32_e32 v5, 0xbfb8aa3b, v7
	v_mul_f32_e32 v3, 0xbfb8aa3b, v3
	v_exp_f32_e32 v4, v4
	v_exp_f32_e32 v5, v5
	v_exp_f32_e32 v3, v3
	v_add_f32_e32 v2, 1.0, v2
	v_add_f32_e32 v4, 1.0, v4
	v_rcp_f32_e32 v7, v2
	v_add_f32_e32 v2, 1.0, v5
	v_add_f32_e32 v3, 1.0, v3
	v_rcp_f32_e32 v4, v4
	v_rcp_f32_e32 v0, v0
	v_rcp_f32_e32 v1, v1
	v_rcp_f32_e32 v2, v2
	v_rcp_f32_e32 v3, v3
	v_cvt_pk_bf16_f32 v0, v4, v0
	v_cvt_pk_bf16_f32 v1, v1, v2
	v_cvt_pk_bf16_f32 v2, v8, v6
	v_cvt_pk_bf16_f32 v3, v7, v3
	global_store_dwordx4 v[12:13], v[0:3], off offset:256 sc0 sc1
	s_cbranch_vccnz .LBB0_332
	s_andn2_b64 vcc, exec, s[4:5]
	s_cbranch_vccnz .LBB0_331
	s_barrier
	s_branch .LBB0_331

; #define LAS __attribute__((address_space(3)))
; __device__ __forceinline__ float bflo(unsigned w) { return __uint_as_float(w << 16); }
; __device__ __forceinline__ float bfhi(unsigned w) { return __uint_as_float(w & 0xffff0000u); }
;     __device__ __forceinline__ void operator()(const f32x4 (&acc)[2][2][4][2], const Unit& u, int wr, int wc, int fr, int fq, const LAS float* rsl) const {
;         const int row0 = u.pm * 256 + wr * 64 + fr;
; #pragma unroll
;         for (int ai = 0; ai < 2; ++ai)
; #pragma unroll
;             for (int m = 0; m < 4; ++m) {
;                 const int row = row0 + ai * 128 + m * 16; const float rs = rsl[ai * 128 + wr * 64 + m * 16 + fr];
;                 if (u.pn < 14) {
; #pragma unroll
;                     for (int bj = 0; bj < 2; ++bj) {
;                         const f32x4 v0 = acc[ai][bj][m][0] * rs, v1 = acc[ai][bj][m][1] * rs;
;                         *(u32x4*)(P + (size_t)row * PW + u.pn * 256 + bj * 128 + wc * 32 + 8 * fq) = pack8(v0, v1);
;                     }
;                 } else if (wc == 0) {
;                     const f32x4 v0 = acc[ai][0][m][0] * rs, v1 = acc[ai][0][m][1] * rs;
;                     const u32x4 hi = pack8(v0, v1);
;                     const f32x4 d0 = (f32x4){v0[0] - bflo(hi.x), v0[1] - bfhi(hi.x), v0[2] - bflo(hi.y), v0[3] - bfhi(hi.y)};
;                     const f32x4 d1 = (f32x4){v1[0] - bflo(hi.z), v1[1] - bfhi(hi.z), v1[2] - bflo(hi.w), v1[3] - bfhi(hi.w)};
;                     bf16_t* lp = lr + (size_t)row * 64 + (fq >> 1) * 32 + (fq & 1) * 8;
;                     *(u32x4*)lp = hi; *(u32x4*)(lp + 16) = pack8(d0, d1);
;                 }
;             }
;     }
.LBB0_556:
	v_add_u32_e32 v164, s15, v162
	ds_read_b32 v160, v164
	s_cmp_gt_i32 s50, 13
	s_cselect_b64 s[28:29], -1, 0
	v_cndmask_b32_e64 v146, 0, 1, s[18:19]
	v_lshl_add_u32 v158, s14, 8, v137
	s_mov_b64 s[14:15], -1
	s_and_b64 vcc, exec, s[28:29]
	v_cmp_ne_u32_e64 s[12:13], 1, v146
	s_cbranch_vccz .LBB0_560
	s_and_b64 vcc, exec, s[12:13]
	s_cbranch_vccnz .LBB0_559
	s_waitcnt lgkmcnt(0)
	v_pk_mul_f32 v[168:169], v[126:127], v[160:161] op_sel_hi:[1,0]
	v_pk_mul_f32 v[166:167], v[124:125], v[160:161] op_sel_hi:[1,0]
	v_pk_mul_f32 v[170:171], v[122:123], v[160:161] op_sel_hi:[1,0]
	v_pk_mul_f32 v[172:173], v[120:121], v[160:161] op_sel_hi:[1,0]
	v_cvt_pk_bf16_f32 v166, v166, v167
	v_cvt_pk_bf16_f32 v167, v168, v169
	v_cvt_pk_bf16_f32 v168, v172, v173
	v_cvt_pk_bf16_f32 v169, v170, v171
	v_ashrrev_i32_e32 v159, 31, v158
	v_lshlrev_b32_e32 v170, 16, v166
	v_and_b32_e32 v171, 0xffff0000, v166
	v_lshlrev_b32_e32 v172, 16, v167
	v_and_b32_e32 v173, 0xffff0000, v167
	v_lshlrev_b32_e32 v174, 16, v168
	v_and_b32_e32 v175, 0xffff0000, v168
	v_lshlrev_b32_e32 v176, 16, v169
	v_and_b32_e32 v177, 0xffff0000, v169
	v_lshlrev_b64 v[178:179], 7, v[158:159]
	v_pk_fma_f32 v[170:171], v[124:125], v[160:161], v[170:171] op_sel_hi:[1,0,1] neg_lo:[0,0,1] neg_hi:[0,0,1]
	v_pk_fma_f32 v[172:173], v[126:127], v[160:161], v[172:173] op_sel_hi:[1,0,1] neg_lo:[0,0,1] neg_hi:[0,0,1]
	v_pk_fma_f32 v[174:175], v[120:121], v[160:161], v[174:175] op_sel_hi:[1,0,1] neg_lo:[0,0,1] neg_hi:[0,0,1]
	v_pk_fma_f32 v[176:177], v[122:123], v[160:161], v[176:177] op_sel_hi:[1,0,1] neg_lo:[0,0,1] neg_hi:[0,0,1]
	v_lshl_add_u64 v[178:179], v[140:141], 0, v[178:179]
	global_store_dwordx4 v[178:179], v[166:169], off sc0 sc1
	s_nop 1
	v_cvt_pk_bf16_f32 v166, v170, v171
	v_cvt_pk_bf16_f32 v167, v172, v173
	v_cvt_pk_bf16_f32 v168, v174, v175
	v_cvt_pk_bf16_f32 v169, v176, v177
	global_store_dwordx4 v[178:179], v[166:169], off offset:32 sc0 sc1

; #define LAS __attribute__((address_space(3)))
; __device__ __forceinline__ float bflo(unsigned w) { return __uint_as_float(w << 16); }
; __device__ __forceinline__ float bfhi(unsigned w) { return __uint_as_float(w & 0xffff0000u); }
;     __device__ __forceinline__ void operator()(const f32x4 (&acc)[2][2][4][2], const Unit& u, int wr, int wc, int fr, int fq, const LAS float* rsl) const {
;         const int row0 = u.pm * 256 + wr * 64 + fr;
; #pragma unroll
;         for (int ai = 0; ai < 2; ++ai)
; #pragma unroll
;             for (int m = 0; m < 4; ++m) {
;                 const int row = row0 + ai * 128 + m * 16; const float rs = rsl[ai * 128 + wr * 64 + m * 16 + fr];
;                 if (u.pn < 14) {
; #pragma unroll
;                     for (int bj = 0; bj < 2; ++bj) {
;                         const f32x4 v0 = acc[ai][bj][m][0] * rs, v1 = acc[ai][bj][m][1] * rs;
;                         *(u32x4*)(P + (size_t)row * PW + u.pn * 256 + bj * 128 + wc * 32 + 8 * fq) = pack8(v0, v1);
;                     }
;                 } else if (wc == 0) {
;                     const f32x4 v0 = acc[ai][0][m][0] * rs, v1 = acc[ai][0][m][1] * rs;
;                     const u32x4 hi = pack8(v0, v1);
;                     const f32x4 d0 = (f32x4){v0[0] - bflo(hi.x), v0[1] - bfhi(hi.x), v0[2] - bflo(hi.y), v0[3] - bfhi(hi.y)};
;                     const f32x4 d1 = (f32x4){v1[0] - bflo(hi.z), v1[1] - bfhi(hi.z), v1[2] - bflo(hi.w), v1[3] - bfhi(hi.w)};
;                     bf16_t* lp = lr + (size_t)row * 64 + (fq >> 1) * 32 + (fq & 1) * 8;
;                     *(u32x4*)lp = hi; *(u32x4*)(lp + 16) = pack8(d0, d1);
;                 }
;             }
;     }
.LBB0_560:
	s_lshl_b32 s26, s50, 8
	s_ashr_i32 s27, s26, 31
	s_andn2_b64 vcc, exec, s[14:15]
	v_lshlrev_b32_e32 v146, 1, v136
	s_cbranch_vccnz .LBB0_562
	s_waitcnt lgkmcnt(0)
	v_pk_mul_f32 v[124:125], v[124:125], v[160:161] op_sel_hi:[1,0]
	v_pk_mul_f32 v[166:167], v[122:123], v[160:161] op_sel_hi:[1,0]
	v_pk_mul_f32 v[122:123], v[120:121], v[160:161] op_sel_hi:[1,0]
	v_cvt_pk_bf16_f32 v120, v124, v125
	v_mov_b64_e32 v[124:125], s[72:73]
	v_mad_i64_i32 v[124:125], s[14:15], v158, s80, v[124:125]
	v_lshl_add_u64 v[124:125], s[26:27], 1, v[124:125]
	s_lshl_b32 s68, s43, 1
	v_pk_mul_f32 v[126:127], v[126:127], v[160:161] op_sel_hi:[1,0]
	v_lshl_add_u64 v[124:125], v[124:125], 0, s[68:69]
	v_cvt_pk_bf16_f32 v121, v126, v127
	v_cvt_pk_bf16_f32 v122, v122, v123
	v_cvt_pk_bf16_f32 v123, v166, v167
	v_lshl_add_u64 v[124:125], v[124:125], 0, v[146:147]
	global_store_dwordx4 v[124:125], v[120:123], off sc0 sc1
	v_pk_mul_f32 v[118:119], v[118:119], v[160:161] op_sel_hi:[1,0]
	v_pk_mul_f32 v[116:117], v[116:117], v[160:161] op_sel_hi:[1,0]
	v_pk_mul_f32 v[120:121], v[114:115], v[160:161] op_sel_hi:[1,0]
	v_pk_mul_f32 v[114:115], v[112:113], v[160:161] op_sel_hi:[1,0]
	v_cvt_pk_bf16_f32 v112, v116, v117
	v_cvt_pk_bf16_f32 v113, v118, v119
	v_cvt_pk_bf16_f32 v114, v114, v115
	v_cvt_pk_bf16_f32 v115, v120, v121
	global_store_dwordx4 v[124:125], v[112:115], off offset:256 sc0 sc1
.LBB0_562:
	ds_read_b32 v112, v164 offset:64
	s_nop 0
	v_cndmask_b32_e64 v113, 0, 1, s[28:29]
	v_or_b32_e32 v114, 16, v158
	v_cmp_ne_u32_e64 s[14:15], 1, v113
	s_andn2_b64 vcc, exec, s[28:29]
	s_mov_b64 s[28:29], -1
	s_cbranch_vccnz .LBB0_566
	s_and_b64 vcc, exec, s[12:13]
	s_cbranch_vccnz .LBB0_565
	s_waitcnt lgkmcnt(0)
	v_pk_mul_f32 v[118:119], v[110:111], v[112:113] op_sel_hi:[1,0]
	v_pk_mul_f32 v[116:117], v[108:109], v[112:113] op_sel_hi:[1,0]
	v_pk_mul_f32 v[120:121], v[106:107], v[112:113] op_sel_hi:[1,0]
	v_pk_mul_f32 v[122:123], v[104:105], v[112:113] op_sel_hi:[1,0]
	v_cvt_pk_bf16_f32 v116, v116, v117
	v_cvt_pk_bf16_f32 v117, v118, v119
	v_cvt_pk_bf16_f32 v118, v122, v123
	v_cvt_pk_bf16_f32 v119, v120, v121
	v_ashrrev_i32_e32 v115, 31, v114
	v_lshlrev_b32_e32 v120, 16, v116
	v_and_b32_e32 v121, 0xffff0000, v116
	v_lshlrev_b32_e32 v122, 16, v117
	v_and_b32_e32 v123, 0xffff0000, v117
	v_lshlrev_b32_e32 v124, 16, v118
	v_and_b32_e32 v125, 0xffff0000, v118
	v_lshlrev_b32_e32 v126, 16, v119
	v_and_b32_e32 v127, 0xffff0000, v119
	v_lshlrev_b64 v[166:167], 7, v[114:115]
	v_pk_fma_f32 v[120:121], v[108:109], v[112:113], v[120:121] op_sel_hi:[1,0,1] neg_lo:[0,0,1] neg_hi:[0,0,1]
	v_pk_fma_f32 v[122:123], v[110:111], v[112:113], v[122:123] op_sel_hi:[1,0,1] neg_lo:[0,0,1] neg_hi:[0,0,1]
	v_pk_fma_f32 v[124:125], v[104:105], v[112:113], v[124:125] op_sel_hi:[1,0,1] neg_lo:[0,0,1] neg_hi:[0,0,1]
	v_pk_fma_f32 v[126:127], v[106:107], v[112:113], v[126:127] op_sel_hi:[1,0,1] neg_lo:[0,0,1] neg_hi:[0,0,1]
	v_lshl_add_u64 v[166:167], v[140:141], 0, v[166:167]
	global_store_dwordx4 v[166:167], v[116:119], off sc0 sc1
	s_nop 1
	v_cvt_pk_bf16_f32 v116, v120, v121
	v_cvt_pk_bf16_f32 v117, v122, v123
	v_cvt_pk_bf16_f32 v118, v124, v125
	v_cvt_pk_bf16_f32 v119, v126, v127
	global_store_dwordx4 v[166:167], v[116:119], off offset:32 sc0 sc1

; #define LAS __attribute__((address_space(3)))
; __device__ __forceinline__ float bflo(unsigned w) { return __uint_as_float(w << 16); }
; __device__ __forceinline__ float bfhi(unsigned w) { return __uint_as_float(w & 0xffff0000u); }
;     __device__ __forceinline__ void operator()(const f32x4 (&acc)[2][2][4][2], const Unit& u, int wr, int wc, int fr, int fq, const LAS float* rsl) const {
;         const int row0 = u.pm * 256 + wr * 64 + fr;
; #pragma unroll
;         for (int ai = 0; ai < 2; ++ai)
; #pragma unroll
;             for (int m = 0; m < 4; ++m) {
;                 const int row = row0 + ai * 128 + m * 16; const float rs = rsl[ai * 128 + wr * 64 + m * 16 + fr];
;                 if (u.pn < 14) {
; #pragma unroll
;                     for (int bj = 0; bj < 2; ++bj) {
;                         const f32x4 v0 = acc[ai][bj][m][0] * rs, v1 = acc[ai][bj][m][1] * rs;
;                         *(u32x4*)(P + (size_t)row * PW + u.pn * 256 + bj * 128 + wc * 32 + 8 * fq) = pack8(v0, v1);
;                     }
;                 } else if (wc == 0) {
;                     const f32x4 v0 = acc[ai][0][m][0] * rs, v1 = acc[ai][0][m][1] * rs;
;                     const u32x4 hi = pack8(v0, v1);
;                     const f32x4 d0 = (f32x4){v0[0] - bflo(hi.x), v0[1] - bfhi(hi.x), v0[2] - bflo(hi.y), v0[3] - bfhi(hi.y)};
;                     const f32x4 d1 = (f32x4){v1[0] - bflo(hi.z), v1[1] - bfhi(hi.z), v1[2] - bflo(hi.w), v1[3] - bfhi(hi.w)};
;                     bf16_t* lp = lr + (size_t)row * 64 + (fq >> 1) * 32 + (fq & 1) * 8;
;                     *(u32x4*)lp = hi; *(u32x4*)(lp + 16) = pack8(d0, d1);
;                 }
;             }
;     }
.LBB0_566:
	s_andn2_b64 vcc, exec, s[28:29]
	s_cbranch_vccnz .LBB0_568
	s_waitcnt lgkmcnt(0)
	v_pk_mul_f32 v[108:109], v[108:109], v[112:113] op_sel_hi:[1,0]
	v_pk_mul_f32 v[116:117], v[106:107], v[112:113] op_sel_hi:[1,0]
	v_pk_mul_f32 v[106:107], v[104:105], v[112:113] op_sel_hi:[1,0]
	v_cvt_pk_bf16_f32 v104, v108, v109
	v_mov_b64_e32 v[108:109], s[72:73]
	v_mad_i64_i32 v[108:109], s[28:29], v114, s80, v[108:109]
	v_lshl_add_u64 v[108:109], s[26:27], 1, v[108:109]
	s_lshl_b32 s68, s43, 1
	v_pk_mul_f32 v[110:111], v[110:111], v[112:113] op_sel_hi:[1,0]
	v_lshl_add_u64 v[108:109], v[108:109], 0, s[68:69]
	v_cvt_pk_bf16_f32 v105, v110, v111
	v_cvt_pk_bf16_f32 v106, v106, v107
	v_cvt_pk_bf16_f32 v107, v116, v117
	v_lshl_add_u64 v[108:109], v[108:109], 0, v[146:147]
	global_store_dwordx4 v[108:109], v[104:107], off sc0 sc1
	v_pk_mul_f32 v[102:103], v[102:103], v[112:113] op_sel_hi:[1,0]
	v_pk_mul_f32 v[100:101], v[100:101], v[112:113] op_sel_hi:[1,0]
	v_pk_mul_f32 v[104:105], v[98:99], v[112:113] op_sel_hi:[1,0]
	v_pk_mul_f32 v[98:99], v[96:97], v[112:113] op_sel_hi:[1,0]
	v_cvt_pk_bf16_f32 v96, v100, v101
	v_cvt_pk_bf16_f32 v97, v102, v103
	v_cvt_pk_bf16_f32 v98, v98, v99
	v_cvt_pk_bf16_f32 v99, v104, v105
	global_store_dwordx4 v[108:109], v[96:99], off offset:256 sc0 sc1
.LBB0_568:
	ds_read_b32 v96, v164 offset:128
	s_nop 0
	v_or_b32_e32 v98, 32, v158
	s_and_b64 vcc, exec, s[14:15]
	s_mov_b64 s[28:29], -1
	s_cbranch_vccnz .LBB0_572
	s_and_b64 vcc, exec, s[12:13]
	s_cbranch_vccnz .LBB0_571
	s_waitcnt lgkmcnt(0)
	v_pk_mul_f32 v[102:103], v[94:95], v[96:97] op_sel_hi:[1,0]
	v_pk_mul_f32 v[100:101], v[92:93], v[96:97] op_sel_hi:[1,0]
	v_pk_mul_f32 v[104:105], v[90:91], v[96:97] op_sel_hi:[1,0]
	v_pk_mul_f32 v[106:107], v[88:89], v[96:97] op_sel_hi:[1,0]
	v_cvt_pk_bf16_f32 v100, v100, v101
	v_cvt_pk_bf16_f32 v101, v102, v103
	v_cvt_pk_bf16_f32 v102, v106, v107
	v_cvt_pk_bf16_f32 v103, v104, v105
	v_ashrrev_i32_e32 v99, 31, v98
	v_lshlrev_b32_e32 v104, 16, v100
	v_and_b32_e32 v105, 0xffff0000, v100
	v_lshlrev_b32_e32 v106, 16, v101
	v_and_b32_e32 v107, 0xffff0000, v101
	v_lshlrev_b32_e32 v108, 16, v102
	v_and_b32_e32 v109, 0xffff0000, v102
	v_lshlrev_b32_e32 v110, 16, v103
	v_and_b32_e32 v111, 0xffff0000, v103
	v_lshlrev_b64 v[112:113], 7, v[98:99]
	v_pk_fma_f32 v[104:105], v[92:93], v[96:97], v[104:105] op_sel_hi:[1,0,1] neg_lo:[0,0,1] neg_hi:[0,0,1]
	v_pk_fma_f32 v[106:107], v[94:95], v[96:97], v[106:107] op_sel_hi:[1,0,1] neg_lo:[0,0,1] neg_hi:[0,0,1]
	v_pk_fma_f32 v[108:109], v[88:89], v[96:97], v[108:109] op_sel_hi:[1,0,1] neg_lo:[0,0,1] neg_hi:[0,0,1]
	v_pk_fma_f32 v[110:111], v[90:91], v[96:97], v[110:111] op_sel_hi:[1,0,1] neg_lo:[0,0,1] neg_hi:[0,0,1]
	v_lshl_add_u64 v[112:113], v[140:141], 0, v[112:113]
	global_store_dwordx4 v[112:113], v[100:103], off sc0 sc1
	s_nop 1
	v_cvt_pk_bf16_f32 v100, v104, v105
	v_cvt_pk_bf16_f32 v101, v106, v107
	v_cvt_pk_bf16_f32 v102, v108, v109
	v_cvt_pk_bf16_f32 v103, v110, v111
	global_store_dwordx4 v[112:113], v[100:103], off offset:32 sc0 sc1

; #define LAS __attribute__((address_space(3)))
; __device__ __forceinline__ float bflo(unsigned w) { return __uint_as_float(w << 16); }
; __device__ __forceinline__ float bfhi(unsigned w) { return __uint_as_float(w & 0xffff0000u); }
;     __device__ __forceinline__ void operator()(const f32x4 (&acc)[2][2][4][2], const Unit& u, int wr, int wc, int fr, int fq, const LAS float* rsl) const {
;         const int row0 = u.pm * 256 + wr * 64 + fr;
; #pragma unroll
;         for (int ai = 0; ai < 2; ++ai)
; #pragma unroll
;             for (int m = 0; m < 4; ++m) {
;                 const int row = row0 + ai * 128 + m * 16; const float rs = rsl[ai * 128 + wr * 64 + m * 16 + fr];
;                 if (u.pn < 14) {
; #pragma unroll
;                     for (int bj = 0; bj < 2; ++bj) {
;                         const f32x4 v0 = acc[ai][bj][m][0] * rs, v1 = acc[ai][bj][m][1] * rs;
;                         *(u32x4*)(P + (size_t)row * PW + u.pn * 256 + bj * 128 + wc * 32 + 8 * fq) = pack8(v0, v1);
;                     }
;                 } else if (wc == 0) {
;                     const f32x4 v0 = acc[ai][0][m][0] * rs, v1 = acc[ai][0][m][1] * rs;
;                     const u32x4 hi = pack8(v0, v1);
;                     const f32x4 d0 = (f32x4){v0[0] - bflo(hi.x), v0[1] - bfhi(hi.x), v0[2] - bflo(hi.y), v0[3] - bfhi(hi.y)};
;                     const f32x4 d1 = (f32x4){v1[0] - bflo(hi.z), v1[1] - bfhi(hi.z), v1[2] - bflo(hi.w), v1[3] - bfhi(hi.w)};
;                     bf16_t* lp = lr + (size_t)row * 64 + (fq >> 1) * 32 + (fq & 1) * 8;
;                     *(u32x4*)lp = hi; *(u32x4*)(lp + 16) = pack8(d0, d1);
;                 }
;             }
;     }
.LBB0_572:
	s_andn2_b64 vcc, exec, s[28:29]
	s_cbranch_vccnz .LBB0_574
	s_waitcnt lgkmcnt(0)
	v_pk_mul_f32 v[92:93], v[92:93], v[96:97] op_sel_hi:[1,0]
	v_pk_mul_f32 v[100:101], v[90:91], v[96:97] op_sel_hi:[1,0]
	v_pk_mul_f32 v[90:91], v[88:89], v[96:97] op_sel_hi:[1,0]
	v_cvt_pk_bf16_f32 v88, v92, v93
	v_mov_b64_e32 v[92:93], s[72:73]
	v_mad_i64_i32 v[92:93], s[28:29], v98, s80, v[92:93]
	v_lshl_add_u64 v[92:93], s[26:27], 1, v[92:93]
	s_lshl_b32 s68, s43, 1
	v_pk_mul_f32 v[94:95], v[94:95], v[96:97] op_sel_hi:[1,0]
	v_lshl_add_u64 v[92:93], v[92:93], 0, s[68:69]
	v_cvt_pk_bf16_f32 v89, v94, v95
	v_cvt_pk_bf16_f32 v90, v90, v91
	v_cvt_pk_bf16_f32 v91, v100, v101
	v_lshl_add_u64 v[92:93], v[92:93], 0, v[146:147]
	global_store_dwordx4 v[92:93], v[88:91], off sc0 sc1
	v_pk_mul_f32 v[86:87], v[86:87], v[96:97] op_sel_hi:[1,0]
	v_pk_mul_f32 v[84:85], v[84:85], v[96:97] op_sel_hi:[1,0]
	v_pk_mul_f32 v[88:89], v[82:83], v[96:97] op_sel_hi:[1,0]
	v_pk_mul_f32 v[82:83], v[80:81], v[96:97] op_sel_hi:[1,0]
	v_cvt_pk_bf16_f32 v80, v84, v85
	v_cvt_pk_bf16_f32 v81, v86, v87
	v_cvt_pk_bf16_f32 v82, v82, v83
	v_cvt_pk_bf16_f32 v83, v88, v89
	global_store_dwordx4 v[92:93], v[80:83], off offset:256 sc0 sc1
.LBB0_574:
	ds_read_b32 v80, v164 offset:192
	s_nop 0
	v_or_b32_e32 v82, 48, v158
	s_and_b64 vcc, exec, s[14:15]
	s_mov_b64 s[28:29], -1
	s_cbranch_vccnz .LBB0_578
	s_and_b64 vcc, exec, s[12:13]
	s_cbranch_vccnz .LBB0_577
	s_waitcnt lgkmcnt(0)
	v_pk_mul_f32 v[86:87], v[78:79], v[80:81] op_sel_hi:[1,0]
	v_pk_mul_f32 v[84:85], v[76:77], v[80:81] op_sel_hi:[1,0]
	v_pk_mul_f32 v[88:89], v[74:75], v[80:81] op_sel_hi:[1,0]
	v_pk_mul_f32 v[90:91], v[72:73], v[80:81] op_sel_hi:[1,0]
	v_cvt_pk_bf16_f32 v84, v84, v85
	v_cvt_pk_bf16_f32 v85, v86, v87
	v_cvt_pk_bf16_f32 v86, v90, v91
	v_cvt_pk_bf16_f32 v87, v88, v89
	v_ashrrev_i32_e32 v83, 31, v82
	v_lshlrev_b32_e32 v88, 16, v84
	v_and_b32_e32 v89, 0xffff0000, v84
	v_lshlrev_b32_e32 v90, 16, v85
	v_and_b32_e32 v91, 0xffff0000, v85
	v_lshlrev_b32_e32 v92, 16, v86
	v_and_b32_e32 v93, 0xffff0000, v86
	v_lshlrev_b32_e32 v94, 16, v87
	v_and_b32_e32 v95, 0xffff0000, v87
	v_lshlrev_b64 v[96:97], 7, v[82:83]
	v_pk_fma_f32 v[88:89], v[76:77], v[80:81], v[88:89] op_sel_hi:[1,0,1] neg_lo:[0,0,1] neg_hi:[0,0,1]
	v_pk_fma_f32 v[90:91], v[78:79], v[80:81], v[90:91] op_sel_hi:[1,0,1] neg_lo:[0,0,1] neg_hi:[0,0,1]
	v_pk_fma_f32 v[92:93], v[72:73], v[80:81], v[92:93] op_sel_hi:[1,0,1] neg_lo:[0,0,1] neg_hi:[0,0,1]
	v_pk_fma_f32 v[94:95], v[74:75], v[80:81], v[94:95] op_sel_hi:[1,0,1] neg_lo:[0,0,1] neg_hi:[0,0,1]
	v_lshl_add_u64 v[96:97], v[140:141], 0, v[96:97]
	global_store_dwordx4 v[96:97], v[84:87], off sc0 sc1
	s_nop 1
	v_cvt_pk_bf16_f32 v84, v88, v89
	v_cvt_pk_bf16_f32 v85, v90, v91
	v_cvt_pk_bf16_f32 v86, v92, v93
	v_cvt_pk_bf16_f32 v87, v94, v95
	global_store_dwordx4 v[96:97], v[84:87], off offset:32 sc0 sc1

; #define LAS __attribute__((address_space(3)))
; __device__ __forceinline__ float bflo(unsigned w) { return __uint_as_float(w << 16); }
; __device__ __forceinline__ float bfhi(unsigned w) { return __uint_as_float(w & 0xffff0000u); }
;     __device__ __forceinline__ void operator()(const f32x4 (&acc)[2][2][4][2], const Unit& u, int wr, int wc, int fr, int fq, const LAS float* rsl) const {
;         const int row0 = u.pm * 256 + wr * 64 + fr;
; #pragma unroll
;         for (int ai = 0; ai < 2; ++ai)
; #pragma unroll
;             for (int m = 0; m < 4; ++m) {
;                 const int row = row0 + ai * 128 + m * 16; const float rs = rsl[ai * 128 + wr * 64 + m * 16 + fr];
;                 if (u.pn < 14) {
; #pragma unroll
;                     for (int bj = 0; bj < 2; ++bj) {
;                         const f32x4 v0 = acc[ai][bj][m][0] * rs, v1 = acc[ai][bj][m][1] * rs;
;                         *(u32x4*)(P + (size_t)row * PW + u.pn * 256 + bj * 128 + wc * 32 + 8 * fq) = pack8(v0, v1);
;                     }
;                 } else if (wc == 0) {
;                     const f32x4 v0 = acc[ai][0][m][0] * rs, v1 = acc[ai][0][m][1] * rs;
;                     const u32x4 hi = pack8(v0, v1);
;                     const f32x4 d0 = (f32x4){v0[0] - bflo(hi.x), v0[1] - bfhi(hi.x), v0[2] - bflo(hi.y), v0[3] - bfhi(hi.y)};
;                     const f32x4 d1 = (f32x4){v1[0] - bflo(hi.z), v1[1] - bfhi(hi.z), v1[2] - bflo(hi.w), v1[3] - bfhi(hi.w)};
;                     bf16_t* lp = lr + (size_t)row * 64 + (fq >> 1) * 32 + (fq & 1) * 8;
;                     *(u32x4*)lp = hi; *(u32x4*)(lp + 16) = pack8(d0, d1);
;                 }
;             }
;     }
.LBB0_578:
	s_andn2_b64 vcc, exec, s[28:29]
	s_cbranch_vccnz .LBB0_580
	s_waitcnt lgkmcnt(0)
	v_pk_mul_f32 v[76:77], v[76:77], v[80:81] op_sel_hi:[1,0]
	v_pk_mul_f32 v[84:85], v[74:75], v[80:81] op_sel_hi:[1,0]
	v_pk_mul_f32 v[74:75], v[72:73], v[80:81] op_sel_hi:[1,0]
	v_cvt_pk_bf16_f32 v72, v76, v77
	v_mov_b64_e32 v[76:77], s[72:73]
	v_mad_i64_i32 v[76:77], s[28:29], v82, s80, v[76:77]
	v_lshl_add_u64 v[76:77], s[26:27], 1, v[76:77]
	s_lshl_b32 s68, s43, 1
	v_pk_mul_f32 v[78:79], v[78:79], v[80:81] op_sel_hi:[1,0]
	v_lshl_add_u64 v[76:77], v[76:77], 0, s[68:69]
	v_cvt_pk_bf16_f32 v73, v78, v79
	v_cvt_pk_bf16_f32 v74, v74, v75
	v_cvt_pk_bf16_f32 v75, v84, v85
	v_lshl_add_u64 v[76:77], v[76:77], 0, v[146:147]
	global_store_dwordx4 v[76:77], v[72:75], off sc0 sc1
	v_pk_mul_f32 v[70:71], v[70:71], v[80:81] op_sel_hi:[1,0]
	v_pk_mul_f32 v[68:69], v[68:69], v[80:81] op_sel_hi:[1,0]
	v_pk_mul_f32 v[72:73], v[66:67], v[80:81] op_sel_hi:[1,0]
	v_pk_mul_f32 v[66:67], v[64:65], v[80:81] op_sel_hi:[1,0]
	v_cvt_pk_bf16_f32 v64, v68, v69
	v_cvt_pk_bf16_f32 v65, v70, v71
	v_cvt_pk_bf16_f32 v66, v66, v67
	v_cvt_pk_bf16_f32 v67, v72, v73
	global_store_dwordx4 v[76:77], v[64:67], off offset:256 sc0 sc1
.LBB0_580:
	ds_read_b32 v64, v164 offset:512
	s_nop 0
	v_add_u32_e32 v66, 0x80, v158
	s_and_b64 vcc, exec, s[14:15]
	s_mov_b64 s[28:29], -1
	s_cbranch_vccnz .LBB0_584
	s_and_b64 vcc, exec, s[12:13]
	s_cbranch_vccnz .LBB0_583
	s_waitcnt lgkmcnt(0)
	v_pk_mul_f32 v[70:71], v[62:63], v[64:65] op_sel_hi:[1,0]
	v_pk_mul_f32 v[68:69], v[60:61], v[64:65] op_sel_hi:[1,0]
	v_pk_mul_f32 v[72:73], v[58:59], v[64:65] op_sel_hi:[1,0]
	v_pk_mul_f32 v[74:75], v[56:57], v[64:65] op_sel_hi:[1,0]
	v_cvt_pk_bf16_f32 v68, v68, v69
	v_cvt_pk_bf16_f32 v69, v70, v71
	v_cvt_pk_bf16_f32 v70, v74, v75
	v_cvt_pk_bf16_f32 v71, v72, v73
	v_ashrrev_i32_e32 v67, 31, v66
	v_lshlrev_b32_e32 v72, 16, v68
	v_and_b32_e32 v73, 0xffff0000, v68
	v_lshlrev_b32_e32 v74, 16, v69
	v_and_b32_e32 v75, 0xffff0000, v69
	v_lshlrev_b32_e32 v76, 16, v70
	v_and_b32_e32 v77, 0xffff0000, v70
	v_lshlrev_b32_e32 v78, 16, v71
	v_and_b32_e32 v79, 0xffff0000, v71
	v_lshlrev_b64 v[80:81], 7, v[66:67]
	v_pk_fma_f32 v[72:73], v[60:61], v[64:65], v[72:73] op_sel_hi:[1,0,1] neg_lo:[0,0,1] neg_hi:[0,0,1]
	v_pk_fma_f32 v[74:75], v[62:63], v[64:65], v[74:75] op_sel_hi:[1,0,1] neg_lo:[0,0,1] neg_hi:[0,0,1]
	v_pk_fma_f32 v[76:77], v[56:57], v[64:65], v[76:77] op_sel_hi:[1,0,1] neg_lo:[0,0,1] neg_hi:[0,0,1]
	v_pk_fma_f32 v[78:79], v[58:59], v[64:65], v[78:79] op_sel_hi:[1,0,1] neg_lo:[0,0,1] neg_hi:[0,0,1]
	v_lshl_add_u64 v[80:81], v[140:141], 0, v[80:81]
	global_store_dwordx4 v[80:81], v[68:71], off sc0 sc1
	s_nop 1
	v_cvt_pk_bf16_f32 v68, v72, v73
	v_cvt_pk_bf16_f32 v69, v74, v75
	v_cvt_pk_bf16_f32 v70, v76, v77
	v_cvt_pk_bf16_f32 v71, v78, v79
	global_store_dwordx4 v[80:81], v[68:71], off offset:32 sc0 sc1

; #define LAS __attribute__((address_space(3)))
; __device__ __forceinline__ float bflo(unsigned w) { return __uint_as_float(w << 16); }
; __device__ __forceinline__ float bfhi(unsigned w) { return __uint_as_float(w & 0xffff0000u); }
;     __device__ __forceinline__ void operator()(const f32x4 (&acc)[2][2][4][2], const Unit& u, int wr, int wc, int fr, int fq, const LAS float* rsl) const {
;         const int row0 = u.pm * 256 + wr * 64 + fr;
; #pragma unroll
;         for (int ai = 0; ai < 2; ++ai)
; #pragma unroll
;             for (int m = 0; m < 4; ++m) {
;                 const int row = row0 + ai * 128 + m * 16; const float rs = rsl[ai * 128 + wr * 64 + m * 16 + fr];
;                 if (u.pn < 14) {
; #pragma unroll
;                     for (int bj = 0; bj < 2; ++bj) {
;                         const f32x4 v0 = acc[ai][bj][m][0] * rs, v1 = acc[ai][bj][m][1] * rs;
;                         *(u32x4*)(P + (size_t)row * PW + u.pn * 256 + bj * 128 + wc * 32 + 8 * fq) = pack8(v0, v1);
;                     }
;                 } else if (wc == 0) {
;                     const f32x4 v0 = acc[ai][0][m][0] * rs, v1 = acc[ai][0][m][1] * rs;
;                     const u32x4 hi = pack8(v0, v1);
;                     const f32x4 d0 = (f32x4){v0[0] - bflo(hi.x), v0[1] - bfhi(hi.x), v0[2] - bflo(hi.y), v0[3] - bfhi(hi.y)};
;                     const f32x4 d1 = (f32x4){v1[0] - bflo(hi.z), v1[1] - bfhi(hi.z), v1[2] - bflo(hi.w), v1[3] - bfhi(hi.w)};
;                     bf16_t* lp = lr + (size_t)row * 64 + (fq >> 1) * 32 + (fq & 1) * 8;
;                     *(u32x4*)lp = hi; *(u32x4*)(lp + 16) = pack8(d0, d1);
;                 }
;             }
;     }
.LBB0_584:
	s_andn2_b64 vcc, exec, s[28:29]
	s_cbranch_vccnz .LBB0_586
	s_waitcnt lgkmcnt(0)
	v_pk_mul_f32 v[60:61], v[60:61], v[64:65] op_sel_hi:[1,0]
	v_pk_mul_f32 v[68:69], v[58:59], v[64:65] op_sel_hi:[1,0]
	v_pk_mul_f32 v[58:59], v[56:57], v[64:65] op_sel_hi:[1,0]
	v_cvt_pk_bf16_f32 v56, v60, v61
	v_mov_b64_e32 v[60:61], s[72:73]
	v_mad_i64_i32 v[60:61], s[28:29], v66, s80, v[60:61]
	v_lshl_add_u64 v[60:61], s[26:27], 1, v[60:61]
	s_lshl_b32 s68, s43, 1
	v_pk_mul_f32 v[62:63], v[62:63], v[64:65] op_sel_hi:[1,0]
	v_lshl_add_u64 v[60:61], v[60:61], 0, s[68:69]
	v_cvt_pk_bf16_f32 v57, v62, v63
	v_cvt_pk_bf16_f32 v58, v58, v59
	v_cvt_pk_bf16_f32 v59, v68, v69
	v_lshl_add_u64 v[60:61], v[60:61], 0, v[146:147]
	global_store_dwordx4 v[60:61], v[56:59], off sc0 sc1
	v_pk_mul_f32 v[54:55], v[54:55], v[64:65] op_sel_hi:[1,0]
	v_pk_mul_f32 v[52:53], v[52:53], v[64:65] op_sel_hi:[1,0]
	v_pk_mul_f32 v[56:57], v[50:51], v[64:65] op_sel_hi:[1,0]
	v_pk_mul_f32 v[50:51], v[48:49], v[64:65] op_sel_hi:[1,0]
	v_cvt_pk_bf16_f32 v48, v52, v53
	v_cvt_pk_bf16_f32 v49, v54, v55
	v_cvt_pk_bf16_f32 v50, v50, v51
	v_cvt_pk_bf16_f32 v51, v56, v57
	global_store_dwordx4 v[60:61], v[48:51], off offset:256 sc0 sc1
.LBB0_586:
	ds_read_b32 v48, v164 offset:576
	s_nop 0
	v_add_u32_e32 v50, 0x90, v158
	s_and_b64 vcc, exec, s[14:15]
	s_mov_b64 s[28:29], -1
	s_cbranch_vccnz .LBB0_590
	s_and_b64 vcc, exec, s[12:13]
	s_cbranch_vccnz .LBB0_589
	s_waitcnt lgkmcnt(0)
	v_pk_mul_f32 v[54:55], v[46:47], v[48:49] op_sel_hi:[1,0]
	v_pk_mul_f32 v[52:53], v[44:45], v[48:49] op_sel_hi:[1,0]
	v_pk_mul_f32 v[56:57], v[42:43], v[48:49] op_sel_hi:[1,0]
	v_pk_mul_f32 v[58:59], v[40:41], v[48:49] op_sel_hi:[1,0]
	v_cvt_pk_bf16_f32 v52, v52, v53
	v_cvt_pk_bf16_f32 v53, v54, v55
	v_cvt_pk_bf16_f32 v54, v58, v59
	v_cvt_pk_bf16_f32 v55, v56, v57
	v_ashrrev_i32_e32 v51, 31, v50
	v_lshlrev_b32_e32 v56, 16, v52
	v_and_b32_e32 v57, 0xffff0000, v52
	v_lshlrev_b32_e32 v58, 16, v53
	v_and_b32_e32 v59, 0xffff0000, v53
	v_lshlrev_b32_e32 v60, 16, v54
	v_and_b32_e32 v61, 0xffff0000, v54
	v_lshlrev_b32_e32 v62, 16, v55
	v_and_b32_e32 v63, 0xffff0000, v55
	v_lshlrev_b64 v[64:65], 7, v[50:51]
	v_pk_fma_f32 v[56:57], v[44:45], v[48:49], v[56:57] op_sel_hi:[1,0,1] neg_lo:[0,0,1] neg_hi:[0,0,1]
	v_pk_fma_f32 v[58:59], v[46:47], v[48:49], v[58:59] op_sel_hi:[1,0,1] neg_lo:[0,0,1] neg_hi:[0,0,1]
	v_pk_fma_f32 v[60:61], v[40:41], v[48:49], v[60:61] op_sel_hi:[1,0,1] neg_lo:[0,0,1] neg_hi:[0,0,1]
	v_pk_fma_f32 v[62:63], v[42:43], v[48:49], v[62:63] op_sel_hi:[1,0,1] neg_lo:[0,0,1] neg_hi:[0,0,1]
	v_lshl_add_u64 v[64:65], v[140:141], 0, v[64:65]
	global_store_dwordx4 v[64:65], v[52:55], off sc0 sc1
	s_nop 1
	v_cvt_pk_bf16_f32 v52, v56, v57
	v_cvt_pk_bf16_f32 v53, v58, v59
	v_cvt_pk_bf16_f32 v54, v60, v61
	v_cvt_pk_bf16_f32 v55, v62, v63
	global_store_dwordx4 v[64:65], v[52:55], off offset:32 sc0 sc1

; #define LAS __attribute__((address_space(3)))
; __device__ __forceinline__ float bflo(unsigned w) { return __uint_as_float(w << 16); }
; __device__ __forceinline__ float bfhi(unsigned w) { return __uint_as_float(w & 0xffff0000u); }
;     __device__ __forceinline__ void operator()(const f32x4 (&acc)[2][2][4][2], const Unit& u, int wr, int wc, int fr, int fq, const LAS float* rsl) const {
;         const int row0 = u.pm * 256 + wr * 64 + fr;
; #pragma unroll
;         for (int ai = 0; ai < 2; ++ai)
; #pragma unroll
;             for (int m = 0; m < 4; ++m) {
;                 const int row = row0 + ai * 128 + m * 16; const float rs = rsl[ai * 128 + wr * 64 + m * 16 + fr];
;                 if (u.pn < 14) {
; #pragma unroll
;                     for (int bj = 0; bj < 2; ++bj) {
;                         const f32x4 v0 = acc[ai][bj][m][0] * rs, v1 = acc[ai][bj][m][1] * rs;
;                         *(u32x4*)(P + (size_t)row * PW + u.pn * 256 + bj * 128 + wc * 32 + 8 * fq) = pack8(v0, v1);
;                     }
;                 } else if (wc == 0) {
;                     const f32x4 v0 = acc[ai][0][m][0] * rs, v1 = acc[ai][0][m][1] * rs;
;                     const u32x4 hi = pack8(v0, v1);
;                     const f32x4 d0 = (f32x4){v0[0] - bflo(hi.x), v0[1] - bfhi(hi.x), v0[2] - bflo(hi.y), v0[3] - bfhi(hi.y)};
;                     const f32x4 d1 = (f32x4){v1[0] - bflo(hi.z), v1[1] - bfhi(hi.z), v1[2] - bflo(hi.w), v1[3] - bfhi(hi.w)};
;                     bf16_t* lp = lr + (size_t)row * 64 + (fq >> 1) * 32 + (fq & 1) * 8;
;                     *(u32x4*)lp = hi; *(u32x4*)(lp + 16) = pack8(d0, d1);
;                 }
;             }
;     }
.LBB0_590:
	s_andn2_b64 vcc, exec, s[28:29]
	s_cbranch_vccnz .LBB0_592
	s_waitcnt lgkmcnt(0)
	v_pk_mul_f32 v[44:45], v[44:45], v[48:49] op_sel_hi:[1,0]
	v_pk_mul_f32 v[52:53], v[42:43], v[48:49] op_sel_hi:[1,0]
	v_pk_mul_f32 v[42:43], v[40:41], v[48:49] op_sel_hi:[1,0]
	v_cvt_pk_bf16_f32 v40, v44, v45
	v_mov_b64_e32 v[44:45], s[72:73]
	v_mad_i64_i32 v[44:45], s[28:29], v50, s80, v[44:45]
	v_lshl_add_u64 v[44:45], s[26:27], 1, v[44:45]
	s_lshl_b32 s68, s43, 1
	v_pk_mul_f32 v[46:47], v[46:47], v[48:49] op_sel_hi:[1,0]
	v_lshl_add_u64 v[44:45], v[44:45], 0, s[68:69]
	v_cvt_pk_bf16_f32 v41, v46, v47
	v_cvt_pk_bf16_f32 v42, v42, v43
	v_cvt_pk_bf16_f32 v43, v52, v53
	v_lshl_add_u64 v[44:45], v[44:45], 0, v[146:147]
	global_store_dwordx4 v[44:45], v[40:43], off sc0 sc1
	v_pk_mul_f32 v[38:39], v[38:39], v[48:49] op_sel_hi:[1,0]
	v_pk_mul_f32 v[36:37], v[36:37], v[48:49] op_sel_hi:[1,0]
	v_pk_mul_f32 v[40:41], v[34:35], v[48:49] op_sel_hi:[1,0]
	v_pk_mul_f32 v[34:35], v[32:33], v[48:49] op_sel_hi:[1,0]
	v_cvt_pk_bf16_f32 v32, v36, v37
	v_cvt_pk_bf16_f32 v33, v38, v39
	v_cvt_pk_bf16_f32 v34, v34, v35
	v_cvt_pk_bf16_f32 v35, v40, v41
	global_store_dwordx4 v[44:45], v[32:35], off offset:256 sc0 sc1
.LBB0_592:
	ds_read_b32 v32, v164 offset:640
	s_nop 0
	v_add_u32_e32 v34, 0xa0, v158
	s_and_b64 vcc, exec, s[14:15]
	s_mov_b64 s[28:29], -1
	s_cbranch_vccnz .LBB0_596
	s_and_b64 vcc, exec, s[12:13]
	s_cbranch_vccnz .LBB0_595
	s_waitcnt lgkmcnt(0)
	v_pk_mul_f32 v[38:39], v[30:31], v[32:33] op_sel_hi:[1,0]
	v_pk_mul_f32 v[36:37], v[28:29], v[32:33] op_sel_hi:[1,0]
	v_pk_mul_f32 v[40:41], v[26:27], v[32:33] op_sel_hi:[1,0]
	v_pk_mul_f32 v[42:43], v[24:25], v[32:33] op_sel_hi:[1,0]
	v_cvt_pk_bf16_f32 v36, v36, v37
	v_cvt_pk_bf16_f32 v37, v38, v39
	v_cvt_pk_bf16_f32 v38, v42, v43
	v_cvt_pk_bf16_f32 v39, v40, v41
	v_ashrrev_i32_e32 v35, 31, v34
	v_lshlrev_b32_e32 v40, 16, v36
	v_and_b32_e32 v41, 0xffff0000, v36
	v_lshlrev_b32_e32 v42, 16, v37
	v_and_b32_e32 v43, 0xffff0000, v37
	v_lshlrev_b32_e32 v44, 16, v38
	v_and_b32_e32 v45, 0xffff0000, v38
	v_lshlrev_b32_e32 v46, 16, v39
	v_and_b32_e32 v47, 0xffff0000, v39
	v_lshlrev_b64 v[48:49], 7, v[34:35]
	v_pk_fma_f32 v[40:41], v[28:29], v[32:33], v[40:41] op_sel_hi:[1,0,1] neg_lo:[0,0,1] neg_hi:[0,0,1]
	v_pk_fma_f32 v[42:43], v[30:31], v[32:33], v[42:43] op_sel_hi:[1,0,1] neg_lo:[0,0,1] neg_hi:[0,0,1]
	v_pk_fma_f32 v[44:45], v[24:25], v[32:33], v[44:45] op_sel_hi:[1,0,1] neg_lo:[0,0,1] neg_hi:[0,0,1]
	v_pk_fma_f32 v[46:47], v[26:27], v[32:33], v[46:47] op_sel_hi:[1,0,1] neg_lo:[0,0,1] neg_hi:[0,0,1]
	v_lshl_add_u64 v[48:49], v[140:141], 0, v[48:49]
	global_store_dwordx4 v[48:49], v[36:39], off sc0 sc1
	s_nop 1
	v_cvt_pk_bf16_f32 v36, v40, v41
	v_cvt_pk_bf16_f32 v37, v42, v43
	v_cvt_pk_bf16_f32 v38, v44, v45
	v_cvt_pk_bf16_f32 v39, v46, v47
	global_store_dwordx4 v[48:49], v[36:39], off offset:32 sc0 sc1

; #define LAS __attribute__((address_space(3)))
; __device__ __forceinline__ float bflo(unsigned w) { return __uint_as_float(w << 16); }
; __device__ __forceinline__ float bfhi(unsigned w) { return __uint_as_float(w & 0xffff0000u); }
;     __device__ __forceinline__ void operator()(const f32x4 (&acc)[2][2][4][2], const Unit& u, int wr, int wc, int fr, int fq, const LAS float* rsl) const {
;         const int row0 = u.pm * 256 + wr * 64 + fr;
; #pragma unroll
;         for (int ai = 0; ai < 2; ++ai)
; #pragma unroll
;             for (int m = 0; m < 4; ++m) {
;                 const int row = row0 + ai * 128 + m * 16; const float rs = rsl[ai * 128 + wr * 64 + m * 16 + fr];
;                 if (u.pn < 14) {
; #pragma unroll
;                     for (int bj = 0; bj < 2; ++bj) {
;                         const f32x4 v0 = acc[ai][bj][m][0] * rs, v1 = acc[ai][bj][m][1] * rs;
;                         *(u32x4*)(P + (size_t)row * PW + u.pn * 256 + bj * 128 + wc * 32 + 8 * fq) = pack8(v0, v1);
;                     }
;                 } else if (wc == 0) {
;                     const f32x4 v0 = acc[ai][0][m][0] * rs, v1 = acc[ai][0][m][1] * rs;
;                     const u32x4 hi = pack8(v0, v1);
;                     const f32x4 d0 = (f32x4){v0[0] - bflo(hi.x), v0[1] - bfhi(hi.x), v0[2] - bflo(hi.y), v0[3] - bfhi(hi.y)};
;                     const f32x4 d1 = (f32x4){v1[0] - bflo(hi.z), v1[1] - bfhi(hi.z), v1[2] - bflo(hi.w), v1[3] - bfhi(hi.w)};
;                     bf16_t* lp = lr + (size_t)row * 64 + (fq >> 1) * 32 + (fq & 1) * 8;
;                     *(u32x4*)lp = hi; *(u32x4*)(lp + 16) = pack8(d0, d1);
;                 }
;             }
;     }
.LBB0_596:
	s_andn2_b64 vcc, exec, s[28:29]
	s_cbranch_vccnz .LBB0_598
	s_waitcnt lgkmcnt(0)
	v_pk_mul_f32 v[28:29], v[28:29], v[32:33] op_sel_hi:[1,0]
	v_pk_mul_f32 v[36:37], v[26:27], v[32:33] op_sel_hi:[1,0]
	v_pk_mul_f32 v[26:27], v[24:25], v[32:33] op_sel_hi:[1,0]
	v_cvt_pk_bf16_f32 v24, v28, v29
	v_mov_b64_e32 v[28:29], s[72:73]
	v_mad_i64_i32 v[28:29], s[28:29], v34, s80, v[28:29]
	v_lshl_add_u64 v[28:29], s[26:27], 1, v[28:29]
	s_lshl_b32 s68, s43, 1
	v_pk_mul_f32 v[30:31], v[30:31], v[32:33] op_sel_hi:[1,0]
	v_lshl_add_u64 v[28:29], v[28:29], 0, s[68:69]
	v_cvt_pk_bf16_f32 v25, v30, v31
	v_cvt_pk_bf16_f32 v26, v26, v27
	v_cvt_pk_bf16_f32 v27, v36, v37
	v_lshl_add_u64 v[28:29], v[28:29], 0, v[146:147]
	global_store_dwordx4 v[28:29], v[24:27], off sc0 sc1
	v_pk_mul_f32 v[22:23], v[22:23], v[32:33] op_sel_hi:[1,0]
	v_pk_mul_f32 v[20:21], v[20:21], v[32:33] op_sel_hi:[1,0]
	v_pk_mul_f32 v[24:25], v[18:19], v[32:33] op_sel_hi:[1,0]
	v_pk_mul_f32 v[18:19], v[16:17], v[32:33] op_sel_hi:[1,0]
	v_cvt_pk_bf16_f32 v16, v20, v21
	v_cvt_pk_bf16_f32 v17, v22, v23
	v_cvt_pk_bf16_f32 v18, v18, v19
	v_cvt_pk_bf16_f32 v19, v24, v25
	global_store_dwordx4 v[28:29], v[16:19], off offset:256 sc0 sc1

; #define LAS __attribute__((address_space(3)))
; __device__ __forceinline__ float bflo(unsigned w) { return __uint_as_float(w << 16); }
; __device__ __forceinline__ float bfhi(unsigned w) { return __uint_as_float(w & 0xffff0000u); }
;     __device__ __forceinline__ void operator()(const f32x4 (&acc)[2][2][4][2], const Unit& u, int wr, int wc, int fr, int fq, const LAS float* rsl) const {
;         const int row0 = u.pm * 256 + wr * 64 + fr;
; #pragma unroll
;         for (int ai = 0; ai < 2; ++ai)
; #pragma unroll
;             for (int m = 0; m < 4; ++m) {
;                 const int row = row0 + ai * 128 + m * 16; const float rs = rsl[ai * 128 + wr * 64 + m * 16 + fr];
;                 if (u.pn < 14) {
; #pragma unroll
;                     for (int bj = 0; bj < 2; ++bj) {
;                         const f32x4 v0 = acc[ai][bj][m][0] * rs, v1 = acc[ai][bj][m][1] * rs;
;                         *(u32x4*)(P + (size_t)row * PW + u.pn * 256 + bj * 128 + wc * 32 + 8 * fq) = pack8(v0, v1);
;                     }
;                 } else if (wc == 0) {
;                     const f32x4 v0 = acc[ai][0][m][0] * rs, v1 = acc[ai][0][m][1] * rs;
;                     const u32x4 hi = pack8(v0, v1);
;                     const f32x4 d0 = (f32x4){v0[0] - bflo(hi.x), v0[1] - bfhi(hi.x), v0[2] - bflo(hi.y), v0[3] - bfhi(hi.y)};
;                     const f32x4 d1 = (f32x4){v1[0] - bflo(hi.z), v1[1] - bfhi(hi.z), v1[2] - bflo(hi.w), v1[3] - bfhi(hi.w)};
;                     bf16_t* lp = lr + (size_t)row * 64 + (fq >> 1) * 32 + (fq & 1) * 8;
;                     *(u32x4*)lp = hi; *(u32x4*)(lp + 16) = pack8(d0, d1);
;                 }
;             }
;     }
.LBB0_603:
	s_waitcnt lgkmcnt(0)
	v_pk_mul_f32 v[22:23], v[14:15], v[16:17] op_sel_hi:[1,0]
	v_pk_mul_f32 v[20:21], v[12:13], v[16:17] op_sel_hi:[1,0]
	v_pk_mul_f32 v[24:25], v[10:11], v[16:17] op_sel_hi:[1,0]
	v_pk_mul_f32 v[26:27], v[8:9], v[16:17] op_sel_hi:[1,0]
	v_cvt_pk_bf16_f32 v20, v20, v21
	v_cvt_pk_bf16_f32 v21, v22, v23
	v_cvt_pk_bf16_f32 v22, v26, v27
	v_cvt_pk_bf16_f32 v23, v24, v25
	v_ashrrev_i32_e32 v19, 31, v18
	v_lshlrev_b32_e32 v24, 16, v20
	v_and_b32_e32 v25, 0xffff0000, v20
	v_lshlrev_b32_e32 v26, 16, v21
	v_and_b32_e32 v27, 0xffff0000, v21
	v_lshlrev_b32_e32 v28, 16, v22
	v_and_b32_e32 v29, 0xffff0000, v22
	v_lshlrev_b32_e32 v30, 16, v23
	v_and_b32_e32 v31, 0xffff0000, v23
	v_lshlrev_b64 v[32:33], 7, v[18:19]
	v_pk_fma_f32 v[24:25], v[12:13], v[16:17], v[24:25] op_sel_hi:[1,0,1] neg_lo:[0,0,1] neg_hi:[0,0,1]
	v_pk_fma_f32 v[26:27], v[14:15], v[16:17], v[26:27] op_sel_hi:[1,0,1] neg_lo:[0,0,1] neg_hi:[0,0,1]
	v_pk_fma_f32 v[28:29], v[8:9], v[16:17], v[28:29] op_sel_hi:[1,0,1] neg_lo:[0,0,1] neg_hi:[0,0,1]
	v_pk_fma_f32 v[30:31], v[10:11], v[16:17], v[30:31] op_sel_hi:[1,0,1] neg_lo:[0,0,1] neg_hi:[0,0,1]
	v_lshl_add_u64 v[32:33], v[140:141], 0, v[32:33]
	global_store_dwordx4 v[32:33], v[20:23], off sc0 sc1
	s_nop 1
	v_cvt_pk_bf16_f32 v20, v24, v25
	v_cvt_pk_bf16_f32 v21, v26, v27
	v_cvt_pk_bf16_f32 v22, v28, v29
	v_cvt_pk_bf16_f32 v23, v30, v31
	global_store_dwordx4 v[32:33], v[20:23], off offset:32 sc0 sc1
	s_cbranch_execnz .LBB0_600
.LBB0_604:
	s_waitcnt lgkmcnt(0)
	v_pk_mul_f32 v[12:13], v[12:13], v[16:17] op_sel_hi:[1,0]
	v_pk_mul_f32 v[20:21], v[10:11], v[16:17] op_sel_hi:[1,0]
	v_pk_mul_f32 v[10:11], v[8:9], v[16:17] op_sel_hi:[1,0]
	v_cvt_pk_bf16_f32 v8, v12, v13
	v_mov_b64_e32 v[12:13], s[72:73]
	v_mad_i64_i32 v[12:13], s[12:13], v18, s80, v[12:13]
	v_lshl_add_u64 v[12:13], s[26:27], 1, v[12:13]
	s_lshl_b32 s68, s43, 1
	v_pk_mul_f32 v[14:15], v[14:15], v[16:17] op_sel_hi:[1,0]
	v_lshl_add_u64 v[12:13], v[12:13], 0, s[68:69]
	v_cvt_pk_bf16_f32 v9, v14, v15
	v_cvt_pk_bf16_f32 v10, v10, v11
	v_cvt_pk_bf16_f32 v11, v20, v21
	v_lshl_add_u64 v[12:13], v[12:13], 0, v[146:147]
	global_store_dwordx4 v[12:13], v[8:11], off sc0 sc1
	v_pk_mul_f32 v[6:7], v[6:7], v[16:17] op_sel_hi:[1,0]
	v_pk_mul_f32 v[4:5], v[4:5], v[16:17] op_sel_hi:[1,0]
	v_pk_mul_f32 v[8:9], v[2:3], v[16:17] op_sel_hi:[1,0]
	v_pk_mul_f32 v[2:3], v[0:1], v[16:17] op_sel_hi:[1,0]
	v_cvt_pk_bf16_f32 v0, v4, v5
	v_cvt_pk_bf16_f32 v1, v6, v7
	v_cvt_pk_bf16_f32 v2, v2, v3
	v_cvt_pk_bf16_f32 v3, v8, v9
	global_store_dwordx4 v[12:13], v[0:3], off offset:256 sc0 sc1
	s_and_b64 vcc, exec, s[10:11]
	s_mov_b64 s[10:11], -1
	s_cbranch_vccnz .LBB0_544
